# per-row value taken out of the LDS ring: scan waves prefetch it from global 8 groups ahead and quad-broadcast by DPP; staging wave drops one load and one LDS write per group
# speedup vs baseline: 1.0248x; 1.0000x over previous
; #define LAS3 __attribute__((address_space(3)))
; DEV void rwkv_helper(const Params& p, const Ctx& cx, int l, int unit, int lane, char* ring) {
;   const int d = unit & 1, h = (unit >> 1) & 15, b = unit >> 5;
;   const int j = lane >> 4, s = lane & 15;
;   const h16* SC = (const h16*)(p.ws + OFF_SCAN);
;   const char* pR = (const char*)(SC + 0 * ARR + h * 64);
;   const char* pK = (const char*)(SC + 1 * ARR + h * 64);
;   const char* pV = (const char*)(SC + 2 * ARR + h * 64);
;   const char* pKK = (const char*)(SC + 3 * ARR + h * 64);
;   const char* pA = (const char*)(SC + (size_t)(4 + d) * ARR + h * 64);
;   const char* pW = (const char*)(SC + (size_t)(6 + d) * ARR + h * 64);
;   const int jm = d ? 3 - j : j;
;   const unsigned vo0 = (unsigned)(jm * 2048 + s * 8);
;   f4v ka4, om4;
;   {
;     float4 t = *(const float4*)(p.rwkv_k_a + (size_t)l * 1024 + h * 64 + 4 * s);
;     ka4 = f4v{t.x, t.y, t.z, t.w};
;     om4 = 1.f - ka4;
;   }
;   struct RGH { u2v w, a, kk, k, r, v; };
;   RGH q0, q1, q2, q3, q4, q5, q6, q7;
;   const unsigned wofs = (unsigned)(j * 128 + s * 8);
;   const unsigned vwofs = (unsigned)(2560 + j * 128 + s * 8);
;   LAS3 volatile int* pflag = (LAS3 volatile int*)(ring + RW_FLAGS);
;   LAS3 volatile int* cflag = (LAS3 volatile int*)(ring + RW_FLAGS + 64);
;   int cmin = 0;
;     ...
;   RH_LOAD(q0, 0); RH_LOAD(q1, 1); RH_LOAD(q2, 2); RH_LOAD(q3, 3); RH_LOAD(q4, 4); RH_LOAD(q5, 5); RH_LOAD(q6, 6); RH_LOAD(q7, 7);
.LBB0_177:
	s_waitcnt lgkmcnt(0)
	s_barrier
	s_and_saveexec_b64 s[42:43], s[70:71]
	ds_write_b32 v118, v129 offset:49152
	s_or_b64 exec, exec, s[42:43]
	s_and_b32 s34, s31, 63
	s_and_b64 vcc, exec, s[72:73]
	s_waitcnt lgkmcnt(0)
	s_barrier
	s_cbranch_vccz .LBB0_223
	s_mov_b64 s[88:89], 0
	s_and_b64 vcc, exec, s[68:69]
	s_mov_b64 s[42:43], 0
	s_cbranch_vccz .LBB0_224
	s_setprio 1
	v_lshl_add_u32 v183, v116, 1, v116
	v_mul_u32_u24_e32 v182, 0x7e, v107
	v_sub_u32_e32 v182, v183, v182
	v_and_b32_e32 v186, 1, v107
	v_mul_u32_u24_e32 v186, 0x78, v186
	v_sub_u32_e32 v186, v116, v186
	s_lshl_b32 s0, s34, 5
	s_and_b32 s5, s0, 0x3c0
	s_and_b32 s23, s31, 1
	s_bfe_i32 s4, s31, 0x10000
	s_lshr_b32 s22, s34, 5
	s_lshl_b32 s10, s5, 1
	s_add_u32 s94, s2, s10
	s_addc_u32 s95, s3, 0
	v_readlane_b32 s0, v241, 30
	v_readlane_b32 s1, v241, 31
	s_add_u32 s97, s0, s10
	s_addc_u32 s99, s1, 0
	v_readlane_b32 s0, v241, 32
	v_readlane_b32 s1, v241, 33
	s_add_u32 s0, s0, s10
	s_addc_u32 s1, s1, 0
	v_readlane_b32 s36, v241, 42
	v_readlane_b32 s37, v241, 43
	s_add_u32 s8, s36, s10
	s_addc_u32 s84, s37, 0
	s_mul_i32 s33, s23, 0x4100000
	s_add_u32 s33, s2, s33
	s_addc_u32 s35, s3, 0
	s_add_u32 s10, s33, s10
	s_addc_u32 s33, s35, 0
	s_add_u32 s85, s10, 0x10400000
	s_addc_u32 s86, s33, 0
	s_add_u32 s87, s10, 0x18600000
	s_addc_u32 s35, s33, 0
	s_lshl_b32 s33, s22, 8
	s_bitset1_b32 s33, 15
	s_and_b32 s4, s4, 0xfc
	s_or_b32 s4, s33, s4
	s_lshl_b32 s10, s5, 2
	s_lshl_b32 s42, s4, 11
	s_add_u32 s4, s87, s42
	s_addc_u32 s5, s35, 0
	s_add_u32 s36, s85, s42
	s_addc_u32 s37, s86, 0
	s_add_u32 s44, s8, s42
	s_addc_u32 s45, s84, 0
	s_add_u32 s90, s97, s42
	s_addc_u32 s91, s99, 0
	s_add_u32 s92, s94, s42
	s_addc_u32 s93, s95, 0
	s_add_u32 vcc_lo, s0, s42
	s_addc_u32 vcc_hi, s1, 0
	s_cmp_eq_u32 s23, 0
	s_cselect_b64 s[42:43], -1, 0
	v_cndmask_b32_e64 v0, v109, v108, s[42:43]
	v_or_b32_e32 v119, v0, v110
	v_lshl_add_u64 v[0:1], v[80:81], 0, s[10:11]
	s_waitcnt vmcnt(0)
	v_mov_b32_e32 v8, v119
	global_load_dwordx4 v[0:3], v[0:1], off
	global_load_dwordx2 v[4:5], v8, s[4:5]
	global_load_dwordx2 v[36:37], v8, s[36:37]
	global_load_dwordx2 v[6:7], v8, s[44:45]
	global_load_dwordx2 v[44:45], v8, s[90:91]
	global_load_dwordx2 v[38:39], v8, s[92:93]
	s_and_b64 s[4:5], s[42:43], exec
	s_cselect_b32 s4, 4, 0xf8
	s_cselect_b32 s37, 8, 0xf4
	s_cselect_b32 s44, 12, 0xf0
	s_cselect_b32 s45, 16, 0xec
	s_cselect_b32 s36, 20, 0xe8
	s_cselect_b32 s23, 24, 0xe4
	s_cselect_b32 s10, 28, 0xe0
	s_or_b32 s4, s33, s4
	s_lshl_b32 s90, s4, 11
	s_add_u32 s4, s87, s90
	v_mov_b32_e32 v12, v119
	s_addc_u32 s5, s35, 0
	global_load_dwordx2 v[8:9], v12, s[4:5]
	s_add_u32 s4, s85, s90
	s_addc_u32 s5, s86, 0
	global_load_dwordx2 v[40:41], v12, s[4:5]
	s_add_u32 s4, s8, s90
	s_addc_u32 s5, s84, 0
	global_load_dwordx2 v[10:11], v12, s[4:5]
	s_add_u32 s4, s97, s90
	s_addc_u32 s5, s99, 0
	global_load_dwordx2 v[52:53], v12, s[4:5]
	s_add_u32 s4, s94, s90
	s_addc_u32 s5, s95, 0
	global_load_dwordx2 v[46:47], v12, s[4:5]
	s_add_u32 s4, s0, s90
	s_addc_u32 s5, s1, 0
	s_or_b32 s4, s33, s37
	s_lshl_b32 s37, s4, 11
	s_add_u32 s4, s87, s37
	v_mov_b32_e32 v16, v119
	s_addc_u32 s5, s35, 0
	global_load_dwordx2 v[12:13], v16, s[4:5]
	s_add_u32 s4, s85, s37
	s_addc_u32 s5, s86, 0
	global_load_dwordx2 v[48:49], v16, s[4:5]
	s_add_u32 s4, s8, s37
	s_addc_u32 s5, s84, 0
	global_load_dwordx2 v[14:15], v16, s[4:5]
	s_add_u32 s4, s97, s37
	s_addc_u32 s5, s99, 0
	global_load_dwordx2 v[60:61], v16, s[4:5]
	s_add_u32 s4, s94, s37
	s_addc_u32 s5, s95, 0
	global_load_dwordx2 v[54:55], v16, s[4:5]
	s_add_u32 s4, s0, s37
	s_addc_u32 s5, s1, 0
	s_or_b32 s4, s33, s44
	s_lshl_b32 s37, s4, 11
	s_add_u32 s4, s87, s37
	v_mov_b32_e32 v20, v119
	s_addc_u32 s5, s35, 0
	global_load_dwordx2 v[16:17], v20, s[4:5]
	s_add_u32 s4, s85, s37
	s_addc_u32 s5, s86, 0
	global_load_dwordx2 v[56:57], v20, s[4:5]
	s_add_u32 s4, s8, s37
	s_addc_u32 s5, s84, 0
	global_load_dwordx2 v[18:19], v20, s[4:5]
	s_add_u32 s4, s97, s37
	s_addc_u32 s5, s99, 0
	global_load_dwordx2 v[66:67], v20, s[4:5]
	s_add_u32 s4, s94, s37
	s_addc_u32 s5, s95, 0
	global_load_dwordx2 v[62:63], v20, s[4:5]
	s_add_u32 s4, s0, s37
	s_addc_u32 s5, s1, 0
	s_or_b32 s4, s33, s45
	s_lshl_b32 s37, s4, 11
	s_add_u32 s4, s87, s37
	v_mov_b32_e32 v24, v119
	s_addc_u32 s5, s35, 0
	global_load_dwordx2 v[20:21], v24, s[4:5]
	s_add_u32 s4, s85, s37
	s_addc_u32 s5, s86, 0
	global_load_dwordx2 v[64:65], v24, s[4:5]
	s_add_u32 s4, s8, s37
	s_addc_u32 s5, s84, 0
	global_load_dwordx2 v[22:23], v24, s[4:5]
	s_add_u32 s4, s97, s37
	s_addc_u32 s5, s99, 0
	global_load_dwordx2 v[76:77], v24, s[4:5]
	s_add_u32 s4, s94, s37
	s_addc_u32 s5, s95, 0
	global_load_dwordx2 v[70:71], v24, s[4:5]
	s_add_u32 s4, s0, s37
	s_addc_u32 s5, s1, 0
	s_or_b32 s4, s33, s36
	s_lshl_b32 s36, s4, 11
	s_add_u32 s4, s87, s36
	v_mov_b32_e32 v28, v119
	s_addc_u32 s5, s35, 0
	global_load_dwordx2 v[24:25], v28, s[4:5]
	s_add_u32 s4, s85, s36
	s_addc_u32 s5, s86, 0
	global_load_dwordx2 v[72:73], v28, s[4:5]
	s_add_u32 s4, s8, s36
	s_addc_u32 s5, s84, 0
	global_load_dwordx2 v[26:27], v28, s[4:5]
	s_add_u32 s4, s97, s36
	s_addc_u32 s5, s99, 0
	global_load_dwordx2 v[84:85], v28, s[4:5]
	s_add_u32 s4, s94, s36
	s_addc_u32 s5, s95, 0
	global_load_dwordx2 v[78:79], v28, s[4:5]
	s_add_u32 s4, s0, s36
	s_addc_u32 s5, s1, 0
	s_or_b32 s4, s33, s23
	s_lshl_b32 s23, s4, 11
	s_add_u32 s4, s87, s23
	v_mov_b32_e32 v32, v119
	s_addc_u32 s5, s35, 0
	global_load_dwordx2 v[28:29], v32, s[4:5]
	s_add_u32 s4, s85, s23
	s_addc_u32 s5, s86, 0
	global_load_dwordx2 v[82:83], v32, s[4:5]
	s_add_u32 s4, s8, s23
	s_addc_u32 s5, s84, 0
	global_load_dwordx2 v[30:31], v32, s[4:5]
	s_add_u32 s4, s97, s23
	s_addc_u32 s5, s99, 0
	global_load_dwordx2 v[98:99], v32, s[4:5]
	s_add_u32 s4, s94, s23
	s_addc_u32 s5, s95, 0
	global_load_dwordx2 v[88:89], v32, s[4:5]
	s_add_u32 s4, s0, s23
	s_addc_u32 s5, s1, 0
	s_or_b32 s4, s33, s10
	s_lshl_b32 s10, s4, 11
	s_add_u32 s4, s87, s10
	v_mov_b32_e32 v92, v119
	s_addc_u32 s5, s35, 0
	global_load_dwordx2 v[32:33], v92, s[4:5]
	s_add_u32 s4, s85, s10
	s_addc_u32 s5, s86, 0
	global_load_dwordx2 v[90:91], v92, s[4:5]
	s_add_u32 s4, s8, s10
	s_addc_u32 s5, s84, 0
	global_load_dwordx2 v[34:35], v92, s[4:5]
	s_add_u32 s4, s97, s10
	s_addc_u32 s5, s99, 0
	global_load_dwordx2 v[102:103], v92, s[4:5]
	s_add_u32 s4, s94, s10
	s_addc_u32 s5, s95, 0
	global_load_dwordx2 v[100:101], v92, s[4:5]
	s_add_u32 s4, s0, s10
	s_addc_u32 s5, s1, 0
	s_mov_b32 s36, 0
	s_waitcnt vmcnt(40)
	v_sub_f32_e32 v93, 1.0, v3
	v_sub_f32_e32 v92, 1.0, v2
	v_sub_f32_e32 v95, 1.0, v1
	v_sub_f32_e32 v94, 1.0, v0
	s_lshl_b32 s10, s22, 14
	s_mov_b32 s37, 0
	s_branch .LBB0_183
; DEV void rwkv_helper(const Params& p, const Ctx& cx, int l, int unit, int lane, char* ring) {
;     ...
;   RH_LOAD(q0, 0); RH_LOAD(q1, 1); RH_LOAD(q2, 2); RH_LOAD(q3, 3); RH_LOAD(q4, 4); RH_LOAD(q5, 5); RH_LOAD(q6, 6); RH_LOAD(q7, 7);
; #pragma unroll 1
;   for (int g = 0; g < RW_NG; g += 8) {
;     RH_STEP(q0, g); RH_LOAD(q0, g + 8); __builtin_amdgcn_sched_barrier(0);
;     RH_STEP(q1, g + 1); RH_LOAD(q1, g + 9); __builtin_amdgcn_sched_barrier(0);
;     RH_STEP(q2, g + 2); RH_LOAD(q2, g + 10); __builtin_amdgcn_sched_barrier(0);
;     RH_STEP(q3, g + 3); RH_LOAD(q3, g + 11); __builtin_amdgcn_sched_barrier(0);
;     RH_STEP(q4, g + 4); RH_LOAD(q4, g + 12); __builtin_amdgcn_sched_barrier(0);
;     RH_STEP(q5, g + 5); RH_LOAD(q5, g + 13); __builtin_amdgcn_sched_barrier(0);
;     RH_STEP(q6, g + 6); RH_LOAD(q6, g + 14); __builtin_amdgcn_sched_barrier(0);
;     RH_STEP(q7, g + 7); RH_LOAD(q7, g + 15); __builtin_amdgcn_sched_barrier(0);
.LBB0_182:
	s_min_u32 s4, s37, 0x1030
	s_lshl_b32 s4, s4, 2
	s_cmp_gt_u32 s37, 48
	s_cselect_b32 s5, 0xffffff3c, 60
	s_cselect_b32 s23, s10, s33
	s_cselect_b32 s37, s46, 0xfc
	s_add_i32 s44, s4, s5
	s_sub_i32 s37, s37, s44
	s_waitcnt vmcnt(38)
	v_cvt_f32_f16_sdwa v123, v90 dst_sel:DWORD dst_unused:UNUSED_PAD src0_sel:WORD_1
	v_cvt_f32_f16_sdwa v125, v91 dst_sel:DWORD dst_unused:UNUSED_PAD src0_sel:WORD_1
	v_cvt_f32_f16_e32 v122, v90
	v_cvt_f32_f16_e32 v124, v91
	s_and_b64 s[4:5], s[42:43], exec
	s_waitcnt vmcnt(36)
	v_cvt_f32_f16_sdwa v127, v102 dst_sel:DWORD dst_unused:UNUSED_PAD src0_sel:WORD_1
	v_cvt_f32_f16_sdwa v133, v103 dst_sel:DWORD dst_unused:UNUSED_PAD src0_sel:WORD_1
	v_cvt_f32_f16_e32 v126, v102
	v_cvt_f32_f16_e32 v132, v103
	s_cselect_b32 s4, s44, s37
	s_add_i32 s4, s4, s23
	s_ashr_i32 s5, s4, 31
	v_pk_fma_f32 v[102:103], v[2:3], v[124:125], v[92:93]
	v_pk_fma_f32 v[122:123], v[0:1], v[122:123], v[94:95]
	s_lshl_b64 s[4:5], s[4:5], 11
	v_pk_mul_f32 v[102:103], v[102:103], v[132:133]
	v_pk_mul_f32 v[126:127], v[122:123], v[126:127]
	s_add_u32 s44, s87, s4
	v_pk_mul_f16 v123, v91, v35
	v_pk_mul_f16 v122, v90, v34
	v_cvt_pk_f16_f32 v125, v102, v103
	v_cvt_pk_f16_f32 v124, v126, v127
	ds_write_b128 v120, v[32:35] offset:21504
	ds_write_b128 v120, v[122:125] offset:22528
	s_waitcnt vmcnt(35)
	v_add_u32_e32 v185, v121, v186
	ds_write_b64 v185, v[100:101] offset:23552
	v_mov_b32_e32 v32, s22
	s_addc_u32 s45, s35, s5
	s_waitcnt lgkmcnt(0)
	ds_write_b32 v161, v32 offset:49152
	global_load_dwordx2 v[32:33], v119, s[44:45]
	s_add_u32 s44, s85, s4
	s_addc_u32 s45, s86, s5
	global_load_dwordx2 v[90:91], v119, s[44:45]
	s_add_u32 s44, s8, s4
	s_addc_u32 s45, s84, s5
	global_load_dwordx2 v[34:35], v119, s[44:45]
	s_add_u32 s44, s97, s4
	s_addc_u32 s45, s99, s5
	global_load_dwordx2 v[102:103], v119, s[44:45]
	s_add_u32 s44, s94, s4
	s_addc_u32 s45, s95, s5
	s_add_u32 s4, s0, s4
	s_addc_u32 s5, s1, s5
	global_load_dwordx2 v[100:101], v119, s[44:45]
	s_nop 0
	s_andn2_b64 vcc, exec, s[90:91]
	s_mov_b32 s37, s22
	s_cbranch_vccz .LBB0_242

; DEV void rwkv_helper(const Params& p, const Ctx& cx, int l, int unit, int lane, char* ring) {
;     ...
;   RH_LOAD(q0, 0); RH_LOAD(q1, 1); RH_LOAD(q2, 2); RH_LOAD(q3, 3); RH_LOAD(q4, 4); RH_LOAD(q5, 5); RH_LOAD(q6, 6); RH_LOAD(q7, 7);
; #pragma unroll 1
;   for (int g = 0; g < RW_NG; g += 8) {
;     RH_STEP(q0, g); RH_LOAD(q0, g + 8); __builtin_amdgcn_sched_barrier(0);
;     RH_STEP(q1, g + 1); RH_LOAD(q1, g + 9); __builtin_amdgcn_sched_barrier(0);
;     RH_STEP(q2, g + 2); RH_LOAD(q2, g + 10); __builtin_amdgcn_sched_barrier(0);
;     RH_STEP(q3, g + 3); RH_LOAD(q3, g + 11); __builtin_amdgcn_sched_barrier(0);
;     RH_STEP(q4, g + 4); RH_LOAD(q4, g + 12); __builtin_amdgcn_sched_barrier(0);
;     RH_STEP(q5, g + 5); RH_LOAD(q5, g + 13); __builtin_amdgcn_sched_barrier(0);
;     RH_STEP(q6, g + 6); RH_LOAD(q6, g + 14); __builtin_amdgcn_sched_barrier(0);
;     RH_STEP(q7, g + 7); RH_LOAD(q7, g + 15); __builtin_amdgcn_sched_barrier(0);
.LBB0_185:
	s_waitcnt vmcnt(38)
	v_cvt_f32_f16_sdwa v121, v36 dst_sel:DWORD dst_unused:UNUSED_PAD src0_sel:WORD_1
	v_cvt_f32_f16_e32 v120, v36
	s_waitcnt vmcnt(36)
	v_cvt_f32_f16_sdwa v125, v44 dst_sel:DWORD dst_unused:UNUSED_PAD src0_sel:WORD_1
	v_cvt_f32_f16_e32 v124, v44
	s_and_b32 s4, s37, 8
	v_cvt_f32_f16_sdwa v123, v37 dst_sel:DWORD dst_unused:UNUSED_PAD src0_sel:WORD_1
	v_cvt_f32_f16_e32 v122, v37
	s_mulk_i32 s4, 0xc00
	s_add_i32 s4, s4, 16
	v_pk_fma_f32 v[120:121], v[0:1], v[120:121], v[94:95]
	s_or_b32 s23, s37, 1
	s_add_i32 s22, s37, 8
	v_pk_mul_f32 v[120:121], v[120:121], v[124:125]
	s_cmpk_gt_u32 s37, 0x1037
	v_cvt_f32_f16_sdwa v127, v45 dst_sel:DWORD dst_unused:UNUSED_PAD src0_sel:WORD_1
	v_cvt_f32_f16_e32 v126, v45
	v_pk_fma_f32 v[44:45], v[2:3], v[122:123], v[92:93]
	v_pk_mul_f16 v122, v36, v6
	v_cvt_pk_f16_f32 v124, v120, v121
	v_add_u32_e32 v36, s4, v113
	v_add_u32_e32 v121, s4, v111
	s_cselect_b64 s[90:91], -1, 0
	s_lshl_b32 s4, s22, 2
	s_cmpk_lt_u32 s37, 0x1038
	s_cselect_b32 s4, s4, 0x40fc
	s_add_i32 s5, s4, 0xffffff00
	s_min_u32 s44, s5, s4
	s_cmpk_gt_u32 s4, 0xff
	s_movk_i32 s4, 0x3fff
	s_cselect_b32 s4, s4, 0xff
	s_cselect_b32 s45, s10, s33
	s_sub_i32 s4, s4, s44
	s_add_i32 vcc_lo, s4, -3
	s_and_b64 s[4:5], s[42:43], exec
	s_cselect_b32 s4, s44, vcc_lo
	s_add_i32 s4, s4, s45
	s_ashr_i32 s5, s4, 31
	s_lshl_b64 s[4:5], s[4:5], 11
	v_pk_mul_f32 v[44:45], v[44:45], v[126:127]
	v_add_u32_e32 v120, v36, v128
	s_add_u32 s44, s87, s4
	v_pk_mul_f16 v123, v37, v7
	v_cvt_pk_f16_f32 v125, v44, v45
	ds_write_b128 v120, v[4:7]
	ds_write_b128 v120, v[122:125] offset:1024
	s_waitcnt vmcnt(35)
	v_add_u32_e32 v185, v121, v186
	ds_write_b64 v185, v[38:39] offset:2048
	v_mov_b32_e32 v4, s23
	s_addc_u32 s45, s35, s5
	s_waitcnt lgkmcnt(0)
	ds_write_b32 v161, v4 offset:49152
	global_load_dwordx2 v[4:5], v119, s[44:45]
	s_add_u32 s44, s85, s4
	s_addc_u32 s45, s86, s5
	global_load_dwordx2 v[36:37], v119, s[44:45]
	s_add_u32 s44, s8, s4
	s_addc_u32 s45, s84, s5
	global_load_dwordx2 v[6:7], v119, s[44:45]
	s_add_u32 s44, s97, s4
	s_addc_u32 s45, s99, s5
	global_load_dwordx2 v[44:45], v119, s[44:45]
	s_add_u32 s44, s94, s4
	s_addc_u32 s45, s95, s5
	s_add_u32 s4, s0, s4
	s_addc_u32 s5, s1, s5
	global_load_dwordx2 v[38:39], v119, s[44:45]
	s_nop 0
	v_cndmask_b32_e64 v122, 0, 1, s[92:93]
	v_cmp_ne_u32_e64 s[44:45], 1, v122
	s_andn2_b64 vcc, exec, s[92:93]
	s_cbranch_vccnz .LBB0_187
	s_add_i32 s4, s37, -14
	s_cmp_ge_i32 s36, s4
	s_cbranch_scc0 .LBB0_203
.LBB0_187:
	s_waitcnt vmcnt(38)
	v_cvt_f32_f16_sdwa v123, v40 dst_sel:DWORD dst_unused:UNUSED_PAD src0_sel:WORD_1
	v_cvt_f32_f16_sdwa v125, v41 dst_sel:DWORD dst_unused:UNUSED_PAD src0_sel:WORD_1
	v_cvt_f32_f16_e32 v122, v40
	v_cvt_f32_f16_e32 v124, v41
	s_waitcnt vmcnt(36)
	v_cvt_f32_f16_sdwa v127, v52 dst_sel:DWORD dst_unused:UNUSED_PAD src0_sel:WORD_1
	v_cvt_f32_f16_sdwa v133, v53 dst_sel:DWORD dst_unused:UNUSED_PAD src0_sel:WORD_1
	v_cvt_f32_f16_e32 v126, v52
	v_cvt_f32_f16_e32 v132, v53
	s_and_b32 s4, s23, 9
	s_mulk_i32 s4, 0xc00
	s_add_i32 s4, s4, 16
	v_pk_fma_f32 v[52:53], v[2:3], v[124:125], v[92:93]
	v_pk_fma_f32 v[122:123], v[0:1], v[122:123], v[94:95]
	v_pk_mul_f32 v[52:53], v[52:53], v[132:133]
	v_pk_mul_f32 v[126:127], v[122:123], v[126:127]
	v_pk_mul_f16 v122, v40, v10
	v_add3_u32 v40, s4, v113, v128
	v_pk_mul_f16 v123, v41, v11
	v_cvt_pk_f16_f32 v125, v52, v53
	v_cvt_pk_f16_f32 v124, v126, v127
	ds_write_b128 v40, v[8:11]
	ds_write_b128 v40, v[122:125] offset:1024
	v_add_u32_e32 v8, s4, v111
	s_or_b32 s4, s37, 2
	s_waitcnt vmcnt(35)
	v_add_u32_e32 v185, v8, v186
	ds_write_b64 v185, v[46:47] offset:2048
	v_mov_b32_e32 v8, s4
	s_min_u32 s4, s37, 0x1036
	s_lshl_b32 s4, s4, 2
	s_cmp_gt_u32 s37, 54
	s_cselect_b32 s5, 0xffffff24, 36
	s_cselect_b32 s23, s10, s33
	s_cselect_b32 s92, s46, 0xfc
	s_add_i32 s93, s4, s5
	s_sub_i32 s92, s92, s93
	s_and_b64 s[4:5], s[42:43], exec
	s_cselect_b32 s4, s93, s92
	s_add_i32 s4, s4, s23
	s_ashr_i32 s5, s4, 31
	s_lshl_b64 s[4:5], s[4:5], 11
	s_add_u32 s92, s87, s4
	s_addc_u32 s93, s35, s5
	s_waitcnt lgkmcnt(0)
	ds_write_b32 v161, v8 offset:49152
	global_load_dwordx2 v[8:9], v119, s[92:93]
	s_add_u32 s92, s85, s4
	s_addc_u32 s93, s86, s5
	global_load_dwordx2 v[40:41], v119, s[92:93]
	s_add_u32 s92, s8, s4
	s_addc_u32 s93, s84, s5
	global_load_dwordx2 v[10:11], v119, s[92:93]
	s_add_u32 s92, s97, s4
	s_addc_u32 s93, s99, s5
	global_load_dwordx2 v[52:53], v119, s[92:93]
	s_add_u32 s92, s94, s4
	s_addc_u32 s93, s95, s5
	s_add_u32 s4, s0, s4
	s_addc_u32 s5, s1, s5
	global_load_dwordx2 v[46:47], v119, s[92:93]
	s_nop 0
	s_and_b64 vcc, exec, s[44:45]
	s_cbranch_vccnz .LBB0_189
	s_add_i32 s4, s37, -13
	s_cmp_ge_i32 s36, s4
	s_cbranch_scc0 .LBB0_206
; DEV void rwkv_helper(const Params& p, const Ctx& cx, int l, int unit, int lane, char* ring) {
;     ...
;   RH_LOAD(q0, 0); RH_LOAD(q1, 1); RH_LOAD(q2, 2); RH_LOAD(q3, 3); RH_LOAD(q4, 4); RH_LOAD(q5, 5); RH_LOAD(q6, 6); RH_LOAD(q7, 7);
; #pragma unroll 1
;   for (int g = 0; g < RW_NG; g += 8) {
;     RH_STEP(q0, g); RH_LOAD(q0, g + 8); __builtin_amdgcn_sched_barrier(0);
;     RH_STEP(q1, g + 1); RH_LOAD(q1, g + 9); __builtin_amdgcn_sched_barrier(0);
;     RH_STEP(q2, g + 2); RH_LOAD(q2, g + 10); __builtin_amdgcn_sched_barrier(0);
;     RH_STEP(q3, g + 3); RH_LOAD(q3, g + 11); __builtin_amdgcn_sched_barrier(0);
;     RH_STEP(q4, g + 4); RH_LOAD(q4, g + 12); __builtin_amdgcn_sched_barrier(0);
;     RH_STEP(q5, g + 5); RH_LOAD(q5, g + 13); __builtin_amdgcn_sched_barrier(0);
;     RH_STEP(q6, g + 6); RH_LOAD(q6, g + 14); __builtin_amdgcn_sched_barrier(0);
;     RH_STEP(q7, g + 7); RH_LOAD(q7, g + 15); __builtin_amdgcn_sched_barrier(0);
.LBB0_189:
	s_waitcnt vmcnt(38)
	v_cvt_f32_f16_sdwa v123, v48 dst_sel:DWORD dst_unused:UNUSED_PAD src0_sel:WORD_1
	v_cvt_f32_f16_sdwa v125, v49 dst_sel:DWORD dst_unused:UNUSED_PAD src0_sel:WORD_1
	v_cvt_f32_f16_e32 v122, v48
	v_cvt_f32_f16_e32 v124, v49
	s_waitcnt vmcnt(36)
	v_cvt_f32_f16_sdwa v127, v60 dst_sel:DWORD dst_unused:UNUSED_PAD src0_sel:WORD_1
	v_cvt_f32_f16_sdwa v133, v61 dst_sel:DWORD dst_unused:UNUSED_PAD src0_sel:WORD_1
	v_cvt_f32_f16_e32 v126, v60
	v_cvt_f32_f16_e32 v132, v61
	v_pk_fma_f32 v[60:61], v[2:3], v[124:125], v[92:93]
	v_pk_fma_f32 v[122:123], v[0:1], v[122:123], v[94:95]
	s_or_b32 s4, s37, 3
	v_pk_mul_f32 v[60:61], v[60:61], v[132:133]
	v_pk_mul_f32 v[126:127], v[122:123], v[126:127]
	v_pk_mul_f16 v123, v49, v15
	v_pk_mul_f16 v122, v48, v14
	v_cvt_pk_f16_f32 v125, v60, v61
	v_cvt_pk_f16_f32 v124, v126, v127
	ds_write_b128 v120, v[12:15] offset:6144
	ds_write_b128 v120, v[122:125] offset:7168
	s_waitcnt vmcnt(35)
	v_add_u32_e32 v185, v121, v186
	ds_write_b64 v185, v[54:55] offset:8192
	v_mov_b32_e32 v12, s4
	s_min_u32 s4, s37, 0x1035
	s_lshl_b32 s4, s4, 2
	s_cmp_gt_u32 s37, 53
	s_cselect_b32 s5, 0xffffff28, 40
	s_cselect_b32 s23, s10, s33
	s_cselect_b32 s92, s46, 0xfc
	s_add_i32 s93, s4, s5
	s_sub_i32 s92, s92, s93
	s_and_b64 s[4:5], s[42:43], exec
	s_cselect_b32 s4, s93, s92
	s_add_i32 s4, s4, s23
	s_ashr_i32 s5, s4, 31
	s_lshl_b64 s[4:5], s[4:5], 11
	s_add_u32 s92, s87, s4
	s_addc_u32 s93, s35, s5
	s_waitcnt lgkmcnt(0)
	ds_write_b32 v161, v12 offset:49152
	global_load_dwordx2 v[12:13], v119, s[92:93]
	s_add_u32 s92, s85, s4
	s_addc_u32 s93, s86, s5
	global_load_dwordx2 v[48:49], v119, s[92:93]
	s_add_u32 s92, s8, s4
	s_addc_u32 s93, s84, s5
	global_load_dwordx2 v[14:15], v119, s[92:93]
	s_add_u32 s92, s97, s4
	s_addc_u32 s93, s99, s5
	global_load_dwordx2 v[60:61], v119, s[92:93]
	s_add_u32 s92, s94, s4
	s_addc_u32 s93, s95, s5
	s_add_u32 s4, s0, s4
	s_addc_u32 s5, s1, s5
	global_load_dwordx2 v[54:55], v119, s[92:93]
	s_nop 0
	s_and_b64 vcc, exec, s[44:45]
	s_cbranch_vccnz .LBB0_191
	s_add_i32 s4, s37, -12
	s_cmp_ge_i32 s36, s4
	s_cbranch_scc0 .LBB0_209
.LBB0_191:
	s_waitcnt vmcnt(38)
	v_cvt_f32_f16_sdwa v123, v56 dst_sel:DWORD dst_unused:UNUSED_PAD src0_sel:WORD_1
	v_cvt_f32_f16_sdwa v125, v57 dst_sel:DWORD dst_unused:UNUSED_PAD src0_sel:WORD_1
	v_cvt_f32_f16_e32 v122, v56
	v_cvt_f32_f16_e32 v124, v57
	s_waitcnt vmcnt(36)
	v_cvt_f32_f16_sdwa v127, v66 dst_sel:DWORD dst_unused:UNUSED_PAD src0_sel:WORD_1
	v_cvt_f32_f16_sdwa v133, v67 dst_sel:DWORD dst_unused:UNUSED_PAD src0_sel:WORD_1
	v_cvt_f32_f16_e32 v126, v66
	v_cvt_f32_f16_e32 v132, v67
	v_pk_fma_f32 v[66:67], v[2:3], v[124:125], v[92:93]
	v_pk_fma_f32 v[122:123], v[0:1], v[122:123], v[94:95]
	s_or_b32 s4, s37, 4
	v_pk_mul_f32 v[66:67], v[66:67], v[132:133]
	v_pk_mul_f32 v[126:127], v[122:123], v[126:127]
	v_pk_mul_f16 v123, v57, v19
	v_pk_mul_f16 v122, v56, v18
	v_cvt_pk_f16_f32 v125, v66, v67
	v_cvt_pk_f16_f32 v124, v126, v127
	ds_write_b128 v120, v[16:19] offset:9216
	ds_write_b128 v120, v[122:125] offset:10240
	s_waitcnt vmcnt(35)
	v_add_u32_e32 v185, v121, v186
	ds_write_b64 v185, v[62:63] offset:11264
	v_mov_b32_e32 v16, s4
	s_min_u32 s4, s37, 0x1034
	s_lshl_b32 s4, s4, 2
	s_cmp_gt_u32 s37, 52
	s_cselect_b32 s5, 0xffffff2c, 44
	s_cselect_b32 s23, s10, s33
	s_cselect_b32 s92, s46, 0xfc
	s_add_i32 s93, s4, s5
	s_sub_i32 s92, s92, s93
	s_and_b64 s[4:5], s[42:43], exec
	s_cselect_b32 s4, s93, s92
	s_add_i32 s4, s4, s23
	s_ashr_i32 s5, s4, 31
	s_lshl_b64 s[4:5], s[4:5], 11
	s_add_u32 s92, s87, s4
	s_addc_u32 s93, s35, s5
	s_waitcnt lgkmcnt(0)
	ds_write_b32 v161, v16 offset:49152
	global_load_dwordx2 v[16:17], v119, s[92:93]
	s_add_u32 s92, s85, s4
	s_addc_u32 s93, s86, s5
	global_load_dwordx2 v[56:57], v119, s[92:93]
	s_add_u32 s92, s8, s4
	s_addc_u32 s93, s84, s5
	global_load_dwordx2 v[18:19], v119, s[92:93]
	s_add_u32 s92, s97, s4
	s_addc_u32 s93, s99, s5
	global_load_dwordx2 v[66:67], v119, s[92:93]
	s_add_u32 s92, s94, s4
	s_addc_u32 s93, s95, s5
	s_add_u32 s4, s0, s4
	s_addc_u32 s5, s1, s5
	global_load_dwordx2 v[62:63], v119, s[92:93]
	s_nop 0
	s_and_b64 vcc, exec, s[44:45]
	s_cbranch_vccnz .LBB0_193
	s_add_i32 s4, s37, -11
	s_cmp_ge_i32 s36, s4
	s_cbranch_scc0 .LBB0_212
.LBB0_193:
	s_waitcnt vmcnt(38)
	v_cvt_f32_f16_sdwa v123, v64 dst_sel:DWORD dst_unused:UNUSED_PAD src0_sel:WORD_1
	v_cvt_f32_f16_sdwa v125, v65 dst_sel:DWORD dst_unused:UNUSED_PAD src0_sel:WORD_1
	v_cvt_f32_f16_e32 v122, v64
	v_cvt_f32_f16_e32 v124, v65
	s_waitcnt vmcnt(36)
	v_cvt_f32_f16_sdwa v127, v76 dst_sel:DWORD dst_unused:UNUSED_PAD src0_sel:WORD_1
	v_cvt_f32_f16_sdwa v133, v77 dst_sel:DWORD dst_unused:UNUSED_PAD src0_sel:WORD_1
	v_cvt_f32_f16_e32 v126, v76
	v_cvt_f32_f16_e32 v132, v77
	v_pk_fma_f32 v[76:77], v[2:3], v[124:125], v[92:93]
	v_pk_fma_f32 v[122:123], v[0:1], v[122:123], v[94:95]
	s_or_b32 s4, s37, 5
	v_pk_mul_f32 v[76:77], v[76:77], v[132:133]
	v_pk_mul_f32 v[126:127], v[122:123], v[126:127]
	v_pk_mul_f16 v123, v65, v23
	v_pk_mul_f16 v122, v64, v22
	v_cvt_pk_f16_f32 v125, v76, v77
	v_cvt_pk_f16_f32 v124, v126, v127
	ds_write_b128 v120, v[20:23] offset:12288
	ds_write_b128 v120, v[122:125] offset:13312
	s_waitcnt vmcnt(35)
	v_add_u32_e32 v185, v121, v186
	ds_write_b64 v185, v[70:71] offset:14336
	v_mov_b32_e32 v20, s4
	s_min_u32 s4, s37, 0x1033
	s_lshl_b32 s4, s4, 2
	s_cmp_gt_u32 s37, 51
	s_cselect_b32 s5, 0xffffff30, 48
	s_cselect_b32 s23, s10, s33
	s_cselect_b32 s92, s46, 0xfc
	s_add_i32 s93, s4, s5
	s_sub_i32 s92, s92, s93
	s_and_b64 s[4:5], s[42:43], exec
	s_cselect_b32 s4, s93, s92
	s_add_i32 s4, s4, s23
	s_ashr_i32 s5, s4, 31
	s_lshl_b64 s[4:5], s[4:5], 11
	s_add_u32 s92, s87, s4
	s_addc_u32 s93, s35, s5
	s_waitcnt lgkmcnt(0)
	ds_write_b32 v161, v20 offset:49152
	global_load_dwordx2 v[20:21], v119, s[92:93]
	s_add_u32 s92, s85, s4
	s_addc_u32 s93, s86, s5
	global_load_dwordx2 v[64:65], v119, s[92:93]
	s_add_u32 s92, s8, s4
	s_addc_u32 s93, s84, s5
	global_load_dwordx2 v[22:23], v119, s[92:93]
	s_add_u32 s92, s97, s4
	s_addc_u32 s93, s99, s5
	global_load_dwordx2 v[76:77], v119, s[92:93]
	s_add_u32 s92, s94, s4
	s_addc_u32 s93, s95, s5
	s_add_u32 s4, s0, s4
	s_addc_u32 s5, s1, s5
	global_load_dwordx2 v[70:71], v119, s[92:93]
	s_nop 0
	s_and_b64 vcc, exec, s[44:45]
	s_cbranch_vccnz .LBB0_195
	s_add_i32 s4, s37, -10
	s_cmp_ge_i32 s36, s4
	s_cbranch_scc0 .LBB0_215
; DEV void rwkv_helper(const Params& p, const Ctx& cx, int l, int unit, int lane, char* ring) {
;     ...
;   RH_LOAD(q0, 0); RH_LOAD(q1, 1); RH_LOAD(q2, 2); RH_LOAD(q3, 3); RH_LOAD(q4, 4); RH_LOAD(q5, 5); RH_LOAD(q6, 6); RH_LOAD(q7, 7);
; #pragma unroll 1
;   for (int g = 0; g < RW_NG; g += 8) {
;     RH_STEP(q0, g); RH_LOAD(q0, g + 8); __builtin_amdgcn_sched_barrier(0);
;     RH_STEP(q1, g + 1); RH_LOAD(q1, g + 9); __builtin_amdgcn_sched_barrier(0);
;     RH_STEP(q2, g + 2); RH_LOAD(q2, g + 10); __builtin_amdgcn_sched_barrier(0);
;     RH_STEP(q3, g + 3); RH_LOAD(q3, g + 11); __builtin_amdgcn_sched_barrier(0);
;     RH_STEP(q4, g + 4); RH_LOAD(q4, g + 12); __builtin_amdgcn_sched_barrier(0);
;     RH_STEP(q5, g + 5); RH_LOAD(q5, g + 13); __builtin_amdgcn_sched_barrier(0);
;     RH_STEP(q6, g + 6); RH_LOAD(q6, g + 14); __builtin_amdgcn_sched_barrier(0);
;     RH_STEP(q7, g + 7); RH_LOAD(q7, g + 15); __builtin_amdgcn_sched_barrier(0);
.LBB0_195:
	s_waitcnt vmcnt(38)
	v_cvt_f32_f16_sdwa v123, v72 dst_sel:DWORD dst_unused:UNUSED_PAD src0_sel:WORD_1
	v_cvt_f32_f16_sdwa v125, v73 dst_sel:DWORD dst_unused:UNUSED_PAD src0_sel:WORD_1
	v_cvt_f32_f16_e32 v122, v72
	v_cvt_f32_f16_e32 v124, v73
	s_waitcnt vmcnt(36)
	v_cvt_f32_f16_sdwa v127, v84 dst_sel:DWORD dst_unused:UNUSED_PAD src0_sel:WORD_1
	v_cvt_f32_f16_sdwa v133, v85 dst_sel:DWORD dst_unused:UNUSED_PAD src0_sel:WORD_1
	v_cvt_f32_f16_e32 v126, v84
	v_cvt_f32_f16_e32 v132, v85
	v_pk_fma_f32 v[84:85], v[2:3], v[124:125], v[92:93]
	v_pk_fma_f32 v[122:123], v[0:1], v[122:123], v[94:95]
	s_or_b32 s4, s37, 6
	v_pk_mul_f32 v[84:85], v[84:85], v[132:133]
	v_pk_mul_f32 v[126:127], v[122:123], v[126:127]
	v_pk_mul_f16 v123, v73, v27
	v_pk_mul_f16 v122, v72, v26
	v_cvt_pk_f16_f32 v125, v84, v85
	v_cvt_pk_f16_f32 v124, v126, v127
	ds_write_b128 v120, v[24:27] offset:15360
	ds_write_b128 v120, v[122:125] offset:16384
	s_waitcnt vmcnt(35)
	v_add_u32_e32 v185, v121, v186
	ds_write_b64 v185, v[78:79] offset:17408
	v_mov_b32_e32 v24, s4
	s_min_u32 s4, s37, 0x1032
	s_lshl_b32 s4, s4, 2
	s_cmp_gt_u32 s37, 50
	s_cselect_b32 s5, 0xffffff34, 52
	s_cselect_b32 s23, s10, s33
	s_cselect_b32 s92, s46, 0xfc
	s_add_i32 s93, s4, s5
	s_sub_i32 s92, s92, s93
	s_and_b64 s[4:5], s[42:43], exec
	s_cselect_b32 s4, s93, s92
	s_add_i32 s4, s4, s23
	s_ashr_i32 s5, s4, 31
	s_lshl_b64 s[4:5], s[4:5], 11
	s_add_u32 s92, s87, s4
	s_addc_u32 s93, s35, s5
	s_waitcnt lgkmcnt(0)
	ds_write_b32 v161, v24 offset:49152
	global_load_dwordx2 v[24:25], v119, s[92:93]
	s_add_u32 s92, s85, s4
	s_addc_u32 s93, s86, s5
	global_load_dwordx2 v[72:73], v119, s[92:93]
	s_add_u32 s92, s8, s4
	s_addc_u32 s93, s84, s5
	global_load_dwordx2 v[26:27], v119, s[92:93]
	s_add_u32 s92, s97, s4
	s_addc_u32 s93, s99, s5
	global_load_dwordx2 v[84:85], v119, s[92:93]
	s_add_u32 s92, s94, s4
	s_addc_u32 s93, s95, s5
	s_add_u32 s4, s0, s4
	s_addc_u32 s5, s1, s5
	global_load_dwordx2 v[78:79], v119, s[92:93]
	s_nop 0
	s_and_b64 vcc, exec, s[44:45]
	s_cbranch_vccnz .LBB0_197
	s_add_i32 s4, s37, -9
	s_cmp_ge_i32 s36, s4
	s_cbranch_scc0 .LBB0_218
.LBB0_197:
	s_waitcnt vmcnt(38)
	v_cvt_f32_f16_sdwa v123, v82 dst_sel:DWORD dst_unused:UNUSED_PAD src0_sel:WORD_1
	v_cvt_f32_f16_sdwa v125, v83 dst_sel:DWORD dst_unused:UNUSED_PAD src0_sel:WORD_1
	v_cvt_f32_f16_e32 v122, v82
	v_cvt_f32_f16_e32 v124, v83
	s_waitcnt vmcnt(36)
	v_cvt_f32_f16_sdwa v127, v98 dst_sel:DWORD dst_unused:UNUSED_PAD src0_sel:WORD_1
	v_cvt_f32_f16_sdwa v133, v99 dst_sel:DWORD dst_unused:UNUSED_PAD src0_sel:WORD_1
	v_cvt_f32_f16_e32 v126, v98
	v_cvt_f32_f16_e32 v132, v99
	v_pk_fma_f32 v[98:99], v[2:3], v[124:125], v[92:93]
	v_pk_fma_f32 v[122:123], v[0:1], v[122:123], v[94:95]
	s_or_b32 s4, s37, 7
	v_pk_mul_f32 v[98:99], v[98:99], v[132:133]
	v_pk_mul_f32 v[126:127], v[122:123], v[126:127]
	v_pk_mul_f16 v123, v83, v31
	v_pk_mul_f16 v122, v82, v30
	v_cvt_pk_f16_f32 v125, v98, v99
	v_cvt_pk_f16_f32 v124, v126, v127
	ds_write_b128 v120, v[28:31] offset:18432
	ds_write_b128 v120, v[122:125] offset:19456
	s_waitcnt vmcnt(35)
	v_add_u32_e32 v185, v121, v186
	ds_write_b64 v185, v[88:89] offset:20480
	v_mov_b32_e32 v28, s4
	s_min_u32 s4, s37, 0x1031
	s_lshl_b32 s4, s4, 2
	s_cmp_gt_u32 s37, 49
	s_cselect_b32 s5, 0xffffff38, 56
	s_cselect_b32 s23, s10, s33
	s_cselect_b32 s92, s46, 0xfc
	s_add_i32 s93, s4, s5
	s_sub_i32 s92, s92, s93
	s_and_b64 s[4:5], s[42:43], exec
	s_cselect_b32 s4, s93, s92
	s_add_i32 s4, s4, s23
	s_ashr_i32 s5, s4, 31
	s_lshl_b64 s[4:5], s[4:5], 11
	s_add_u32 s92, s87, s4
	s_addc_u32 s93, s35, s5
	s_waitcnt lgkmcnt(0)
	ds_write_b32 v161, v28 offset:49152
	global_load_dwordx2 v[28:29], v119, s[92:93]
	s_add_u32 s92, s85, s4
	s_addc_u32 s93, s86, s5
	global_load_dwordx2 v[82:83], v119, s[92:93]
	s_add_u32 s92, s8, s4
	s_addc_u32 s93, s84, s5
	global_load_dwordx2 v[30:31], v119, s[92:93]
	s_add_u32 s92, s97, s4
	s_addc_u32 s93, s99, s5
	global_load_dwordx2 v[98:99], v119, s[92:93]
	s_add_u32 s92, s94, s4
	s_addc_u32 s93, s95, s5
	s_add_u32 s4, s0, s4
	s_addc_u32 s5, s1, s5
	global_load_dwordx2 v[88:89], v119, s[92:93]
	s_nop 0
	s_and_b64 vcc, exec, s[44:45]
	s_cbranch_vccnz .LBB0_182
	s_add_i32 s4, s37, -8
	s_cmp_ge_i32 s36, s4
	s_cbranch_scc0 .LBB0_221
	s_branch .LBB0_182

; #define LAS3 __attribute__((address_space(3)))
; #define RC_WAIT(gq) { if (pseen <= (gq)) { do { pseen = __builtin_amdgcn_readfirstlane(*pflag); if (pseen <= (gq)) __builtin_amdgcn_s_sleep(1); } while (pseen <= (gq)); } asm volatile("" ::: "memory"); }
; DEV void rwkv_consumer(const Params& p, const Ctx& cx, int l, int task, int lane, const char* ring, int widx) {
;   const int unit = task >> 4, d = unit & 1, h = (unit >> 1) & 15, b = unit >> 5;
;   const int j = lane >> 4, s = lane & 15;
;   const int myrow = (task & 15) * 4 + j;
;   char* pO = (char*)((h16*)(p.ws + OFF_REG2) + (size_t)d * ARR + h * 64);
;   const int sm = d ? 3 - (s & 3) : (s & 3);
;   const unsigned vov0 = (unsigned)(sm * 2048 + myrow * 2);
;   const unsigned rofs = (unsigned)(s * 8);
;   const unsigned vrofs = (unsigned)(2560 + myrow * 2);
;   LAS3 volatile int* pflag = (LAS3 volatile int*)(ring + RW_FLAGS);
;   LAS3 volatile int* cflag = (LAS3 volatile int*)(ring + RW_FLAGS + 64) + widx;
;   float S0 = 0.f, S1 = 0.f, S2 = 0.f, S3 = 0.f;
;   int pseen = 0;
;   struct GD { u2v w[4], kk[4], kka[4], kd[4], r[4]; unsigned v[4]; };
;   GD A, B;
;     ...
;   RC_WAIT(0); RC_LOAD(A, 0);
; #pragma unroll 1
;   for (int g = 0; g < RW_NG; g += 2) {
.LBB0_229:
	s_ashr_i32 s4, s31, 4
	s_lshl_b32 s1, s34, 4
	s_and_b32 s4, s4, -4
	s_or_b32 s1, s1, s4
	s_or_b32 s4, s1, s50
	s_lshl_b32 s1, s4, 2
	v_and_or_b32 v0, s1, 60, v107
	s_waitcnt vmcnt(0)
	v_lshlrev_b32_e32 v82, 1, v0
	v_lshlrev_b32_e32 v184, 3, v0
	v_add_u32_e32 v0, 16, v116
	v_add_u32_e32 v36, 16, v117
	v_add_u32_e32 v20, 0x800, v0
	v_add_u32_e32 v41, 16, v82
	ds_read_b128 v[0:3], v36 offset:2048
	ds_read_b128 v[4:7], v36
	ds_read_b128 v[8:11], v36 offset:256
	ds_read_b128 v[12:15], v36 offset:1024
	ds_read_b128 v[16:19], v36 offset:1280
	ds_read_b128 v[20:23], v36 offset:2304
	ds_read_b128 v[24:27], v36 offset:512
	s_waitcnt vmcnt(9)
	ds_read_b128 v[28:31], v36 offset:768
	s_waitcnt vmcnt(3)
	ds_read_b128 v[32:35], v36 offset:1536
	ds_read_b128 v[36:39], v36 offset:1792
	s_bfe_u32 s5, s4, 0x10004
	s_mul_i32 s8, s5, 0x4100000
	s_add_u32 s8, s20, s8
	s_addc_u32 s10, s21, 0
	s_and_b32 s1, s1, 0x780
	s_mov_b32 s34, s1
	s_add_u32 s1, s8, s1
	s_addc_u32 s8, s10, 0
	s_cmp_eq_u32 s5, 0
	s_cselect_b64 s[42:43], -1, 0
	s_ashr_i32 s4, s4, 9
	v_cndmask_b32_e64 v40, v115, v114, s[42:43]
	s_lshl_b32 s22, s4, 8
	s_mov_b32 s33, 0
	v_or_b32_e32 v83, v40, v82
	s_lshl_b32 s10, s4, 14
	s_add_i32 s22, s22, 0x8000
	v_mov_b32_e32 v84, 0
	v_mov_b32_e32 v85, 0
	v_mov_b32_e32 v86, 0
	v_mov_b32_e32 v87, 0
	s_waitcnt vmcnt(0)
	v_readlane_b32 s90, v241, 32
	v_readlane_b32 s91, v241, 33
	s_nop 0
	s_add_u32 s90, s90, s34
	s_addc_u32 s91, s91, 0
	s_and_b64 s[4:5], s[42:43], exec
	s_cselect_b32 s4, 0, 0xfc
	s_add_i32 s4, s22, s4
	s_lshl_b32 s4, s4, 11
	s_add_u32 s36, s1, s4
	s_addc_u32 s37, s8, 0
	s_add_u32 s22, s90, s4
	s_addc_u32 s23, s91, 0
	s_and_b64 s[4:5], s[42:43], exec
	s_cselect_b32 s4, 0, 0x3ffc
	s_add_i32 s4, s10, s4
	s_lshl_b32 s4, s4, 11
	s_add_u32 s88, s1, s4
	s_addc_u32 s89, s8, 0
	s_add_u32 s90, s90, s4
	s_addc_u32 s91, s91, 0
	s_and_b64 s[4:5], s[42:43], exec
	s_mov_b32 s44, 0xffffe000
	s_and_b64 s[4:5], s[42:43], exec
	s_cselect_b32 s44, 0x2000, s44
	s_cselect_b32 s45, 0, -1
	v_mov_b32_e32 v172, s9
	v_add_u32_e32 v194, 16, v117
	v_add_u32_e32 v195, 16, v184
	v_add_u32_e32 v196, 16, v82
	v_mov_b32_e32 v193, 0

; #define RC_WAIT(gq) { if (pseen <= (gq)) { do { pseen = __builtin_amdgcn_readfirstlane(*pflag); if (pseen <= (gq)) __builtin_amdgcn_s_sleep(1); } while (pseen <= (gq)); } asm volatile("" ::: "memory"); }
; DEV void rwkv_consumer(const Params& p, const Ctx& cx, int l, int task, int lane, const char* ring, int widx) {
;     ...
;   RC_WAIT(0); RC_LOAD(A, 0);
; #pragma unroll 1
;   for (int g = 0; g < RW_NG; g += 2) {
;     RC_WAIT(g + 1); RC_LOAD(B, g + 1);
;     RC_COMP(A, g);
.Lc_init_ld:
	ds_read_b128 v[56:59], v194 offset:5120
	ds_read_b128 v[72:75], v194 offset:3072
	ds_read_b128 v[64:67], v194 offset:3328
	ds_read_b128 v[76:79], v194 offset:4096
	ds_read_b128 v[68:71], v194 offset:4352
	ds_read_b128 v[40:43], v194 offset:5376
	ds_read_b128 v[52:55], v194 offset:3584
	ds_read_b128 v[44:47], v194 offset:3840
	ds_read_b128 v[60:63], v194 offset:4608
	ds_read_b128 v[48:51], v194 offset:4864
	global_load_ushort v197, v83, s[22:23]
	s_add_u32 s22, s22, s44
	s_addc_u32 s23, s23, s45
	global_load_ushort v198, v83, s[22:23]
	s_add_u32 s22, s22, s44
	s_addc_u32 s23, s23, s45
	global_load_ushort v199, v83, s[22:23]
	s_add_u32 s22, s22, s44
	s_addc_u32 s23, s23, s45
	global_load_ushort v200, v83, s[22:23]
	s_add_u32 s22, s22, s44
	s_addc_u32 s23, s23, s45
	global_load_ushort v201, v83, s[22:23]
	s_add_u32 s22, s22, s44
	s_addc_u32 s23, s23, s45
	global_load_ushort v202, v83, s[22:23]
	s_add_u32 s22, s22, s44
	s_addc_u32 s23, s23, s45
	global_load_ushort v203, v83, s[22:23]
	s_add_u32 s22, s22, s44
	s_addc_u32 s23, s23, s45
	global_load_ushort v204, v83, s[22:23]
	s_add_u32 s22, s22, s44
	s_addc_u32 s23, s23, s45
	s_waitcnt vmcnt(0)
	v_mov_b32_dpp v88, v197 quad_perm:[0,0,0,0] row_mask:0xf bank_mask:0xf
	v_mov_b32_dpp v89, v197 quad_perm:[1,1,1,1] row_mask:0xf bank_mask:0xf
	v_mov_b32_dpp v90, v197 quad_perm:[2,2,2,2] row_mask:0xf bank_mask:0xf
	v_mov_b32_dpp v91, v197 quad_perm:[3,3,3,3] row_mask:0xf bank_mask:0xf
	v_mov_b32_dpp v92, v198 quad_perm:[0,0,0,0] row_mask:0xf bank_mask:0xf
	v_mov_b32_dpp v93, v198 quad_perm:[1,1,1,1] row_mask:0xf bank_mask:0xf
	v_mov_b32_dpp v94, v198 quad_perm:[2,2,2,2] row_mask:0xf bank_mask:0xf
	v_mov_b32_dpp v95, v198 quad_perm:[3,3,3,3] row_mask:0xf bank_mask:0xf
	s_mov_b32 s35, s0
	s_waitcnt lgkmcnt(0)
	v_fma_mix_f32 v98, v84, v6, 0 op_sel:[0,0,0] op_sel_hi:[0,1,0]
	v_fma_mix_f32 v98, v85, v6, v98 op_sel:[0,1,0] op_sel_hi:[0,1,0]
	v_fma_mix_f32 v98, v86, v7, v98 op_sel:[0,0,0] op_sel_hi:[0,1,0]
	v_fma_mix_f32 v98, v87, v7, v98 op_sel:[0,1,0] op_sel_hi:[0,1,0]
	v_fma_mix_f32 v100, v88, v14, 0 op_sel:[0,0,0] op_sel_hi:[1,1,0]
	v_fma_mix_f32 v101, v88, v14, 0 op_sel:[0,1,0] op_sel_hi:[1,1,0]
	v_add_f32_dpp v98, v98, v98 quad_perm:[1,0,3,2] row_mask:0xf bank_mask:0xf bound_ctrl:1
	v_fma_mix_f32 v102, v88, v15, 0 op_sel:[0,0,0] op_sel_hi:[1,1,0]
	v_fma_mix_f32 v103, v88, v15, 0 op_sel:[0,1,0] op_sel_hi:[1,1,0]
	v_add_f32_dpp v98, v98, v98 quad_perm:[2,3,0,1] row_mask:0xf bank_mask:0xf bound_ctrl:1
	s_branch .Lc_top
.Lc_top:
	v_fma_mix_f32 v84, v84, v4, v100 op_sel:[0,0,0] op_sel_hi:[0,1,0]
	v_fma_mix_f32 v85, v85, v4, v101 op_sel:[0,1,0] op_sel_hi:[0,1,0]
	v_add_f32_dpp v98, v98, v98 row_half_mirror row_mask:0xf bank_mask:0xf bound_ctrl:1
	v_fma_mix_f32 v86, v86, v5, v102 op_sel:[0,0,0] op_sel_hi:[0,1,0]
	v_fma_mix_f32 v87, v87, v5, v103 op_sel:[0,1,0] op_sel_hi:[0,1,0]
	v_add_f32_dpp v98, v98, v98 row_mirror row_mask:0xf bank_mask:0xf bound_ctrl:1
	v_fma_mix_f32 v84, -v98, v12, v84 op_sel:[0,0,0] op_sel_hi:[0,1,0]
	v_fma_mix_f32 v85, -v98, v12, v85 op_sel:[0,1,0] op_sel_hi:[0,1,0]
	v_fma_mix_f32 v86, -v98, v13, v86 op_sel:[0,0,0] op_sel_hi:[0,1,0]
	v_fma_mix_f32 v87, -v98, v13, v87 op_sel:[0,1,0] op_sel_hi:[0,1,0]
	v_fma_mix_f32 v99, v84, v10, 0 op_sel:[0,0,0] op_sel_hi:[0,1,0]
	v_fma_mix_f32 v96, v84, v0, 0 op_sel:[0,0,0] op_sel_hi:[0,1,0]
	v_fma_mix_f32 v99, v85, v10, v99 op_sel:[0,1,0] op_sel_hi:[0,1,0]
	v_fma_mix_f32 v96, v85, v0, v96 op_sel:[0,1,0] op_sel_hi:[0,1,0]
	v_fma_mix_f32 v99, v86, v11, v99 op_sel:[0,0,0] op_sel_hi:[0,1,0]
	v_fma_mix_f32 v96, v86, v1, v96 op_sel:[0,0,0] op_sel_hi:[0,1,0]
	v_fma_mix_f32 v99, v87, v11, v99 op_sel:[0,1,0] op_sel_hi:[0,1,0]
	v_fma_mix_f32 v96, v87, v1, v96 op_sel:[0,1,0] op_sel_hi:[0,1,0]
	v_fma_mix_f32 v101, v89, v18, 0 op_sel:[0,0,0] op_sel_hi:[1,1,0]
	v_fma_mix_f32 v102, v89, v18, 0 op_sel:[0,1,0] op_sel_hi:[1,1,0]
	v_add_f32_dpp v99, v99, v99 quad_perm:[1,0,3,2] row_mask:0xf bank_mask:0xf bound_ctrl:1
	v_fma_mix_f32 v103, v89, v19, 0 op_sel:[0,0,0] op_sel_hi:[1,1,0]
	v_fma_mix_f32 v104, v89, v19, 0 op_sel:[0,1,0] op_sel_hi:[1,1,0]
	v_add_f32_dpp v99, v99, v99 quad_perm:[2,3,0,1] row_mask:0xf bank_mask:0xf bound_ctrl:1
	v_fma_mix_f32 v84, v84, v8, v101 op_sel:[0,0,0] op_sel_hi:[0,1,0]
	v_fma_mix_f32 v85, v85, v8, v102 op_sel:[0,1,0] op_sel_hi:[0,1,0]
	v_add_f32_dpp v99, v99, v99 row_half_mirror row_mask:0xf bank_mask:0xf bound_ctrl:1
	v_fma_mix_f32 v86, v86, v9, v103 op_sel:[0,0,0] op_sel_hi:[0,1,0]
	v_fma_mix_f32 v87, v87, v9, v104 op_sel:[0,1,0] op_sel_hi:[0,1,0]
	v_add_f32_dpp v99, v99, v99 row_mirror row_mask:0xf bank_mask:0xf bound_ctrl:1
	v_fma_mix_f32 v84, -v99, v16, v84 op_sel:[0,0,0] op_sel_hi:[0,1,0]
	v_fma_mix_f32 v85, -v99, v16, v85 op_sel:[0,1,0] op_sel_hi:[0,1,0]
	v_fma_mix_f32 v86, -v99, v17, v86 op_sel:[0,0,0] op_sel_hi:[0,1,0]
	v_fma_mix_f32 v87, -v99, v17, v87 op_sel:[0,1,0] op_sel_hi:[0,1,0]
	v_fma_mix_f32 v100, v84, v26, 0 op_sel:[0,0,0] op_sel_hi:[0,1,0]
	v_fma_mix_f32 v97, v84, v2, 0 op_sel:[0,0,0] op_sel_hi:[0,1,0]
	v_fma_mix_f32 v100, v85, v26, v100 op_sel:[0,1,0] op_sel_hi:[0,1,0]
	v_fma_mix_f32 v97, v85, v2, v97 op_sel:[0,1,0] op_sel_hi:[0,1,0]
	v_fma_mix_f32 v100, v86, v27, v100 op_sel:[0,0,0] op_sel_hi:[0,1,0]
	v_fma_mix_f32 v97, v86, v3, v97 op_sel:[0,0,0] op_sel_hi:[0,1,0]
	v_fma_mix_f32 v100, v87, v27, v100 op_sel:[0,1,0] op_sel_hi:[0,1,0]
	v_fma_mix_f32 v97, v87, v3, v97 op_sel:[0,1,0] op_sel_hi:[0,1,0]
	v_fma_mix_f32 v102, v90, v34, 0 op_sel:[0,0,0] op_sel_hi:[1,1,0]
	v_fma_mix_f32 v103, v90, v34, 0 op_sel:[0,1,0] op_sel_hi:[1,1,0]
	v_add_f32_dpp v100, v100, v100 quad_perm:[1,0,3,2] row_mask:0xf bank_mask:0xf bound_ctrl:1
	v_fma_mix_f32 v104, v90, v35, 0 op_sel:[0,0,0] op_sel_hi:[1,1,0]
	v_fma_mix_f32 v105, v90, v35, 0 op_sel:[0,1,0] op_sel_hi:[1,1,0]
	v_add_f32_dpp v100, v100, v100 quad_perm:[2,3,0,1] row_mask:0xf bank_mask:0xf bound_ctrl:1
	v_fma_mix_f32 v84, v84, v24, v102 op_sel:[0,0,0] op_sel_hi:[0,1,0]
	v_fma_mix_f32 v85, v85, v24, v103 op_sel:[0,1,0] op_sel_hi:[0,1,0]
	v_add_f32_dpp v100, v100, v100 row_half_mirror row_mask:0xf bank_mask:0xf bound_ctrl:1
	v_fma_mix_f32 v86, v86, v25, v104 op_sel:[0,0,0] op_sel_hi:[0,1,0]
	v_fma_mix_f32 v87, v87, v25, v105 op_sel:[0,1,0] op_sel_hi:[0,1,0]
	v_add_f32_dpp v100, v100, v100 row_mirror row_mask:0xf bank_mask:0xf bound_ctrl:1
	v_fma_mix_f32 v84, -v100, v32, v84 op_sel:[0,0,0] op_sel_hi:[0,1,0]
	v_fma_mix_f32 v85, -v100, v32, v85 op_sel:[0,1,0] op_sel_hi:[0,1,0]
	v_fma_mix_f32 v86, -v100, v33, v86 op_sel:[0,0,0] op_sel_hi:[0,1,0]
	v_fma_mix_f32 v87, -v100, v33, v87 op_sel:[0,1,0] op_sel_hi:[0,1,0]
	v_fma_mix_f32 v101, v84, v30, 0 op_sel:[0,0,0] op_sel_hi:[0,1,0]
	v_fma_mix_f32 v98, v84, v20, 0 op_sel:[0,0,0] op_sel_hi:[0,1,0]
	v_fma_mix_f32 v101, v85, v30, v101 op_sel:[0,1,0] op_sel_hi:[0,1,0]
	v_fma_mix_f32 v98, v85, v20, v98 op_sel:[0,1,0] op_sel_hi:[0,1,0]
	v_fma_mix_f32 v101, v86, v31, v101 op_sel:[0,0,0] op_sel_hi:[0,1,0]
	v_fma_mix_f32 v98, v86, v21, v98 op_sel:[0,0,0] op_sel_hi:[0,1,0]
	v_fma_mix_f32 v101, v87, v31, v101 op_sel:[0,1,0] op_sel_hi:[0,1,0]
	v_fma_mix_f32 v98, v87, v21, v98 op_sel:[0,1,0] op_sel_hi:[0,1,0]
	v_fma_mix_f32 v103, v91, v38, 0 op_sel:[0,0,0] op_sel_hi:[1,1,0]
	v_fma_mix_f32 v104, v91, v38, 0 op_sel:[0,1,0] op_sel_hi:[1,1,0]
	v_add_f32_dpp v101, v101, v101 quad_perm:[1,0,3,2] row_mask:0xf bank_mask:0xf bound_ctrl:1
	v_fma_mix_f32 v105, v91, v39, 0 op_sel:[0,0,0] op_sel_hi:[1,1,0]
	v_fma_mix_f32 v119, v91, v39, 0 op_sel:[0,1,0] op_sel_hi:[1,1,0]
	v_add_f32_dpp v101, v101, v101 quad_perm:[2,3,0,1] row_mask:0xf bank_mask:0xf bound_ctrl:1
	v_fma_mix_f32 v84, v84, v28, v103 op_sel:[0,0,0] op_sel_hi:[0,1,0]
	v_fma_mix_f32 v85, v85, v28, v104 op_sel:[0,1,0] op_sel_hi:[0,1,0]
	v_add_f32_dpp v101, v101, v101 row_half_mirror row_mask:0xf bank_mask:0xf bound_ctrl:1
	v_fma_mix_f32 v86, v86, v29, v105 op_sel:[0,0,0] op_sel_hi:[0,1,0]
	v_fma_mix_f32 v87, v87, v29, v119 op_sel:[0,1,0] op_sel_hi:[0,1,0]
	v_add_f32_dpp v101, v101, v101 row_mirror row_mask:0xf bank_mask:0xf bound_ctrl:1
	v_fma_mix_f32 v84, -v101, v36, v84 op_sel:[0,0,0] op_sel_hi:[0,1,0]
	v_fma_mix_f32 v85, -v101, v36, v85 op_sel:[0,1,0] op_sel_hi:[0,1,0]
	v_fma_mix_f32 v86, -v101, v37, v86 op_sel:[0,0,0] op_sel_hi:[0,1,0]
	v_fma_mix_f32 v87, -v101, v37, v87 op_sel:[0,1,0] op_sel_hi:[0,1,0]
	v_fma_mix_f32 v99, v84, v22, 0 op_sel:[0,0,0] op_sel_hi:[0,1,0]
	v_cndmask_b32_e64 v187, v97, v96, s[38:39]
	v_fma_mix_f32 v99, v85, v22, v99 op_sel:[0,1,0] op_sel_hi:[0,1,0]
	v_cndmask_b32_e64 v188, v96, v97, s[38:39]
	v_fma_mix_f32 v99, v86, v23, v99 op_sel:[0,0,0] op_sel_hi:[0,1,0]
	v_fma_mix_f32 v99, v87, v23, v99 op_sel:[0,1,0] op_sel_hi:[0,1,0]
	v_cndmask_b32_e64 v189, v99, v98, s[38:39]
	v_cndmask_b32_e64 v190, v98, v99, s[38:39]
	s_waitcnt lgkmcnt(0)
	v_fma_mix_f32 v98, v84, v74, 0 op_sel:[0,0,0] op_sel_hi:[0,1,0]
	v_fma_mix_f32 v98, v85, v74, v98 op_sel:[0,1,0] op_sel_hi:[0,1,0]
	v_add_f32_dpp v188, v188, v187 quad_perm:[1,0,3,2] row_mask:0xf bank_mask:0xf bound_ctrl:1
	v_add_f32_dpp v189, v190, v189 quad_perm:[1,0,3,2] row_mask:0xf bank_mask:0xf bound_ctrl:1
	v_fma_mix_f32 v98, v86, v75, v98 op_sel:[0,0,0] op_sel_hi:[0,1,0]
	v_fma_mix_f32 v98, v87, v75, v98 op_sel:[0,1,0] op_sel_hi:[0,1,0]
	v_cndmask_b32_e64 v191, v189, v188, s[40:41]
	v_cndmask_b32_e64 v192, v188, v189, s[40:41]
	v_fma_mix_f32 v100, v92, v78, 0 op_sel:[0,0,0] op_sel_hi:[1,1,0]
	v_fma_mix_f32 v101, v92, v78, 0 op_sel:[0,1,0] op_sel_hi:[1,1,0]
	v_add_f32_dpp v192, v192, v191 quad_perm:[2,3,0,1] row_mask:0xf bank_mask:0xf bound_ctrl:1
	v_add_f32_dpp v98, v98, v98 quad_perm:[1,0,3,2] row_mask:0xf bank_mask:0xf bound_ctrl:1
	v_fma_mix_f32 v102, v92, v79, 0 op_sel:[0,0,0] op_sel_hi:[1,1,0]
	v_add_f32_dpp v192, v192, v192 row_ror:4 row_mask:0xf bank_mask:0xf bound_ctrl:1
	v_fma_mix_f32 v103, v92, v79, 0 op_sel:[0,1,0] op_sel_hi:[1,1,0]
	v_add_f32_dpp v98, v98, v98 quad_perm:[2,3,0,1] row_mask:0xf bank_mask:0xf bound_ctrl:1
	v_add_f32_dpp v192, v192, v192 row_ror:8 row_mask:0xf bank_mask:0xf bound_ctrl:1
	v_cvt_f16_f32_e32 v192, v192
	global_store_short v83, v192, s[36:37]
	s_add_u32 s36, s36, s44
	s_addc_u32 s37, s37, s45
	global_load_ushort v205, v83, s[22:23]
	s_add_u32 s22, s22, s44
	s_addc_u32 s23, s23, s45
	s_cmp_gt_i32 s35, 3
	s_cbranch_scc0 .Lc_poll_A0
.Lc_ret_A0:
	ds_read_b128 v[0:3], v194 offset:8192
	ds_read_b128 v[4:7], v194 offset:6144
	ds_read_b128 v[8:11], v194 offset:6400
	ds_read_b128 v[12:15], v194 offset:7168
	ds_read_b128 v[16:19], v194 offset:7424
	ds_read_b128 v[20:23], v194 offset:8448
	ds_read_b128 v[24:27], v194 offset:6656
	ds_read_b128 v[28:31], v194 offset:6912
	ds_read_b128 v[32:35], v194 offset:7680
	ds_read_b128 v[36:39], v194 offset:7936
	s_waitcnt vmcnt(12)
	v_mov_b32_dpp v88, v199 quad_perm:[0,0,0,0] row_mask:0xf bank_mask:0xf
	v_mov_b32_dpp v89, v199 quad_perm:[1,1,1,1] row_mask:0xf bank_mask:0xf
	v_mov_b32_dpp v90, v199 quad_perm:[2,2,2,2] row_mask:0xf bank_mask:0xf
	v_mov_b32_dpp v91, v199 quad_perm:[3,3,3,3] row_mask:0xf bank_mask:0xf
	v_fma_mix_f32 v84, v84, v72, v100 op_sel:[0,0,0] op_sel_hi:[0,1,0]
	v_fma_mix_f32 v85, v85, v72, v101 op_sel:[0,1,0] op_sel_hi:[0,1,0]
	v_add_f32_dpp v98, v98, v98 row_half_mirror row_mask:0xf bank_mask:0xf bound_ctrl:1
	v_fma_mix_f32 v86, v86, v73, v102 op_sel:[0,0,0] op_sel_hi:[0,1,0]
	v_fma_mix_f32 v87, v87, v73, v103 op_sel:[0,1,0] op_sel_hi:[0,1,0]
	v_add_f32_dpp v98, v98, v98 row_mirror row_mask:0xf bank_mask:0xf bound_ctrl:1
	v_fma_mix_f32 v84, -v98, v76, v84 op_sel:[0,0,0] op_sel_hi:[0,1,0]
	v_fma_mix_f32 v85, -v98, v76, v85 op_sel:[0,1,0] op_sel_hi:[0,1,0]
	v_fma_mix_f32 v86, -v98, v77, v86 op_sel:[0,0,0] op_sel_hi:[0,1,0]
	v_fma_mix_f32 v87, -v98, v77, v87 op_sel:[0,1,0] op_sel_hi:[0,1,0]
	v_fma_mix_f32 v73, v84, v66, 0 op_sel:[0,0,0] op_sel_hi:[0,1,0]
	v_fma_mix_f32 v97, v84, v56, 0 op_sel:[0,0,0] op_sel_hi:[0,1,0]
	v_fma_mix_f32 v73, v85, v66, v73 op_sel:[0,1,0] op_sel_hi:[0,1,0]
	v_fma_mix_f32 v56, v85, v56, v97 op_sel:[0,1,0] op_sel_hi:[0,1,0]
	v_fma_mix_f32 v73, v86, v67, v73 op_sel:[0,0,0] op_sel_hi:[0,1,0]
	v_fma_mix_f32 v56, v86, v57, v56 op_sel:[0,0,0] op_sel_hi:[0,1,0]
	v_fma_mix_f32 v73, v87, v67, v73 op_sel:[0,1,0] op_sel_hi:[0,1,0]
	v_fma_mix_f32 v56, v87, v57, v56 op_sel:[0,1,0] op_sel_hi:[0,1,0]
	v_fma_mix_f32 v75, v93, v70, 0 op_sel:[0,0,0] op_sel_hi:[1,1,0]
	v_fma_mix_f32 v76, v93, v70, 0 op_sel:[0,1,0] op_sel_hi:[1,1,0]
	v_add_f32_dpp v73, v73, v73 quad_perm:[1,0,3,2] row_mask:0xf bank_mask:0xf bound_ctrl:1
	v_fma_mix_f32 v77, v93, v71, 0 op_sel:[0,0,0] op_sel_hi:[1,1,0]
	v_fma_mix_f32 v78, v93, v71, 0 op_sel:[0,1,0] op_sel_hi:[1,1,0]
	v_add_f32_dpp v73, v73, v73 quad_perm:[2,3,0,1] row_mask:0xf bank_mask:0xf bound_ctrl:1
	v_fma_mix_f32 v84, v84, v64, v75 op_sel:[0,0,0] op_sel_hi:[0,1,0]
	v_fma_mix_f32 v85, v85, v64, v76 op_sel:[0,1,0] op_sel_hi:[0,1,0]
	v_add_f32_dpp v73, v73, v73 row_half_mirror row_mask:0xf bank_mask:0xf bound_ctrl:1
	v_fma_mix_f32 v86, v86, v65, v77 op_sel:[0,0,0] op_sel_hi:[0,1,0]
	v_fma_mix_f32 v87, v87, v65, v78 op_sel:[0,1,0] op_sel_hi:[0,1,0]
	v_add_f32_dpp v73, v73, v73 row_mirror row_mask:0xf bank_mask:0xf bound_ctrl:1
	v_fma_mix_f32 v84, -v73, v68, v84 op_sel:[0,0,0] op_sel_hi:[0,1,0]
	v_fma_mix_f32 v85, -v73, v68, v85 op_sel:[0,1,0] op_sel_hi:[0,1,0]
	v_fma_mix_f32 v86, -v73, v69, v86 op_sel:[0,0,0] op_sel_hi:[0,1,0]
	v_fma_mix_f32 v87, -v73, v69, v87 op_sel:[0,1,0] op_sel_hi:[0,1,0]
	v_fma_mix_f32 v64, v84, v54, 0 op_sel:[0,0,0] op_sel_hi:[0,1,0]
	v_fma_mix_f32 v57, v84, v58, 0 op_sel:[0,0,0] op_sel_hi:[0,1,0]
	v_fma_mix_f32 v64, v85, v54, v64 op_sel:[0,1,0] op_sel_hi:[0,1,0]
	v_fma_mix_f32 v57, v85, v58, v57 op_sel:[0,1,0] op_sel_hi:[0,1,0]
	v_fma_mix_f32 v64, v86, v55, v64 op_sel:[0,0,0] op_sel_hi:[0,1,0]
	v_fma_mix_f32 v57, v86, v59, v57 op_sel:[0,0,0] op_sel_hi:[0,1,0]
	v_fma_mix_f32 v64, v87, v55, v64 op_sel:[0,1,0] op_sel_hi:[0,1,0]
	v_fma_mix_f32 v57, v87, v59, v57 op_sel:[0,1,0] op_sel_hi:[0,1,0]
	v_fma_mix_f32 v66, v94, v62, 0 op_sel:[0,0,0] op_sel_hi:[1,1,0]
	v_fma_mix_f32 v67, v94, v62, 0 op_sel:[0,1,0] op_sel_hi:[1,1,0]
	v_add_f32_dpp v64, v64, v64 quad_perm:[1,0,3,2] row_mask:0xf bank_mask:0xf bound_ctrl:1
	v_fma_mix_f32 v68, v94, v63, 0 op_sel:[0,0,0] op_sel_hi:[1,1,0]
	v_fma_mix_f32 v69, v94, v63, 0 op_sel:[0,1,0] op_sel_hi:[1,1,0]
	v_add_f32_dpp v64, v64, v64 quad_perm:[2,3,0,1] row_mask:0xf bank_mask:0xf bound_ctrl:1
	v_fma_mix_f32 v84, v84, v52, v66 op_sel:[0,0,0] op_sel_hi:[0,1,0]
	v_fma_mix_f32 v85, v85, v52, v67 op_sel:[0,1,0] op_sel_hi:[0,1,0]
	v_add_f32_dpp v64, v64, v64 row_half_mirror row_mask:0xf bank_mask:0xf bound_ctrl:1
	v_fma_mix_f32 v86, v86, v53, v68 op_sel:[0,0,0] op_sel_hi:[0,1,0]
	v_fma_mix_f32 v87, v87, v53, v69 op_sel:[0,1,0] op_sel_hi:[0,1,0]
	v_add_f32_dpp v64, v64, v64 row_mirror row_mask:0xf bank_mask:0xf bound_ctrl:1
	v_fma_mix_f32 v84, -v64, v60, v84 op_sel:[0,0,0] op_sel_hi:[0,1,0]
	v_fma_mix_f32 v85, -v64, v60, v85 op_sel:[0,1,0] op_sel_hi:[0,1,0]
	v_fma_mix_f32 v86, -v64, v61, v86 op_sel:[0,0,0] op_sel_hi:[0,1,0]
	v_fma_mix_f32 v87, -v64, v61, v87 op_sel:[0,1,0] op_sel_hi:[0,1,0]
	v_fma_mix_f32 v53, v84, v46, 0 op_sel:[0,0,0] op_sel_hi:[0,1,0]
	v_fma_mix_f32 v59, v84, v40, 0 op_sel:[0,0,0] op_sel_hi:[0,1,0]
	v_fma_mix_f32 v53, v85, v46, v53 op_sel:[0,1,0] op_sel_hi:[0,1,0]
	v_fma_mix_f32 v40, v85, v40, v59 op_sel:[0,1,0] op_sel_hi:[0,1,0]
	v_fma_mix_f32 v53, v86, v47, v53 op_sel:[0,0,0] op_sel_hi:[0,1,0]
	v_fma_mix_f32 v40, v86, v41, v40 op_sel:[0,0,0] op_sel_hi:[0,1,0]
	v_fma_mix_f32 v53, v87, v47, v53 op_sel:[0,1,0] op_sel_hi:[0,1,0]
	v_fma_mix_f32 v40, v87, v41, v40 op_sel:[0,1,0] op_sel_hi:[0,1,0]
	v_fma_mix_f32 v55, v95, v50, 0 op_sel:[0,0,0] op_sel_hi:[1,1,0]
	v_fma_mix_f32 v58, v95, v50, 0 op_sel:[0,1,0] op_sel_hi:[1,1,0]
	v_add_f32_dpp v53, v53, v53 quad_perm:[1,0,3,2] row_mask:0xf bank_mask:0xf bound_ctrl:1
	v_fma_mix_f32 v59, v95, v51, 0 op_sel:[0,0,0] op_sel_hi:[1,1,0]
	v_fma_mix_f32 v60, v95, v51, 0 op_sel:[0,1,0] op_sel_hi:[1,1,0]
	v_add_f32_dpp v53, v53, v53 quad_perm:[2,3,0,1] row_mask:0xf bank_mask:0xf bound_ctrl:1
	v_fma_mix_f32 v84, v84, v44, v55 op_sel:[0,0,0] op_sel_hi:[0,1,0]
	v_fma_mix_f32 v85, v85, v44, v58 op_sel:[0,1,0] op_sel_hi:[0,1,0]
	v_add_f32_dpp v53, v53, v53 row_half_mirror row_mask:0xf bank_mask:0xf bound_ctrl:1
	v_fma_mix_f32 v86, v86, v45, v59 op_sel:[0,0,0] op_sel_hi:[0,1,0]
	v_fma_mix_f32 v87, v87, v45, v60 op_sel:[0,1,0] op_sel_hi:[0,1,0]
	v_add_f32_dpp v53, v53, v53 row_mirror row_mask:0xf bank_mask:0xf bound_ctrl:1
	v_fma_mix_f32 v84, -v53, v48, v84 op_sel:[0,0,0] op_sel_hi:[0,1,0]
	v_fma_mix_f32 v85, -v53, v48, v85 op_sel:[0,1,0] op_sel_hi:[0,1,0]
	v_fma_mix_f32 v86, -v53, v49, v86 op_sel:[0,0,0] op_sel_hi:[0,1,0]
	v_fma_mix_f32 v87, -v53, v49, v87 op_sel:[0,1,0] op_sel_hi:[0,1,0]
	v_fma_mix_f32 v41, v84, v42, 0 op_sel:[0,0,0] op_sel_hi:[0,1,0]
	v_cndmask_b32_e64 v187, v57, v56, s[38:39]
	v_fma_mix_f32 v41, v85, v42, v41 op_sel:[0,1,0] op_sel_hi:[0,1,0]
	v_cndmask_b32_e64 v188, v56, v57, s[38:39]
	v_fma_mix_f32 v41, v86, v43, v41 op_sel:[0,0,0] op_sel_hi:[0,1,0]
	v_fma_mix_f32 v41, v87, v43, v41 op_sel:[0,1,0] op_sel_hi:[0,1,0]
	v_cndmask_b32_e64 v189, v41, v40, s[38:39]
	v_cndmask_b32_e64 v190, v40, v41, s[38:39]
	s_waitcnt lgkmcnt(0)
	v_fma_mix_f32 v98, v84, v6, 0 op_sel:[0,0,0] op_sel_hi:[0,1,0]
	v_fma_mix_f32 v98, v85, v6, v98 op_sel:[0,1,0] op_sel_hi:[0,1,0]
	v_add_f32_dpp v188, v188, v187 quad_perm:[1,0,3,2] row_mask:0xf bank_mask:0xf bound_ctrl:1
	v_add_f32_dpp v189, v190, v189 quad_perm:[1,0,3,2] row_mask:0xf bank_mask:0xf bound_ctrl:1
	v_fma_mix_f32 v98, v86, v7, v98 op_sel:[0,0,0] op_sel_hi:[0,1,0]
	v_fma_mix_f32 v98, v87, v7, v98 op_sel:[0,1,0] op_sel_hi:[0,1,0]
	v_cndmask_b32_e64 v191, v189, v188, s[40:41]
	v_cndmask_b32_e64 v192, v188, v189, s[40:41]
	v_fma_mix_f32 v100, v88, v14, 0 op_sel:[0,0,0] op_sel_hi:[1,1,0]
	v_fma_mix_f32 v101, v88, v14, 0 op_sel:[0,1,0] op_sel_hi:[1,1,0]
	v_add_f32_dpp v192, v192, v191 quad_perm:[2,3,0,1] row_mask:0xf bank_mask:0xf bound_ctrl:1
	v_add_f32_dpp v98, v98, v98 quad_perm:[1,0,3,2] row_mask:0xf bank_mask:0xf bound_ctrl:1
	v_fma_mix_f32 v102, v88, v15, 0 op_sel:[0,0,0] op_sel_hi:[1,1,0]
	v_add_f32_dpp v192, v192, v192 row_ror:4 row_mask:0xf bank_mask:0xf bound_ctrl:1
	v_fma_mix_f32 v103, v88, v15, 0 op_sel:[0,1,0] op_sel_hi:[1,1,0]
	v_add_f32_dpp v98, v98, v98 quad_perm:[2,3,0,1] row_mask:0xf bank_mask:0xf bound_ctrl:1
	v_add_f32_dpp v192, v192, v192 row_ror:8 row_mask:0xf bank_mask:0xf bound_ctrl:1
	v_cvt_f16_f32_e32 v192, v192
	global_store_short v83, v192, s[36:37]
	s_add_u32 s36, s36, s44
	s_addc_u32 s37, s37, s45
	global_load_ushort v206, v83, s[22:23]
	s_add_u32 s22, s22, s44
	s_addc_u32 s23, s23, s45
	ds_read_b128 v[56:59], v194 offset:11264
	ds_read_b128 v[72:75], v194 offset:9216
	ds_read_b128 v[64:67], v194 offset:9472
	ds_read_b128 v[76:79], v194 offset:10240
	ds_read_b128 v[68:71], v194 offset:10496
	ds_read_b128 v[40:43], v194 offset:11520
	ds_read_b128 v[52:55], v194 offset:9728
	ds_read_b128 v[44:47], v194 offset:9984
	ds_read_b128 v[60:63], v194 offset:10752
	ds_read_b128 v[48:51], v194 offset:11008
	s_waitcnt vmcnt(12)
	v_mov_b32_dpp v92, v200 quad_perm:[0,0,0,0] row_mask:0xf bank_mask:0xf
	v_mov_b32_dpp v93, v200 quad_perm:[1,1,1,1] row_mask:0xf bank_mask:0xf
	v_mov_b32_dpp v94, v200 quad_perm:[2,2,2,2] row_mask:0xf bank_mask:0xf
	v_mov_b32_dpp v95, v200 quad_perm:[3,3,3,3] row_mask:0xf bank_mask:0xf
	v_fma_mix_f32 v84, v84, v4, v100 op_sel:[0,0,0] op_sel_hi:[0,1,0]
	v_fma_mix_f32 v85, v85, v4, v101 op_sel:[0,1,0] op_sel_hi:[0,1,0]
	v_add_f32_dpp v98, v98, v98 row_half_mirror row_mask:0xf bank_mask:0xf bound_ctrl:1
	v_fma_mix_f32 v86, v86, v5, v102 op_sel:[0,0,0] op_sel_hi:[0,1,0]
	v_fma_mix_f32 v87, v87, v5, v103 op_sel:[0,1,0] op_sel_hi:[0,1,0]
	v_add_f32_dpp v98, v98, v98 row_mirror row_mask:0xf bank_mask:0xf bound_ctrl:1
	v_fma_mix_f32 v84, -v98, v12, v84 op_sel:[0,0,0] op_sel_hi:[0,1,0]
	v_fma_mix_f32 v85, -v98, v12, v85 op_sel:[0,1,0] op_sel_hi:[0,1,0]
	v_fma_mix_f32 v86, -v98, v13, v86 op_sel:[0,0,0] op_sel_hi:[0,1,0]
	v_fma_mix_f32 v87, -v98, v13, v87 op_sel:[0,1,0] op_sel_hi:[0,1,0]
	v_fma_mix_f32 v99, v84, v10, 0 op_sel:[0,0,0] op_sel_hi:[0,1,0]
	v_fma_mix_f32 v96, v84, v0, 0 op_sel:[0,0,0] op_sel_hi:[0,1,0]
	v_fma_mix_f32 v99, v85, v10, v99 op_sel:[0,1,0] op_sel_hi:[0,1,0]
	v_fma_mix_f32 v96, v85, v0, v96 op_sel:[0,1,0] op_sel_hi:[0,1,0]
	v_fma_mix_f32 v99, v86, v11, v99 op_sel:[0,0,0] op_sel_hi:[0,1,0]
	v_fma_mix_f32 v96, v86, v1, v96 op_sel:[0,0,0] op_sel_hi:[0,1,0]
	v_fma_mix_f32 v99, v87, v11, v99 op_sel:[0,1,0] op_sel_hi:[0,1,0]
	v_fma_mix_f32 v96, v87, v1, v96 op_sel:[0,1,0] op_sel_hi:[0,1,0]
	v_fma_mix_f32 v101, v89, v18, 0 op_sel:[0,0,0] op_sel_hi:[1,1,0]
	v_fma_mix_f32 v102, v89, v18, 0 op_sel:[0,1,0] op_sel_hi:[1,1,0]
	v_add_f32_dpp v99, v99, v99 quad_perm:[1,0,3,2] row_mask:0xf bank_mask:0xf bound_ctrl:1
	v_fma_mix_f32 v103, v89, v19, 0 op_sel:[0,0,0] op_sel_hi:[1,1,0]
	v_fma_mix_f32 v104, v89, v19, 0 op_sel:[0,1,0] op_sel_hi:[1,1,0]
	v_add_f32_dpp v99, v99, v99 quad_perm:[2,3,0,1] row_mask:0xf bank_mask:0xf bound_ctrl:1
	v_fma_mix_f32 v84, v84, v8, v101 op_sel:[0,0,0] op_sel_hi:[0,1,0]
	v_fma_mix_f32 v85, v85, v8, v102 op_sel:[0,1,0] op_sel_hi:[0,1,0]
	v_add_f32_dpp v99, v99, v99 row_half_mirror row_mask:0xf bank_mask:0xf bound_ctrl:1
	v_fma_mix_f32 v86, v86, v9, v103 op_sel:[0,0,0] op_sel_hi:[0,1,0]
	v_fma_mix_f32 v87, v87, v9, v104 op_sel:[0,1,0] op_sel_hi:[0,1,0]
	v_add_f32_dpp v99, v99, v99 row_mirror row_mask:0xf bank_mask:0xf bound_ctrl:1
	v_fma_mix_f32 v84, -v99, v16, v84 op_sel:[0,0,0] op_sel_hi:[0,1,0]
	v_fma_mix_f32 v85, -v99, v16, v85 op_sel:[0,1,0] op_sel_hi:[0,1,0]
	v_fma_mix_f32 v86, -v99, v17, v86 op_sel:[0,0,0] op_sel_hi:[0,1,0]
	v_fma_mix_f32 v87, -v99, v17, v87 op_sel:[0,1,0] op_sel_hi:[0,1,0]
	v_fma_mix_f32 v100, v84, v26, 0 op_sel:[0,0,0] op_sel_hi:[0,1,0]
	v_fma_mix_f32 v97, v84, v2, 0 op_sel:[0,0,0] op_sel_hi:[0,1,0]
	v_fma_mix_f32 v100, v85, v26, v100 op_sel:[0,1,0] op_sel_hi:[0,1,0]
	v_fma_mix_f32 v97, v85, v2, v97 op_sel:[0,1,0] op_sel_hi:[0,1,0]
	v_fma_mix_f32 v100, v86, v27, v100 op_sel:[0,0,0] op_sel_hi:[0,1,0]
	v_fma_mix_f32 v97, v86, v3, v97 op_sel:[0,0,0] op_sel_hi:[0,1,0]
	v_fma_mix_f32 v100, v87, v27, v100 op_sel:[0,1,0] op_sel_hi:[0,1,0]
	v_fma_mix_f32 v97, v87, v3, v97 op_sel:[0,1,0] op_sel_hi:[0,1,0]
	v_fma_mix_f32 v102, v90, v34, 0 op_sel:[0,0,0] op_sel_hi:[1,1,0]
	v_fma_mix_f32 v103, v90, v34, 0 op_sel:[0,1,0] op_sel_hi:[1,1,0]
	v_add_f32_dpp v100, v100, v100 quad_perm:[1,0,3,2] row_mask:0xf bank_mask:0xf bound_ctrl:1
	v_fma_mix_f32 v104, v90, v35, 0 op_sel:[0,0,0] op_sel_hi:[1,1,0]
	v_fma_mix_f32 v105, v90, v35, 0 op_sel:[0,1,0] op_sel_hi:[1,1,0]
	v_add_f32_dpp v100, v100, v100 quad_perm:[2,3,0,1] row_mask:0xf bank_mask:0xf bound_ctrl:1
	v_fma_mix_f32 v84, v84, v24, v102 op_sel:[0,0,0] op_sel_hi:[0,1,0]
	v_fma_mix_f32 v85, v85, v24, v103 op_sel:[0,1,0] op_sel_hi:[0,1,0]
	v_add_f32_dpp v100, v100, v100 row_half_mirror row_mask:0xf bank_mask:0xf bound_ctrl:1
	v_fma_mix_f32 v86, v86, v25, v104 op_sel:[0,0,0] op_sel_hi:[0,1,0]
	v_fma_mix_f32 v87, v87, v25, v105 op_sel:[0,1,0] op_sel_hi:[0,1,0]
	v_add_f32_dpp v100, v100, v100 row_mirror row_mask:0xf bank_mask:0xf bound_ctrl:1
	v_fma_mix_f32 v84, -v100, v32, v84 op_sel:[0,0,0] op_sel_hi:[0,1,0]
	v_fma_mix_f32 v85, -v100, v32, v85 op_sel:[0,1,0] op_sel_hi:[0,1,0]
	v_fma_mix_f32 v86, -v100, v33, v86 op_sel:[0,0,0] op_sel_hi:[0,1,0]
	v_fma_mix_f32 v87, -v100, v33, v87 op_sel:[0,1,0] op_sel_hi:[0,1,0]
	v_fma_mix_f32 v101, v84, v30, 0 op_sel:[0,0,0] op_sel_hi:[0,1,0]
	v_fma_mix_f32 v98, v84, v20, 0 op_sel:[0,0,0] op_sel_hi:[0,1,0]
	v_fma_mix_f32 v101, v85, v30, v101 op_sel:[0,1,0] op_sel_hi:[0,1,0]
	v_fma_mix_f32 v98, v85, v20, v98 op_sel:[0,1,0] op_sel_hi:[0,1,0]
	v_fma_mix_f32 v101, v86, v31, v101 op_sel:[0,0,0] op_sel_hi:[0,1,0]
	v_fma_mix_f32 v98, v86, v21, v98 op_sel:[0,0,0] op_sel_hi:[0,1,0]
	v_fma_mix_f32 v101, v87, v31, v101 op_sel:[0,1,0] op_sel_hi:[0,1,0]
	v_fma_mix_f32 v98, v87, v21, v98 op_sel:[0,1,0] op_sel_hi:[0,1,0]
	v_fma_mix_f32 v103, v91, v38, 0 op_sel:[0,0,0] op_sel_hi:[1,1,0]
	v_fma_mix_f32 v104, v91, v38, 0 op_sel:[0,1,0] op_sel_hi:[1,1,0]
	v_add_f32_dpp v101, v101, v101 quad_perm:[1,0,3,2] row_mask:0xf bank_mask:0xf bound_ctrl:1
	v_fma_mix_f32 v105, v91, v39, 0 op_sel:[0,0,0] op_sel_hi:[1,1,0]
	v_fma_mix_f32 v119, v91, v39, 0 op_sel:[0,1,0] op_sel_hi:[1,1,0]
	v_add_f32_dpp v101, v101, v101 quad_perm:[2,3,0,1] row_mask:0xf bank_mask:0xf bound_ctrl:1
	v_fma_mix_f32 v84, v84, v28, v103 op_sel:[0,0,0] op_sel_hi:[0,1,0]
	v_fma_mix_f32 v85, v85, v28, v104 op_sel:[0,1,0] op_sel_hi:[0,1,0]
	v_add_f32_dpp v101, v101, v101 row_half_mirror row_mask:0xf bank_mask:0xf bound_ctrl:1
	v_fma_mix_f32 v86, v86, v29, v105 op_sel:[0,0,0] op_sel_hi:[0,1,0]
	v_fma_mix_f32 v87, v87, v29, v119 op_sel:[0,1,0] op_sel_hi:[0,1,0]
	v_add_f32_dpp v101, v101, v101 row_mirror row_mask:0xf bank_mask:0xf bound_ctrl:1
	v_fma_mix_f32 v84, -v101, v36, v84 op_sel:[0,0,0] op_sel_hi:[0,1,0]
	v_fma_mix_f32 v85, -v101, v36, v85 op_sel:[0,1,0] op_sel_hi:[0,1,0]
	v_fma_mix_f32 v86, -v101, v37, v86 op_sel:[0,0,0] op_sel_hi:[0,1,0]
	v_fma_mix_f32 v87, -v101, v37, v87 op_sel:[0,1,0] op_sel_hi:[0,1,0]
	v_fma_mix_f32 v99, v84, v22, 0 op_sel:[0,0,0] op_sel_hi:[0,1,0]
	v_cndmask_b32_e64 v187, v97, v96, s[38:39]
	v_fma_mix_f32 v99, v85, v22, v99 op_sel:[0,1,0] op_sel_hi:[0,1,0]
	v_cndmask_b32_e64 v188, v96, v97, s[38:39]
	v_fma_mix_f32 v99, v86, v23, v99 op_sel:[0,0,0] op_sel_hi:[0,1,0]
	v_fma_mix_f32 v99, v87, v23, v99 op_sel:[0,1,0] op_sel_hi:[0,1,0]
	v_cndmask_b32_e64 v189, v99, v98, s[38:39]
	v_cndmask_b32_e64 v190, v98, v99, s[38:39]
	s_waitcnt lgkmcnt(0)
	v_fma_mix_f32 v98, v84, v74, 0 op_sel:[0,0,0] op_sel_hi:[0,1,0]
	v_fma_mix_f32 v98, v85, v74, v98 op_sel:[0,1,0] op_sel_hi:[0,1,0]
	v_add_f32_dpp v188, v188, v187 quad_perm:[1,0,3,2] row_mask:0xf bank_mask:0xf bound_ctrl:1
	v_add_f32_dpp v189, v190, v189 quad_perm:[1,0,3,2] row_mask:0xf bank_mask:0xf bound_ctrl:1
	v_fma_mix_f32 v98, v86, v75, v98 op_sel:[0,0,0] op_sel_hi:[0,1,0]
	v_fma_mix_f32 v98, v87, v75, v98 op_sel:[0,1,0] op_sel_hi:[0,1,0]
	v_cndmask_b32_e64 v191, v189, v188, s[40:41]
	v_cndmask_b32_e64 v192, v188, v189, s[40:41]
	v_fma_mix_f32 v100, v92, v78, 0 op_sel:[0,0,0] op_sel_hi:[1,1,0]
	v_fma_mix_f32 v101, v92, v78, 0 op_sel:[0,1,0] op_sel_hi:[1,1,0]
	v_add_f32_dpp v192, v192, v191 quad_perm:[2,3,0,1] row_mask:0xf bank_mask:0xf bound_ctrl:1
	v_add_f32_dpp v98, v98, v98 quad_perm:[1,0,3,2] row_mask:0xf bank_mask:0xf bound_ctrl:1
	v_fma_mix_f32 v102, v92, v79, 0 op_sel:[0,0,0] op_sel_hi:[1,1,0]
	v_add_f32_dpp v192, v192, v192 row_ror:4 row_mask:0xf bank_mask:0xf bound_ctrl:1
	v_fma_mix_f32 v103, v92, v79, 0 op_sel:[0,1,0] op_sel_hi:[1,1,0]
	v_add_f32_dpp v98, v98, v98 quad_perm:[2,3,0,1] row_mask:0xf bank_mask:0xf bound_ctrl:1
	v_add_f32_dpp v192, v192, v192 row_ror:8 row_mask:0xf bank_mask:0xf bound_ctrl:1
	v_cvt_f16_f32_e32 v192, v192
	global_store_short v83, v192, s[36:37]
	s_add_u32 s36, s36, s44
	s_addc_u32 s37, s37, s45
	global_load_ushort v207, v83, s[22:23]
	s_add_u32 s22, s22, s44
	s_addc_u32 s23, s23, s45
	s_cmp_gt_i32 s35, 5
	s_cbranch_scc0 .Lc_poll_A1
.Lc_ret_A1:
	ds_read_b128 v[0:3], v194 offset:14336
	ds_read_b128 v[4:7], v194 offset:12288
	ds_read_b128 v[8:11], v194 offset:12544
	ds_read_b128 v[12:15], v194 offset:13312
	ds_read_b128 v[16:19], v194 offset:13568
	ds_read_b128 v[20:23], v194 offset:14592
	ds_read_b128 v[24:27], v194 offset:12800
	ds_read_b128 v[28:31], v194 offset:13056
	ds_read_b128 v[32:35], v194 offset:13824
	ds_read_b128 v[36:39], v194 offset:14080
	s_waitcnt vmcnt(12)
	v_mov_b32_dpp v88, v201 quad_perm:[0,0,0,0] row_mask:0xf bank_mask:0xf
	v_mov_b32_dpp v89, v201 quad_perm:[1,1,1,1] row_mask:0xf bank_mask:0xf
	v_mov_b32_dpp v90, v201 quad_perm:[2,2,2,2] row_mask:0xf bank_mask:0xf
	v_mov_b32_dpp v91, v201 quad_perm:[3,3,3,3] row_mask:0xf bank_mask:0xf
	v_fma_mix_f32 v84, v84, v72, v100 op_sel:[0,0,0] op_sel_hi:[0,1,0]
	v_fma_mix_f32 v85, v85, v72, v101 op_sel:[0,1,0] op_sel_hi:[0,1,0]
	v_add_f32_dpp v98, v98, v98 row_half_mirror row_mask:0xf bank_mask:0xf bound_ctrl:1
	v_fma_mix_f32 v86, v86, v73, v102 op_sel:[0,0,0] op_sel_hi:[0,1,0]
	v_fma_mix_f32 v87, v87, v73, v103 op_sel:[0,1,0] op_sel_hi:[0,1,0]
	v_add_f32_dpp v98, v98, v98 row_mirror row_mask:0xf bank_mask:0xf bound_ctrl:1
	v_fma_mix_f32 v84, -v98, v76, v84 op_sel:[0,0,0] op_sel_hi:[0,1,0]
	v_fma_mix_f32 v85, -v98, v76, v85 op_sel:[0,1,0] op_sel_hi:[0,1,0]
	v_fma_mix_f32 v86, -v98, v77, v86 op_sel:[0,0,0] op_sel_hi:[0,1,0]
	v_fma_mix_f32 v87, -v98, v77, v87 op_sel:[0,1,0] op_sel_hi:[0,1,0]
	v_fma_mix_f32 v73, v84, v66, 0 op_sel:[0,0,0] op_sel_hi:[0,1,0]
	v_fma_mix_f32 v97, v84, v56, 0 op_sel:[0,0,0] op_sel_hi:[0,1,0]
	v_fma_mix_f32 v73, v85, v66, v73 op_sel:[0,1,0] op_sel_hi:[0,1,0]
	v_fma_mix_f32 v56, v85, v56, v97 op_sel:[0,1,0] op_sel_hi:[0,1,0]
	v_fma_mix_f32 v73, v86, v67, v73 op_sel:[0,0,0] op_sel_hi:[0,1,0]
	v_fma_mix_f32 v56, v86, v57, v56 op_sel:[0,0,0] op_sel_hi:[0,1,0]
	v_fma_mix_f32 v73, v87, v67, v73 op_sel:[0,1,0] op_sel_hi:[0,1,0]
	v_fma_mix_f32 v56, v87, v57, v56 op_sel:[0,1,0] op_sel_hi:[0,1,0]
	v_fma_mix_f32 v75, v93, v70, 0 op_sel:[0,0,0] op_sel_hi:[1,1,0]
	v_fma_mix_f32 v76, v93, v70, 0 op_sel:[0,1,0] op_sel_hi:[1,1,0]
	v_add_f32_dpp v73, v73, v73 quad_perm:[1,0,3,2] row_mask:0xf bank_mask:0xf bound_ctrl:1
	v_fma_mix_f32 v77, v93, v71, 0 op_sel:[0,0,0] op_sel_hi:[1,1,0]
	v_fma_mix_f32 v78, v93, v71, 0 op_sel:[0,1,0] op_sel_hi:[1,1,0]
	v_add_f32_dpp v73, v73, v73 quad_perm:[2,3,0,1] row_mask:0xf bank_mask:0xf bound_ctrl:1
	v_fma_mix_f32 v84, v84, v64, v75 op_sel:[0,0,0] op_sel_hi:[0,1,0]
	v_fma_mix_f32 v85, v85, v64, v76 op_sel:[0,1,0] op_sel_hi:[0,1,0]
	v_add_f32_dpp v73, v73, v73 row_half_mirror row_mask:0xf bank_mask:0xf bound_ctrl:1
	v_fma_mix_f32 v86, v86, v65, v77 op_sel:[0,0,0] op_sel_hi:[0,1,0]
	v_fma_mix_f32 v87, v87, v65, v78 op_sel:[0,1,0] op_sel_hi:[0,1,0]
	v_add_f32_dpp v73, v73, v73 row_mirror row_mask:0xf bank_mask:0xf bound_ctrl:1
	v_fma_mix_f32 v84, -v73, v68, v84 op_sel:[0,0,0] op_sel_hi:[0,1,0]
	v_fma_mix_f32 v85, -v73, v68, v85 op_sel:[0,1,0] op_sel_hi:[0,1,0]
	v_fma_mix_f32 v86, -v73, v69, v86 op_sel:[0,0,0] op_sel_hi:[0,1,0]
	v_fma_mix_f32 v87, -v73, v69, v87 op_sel:[0,1,0] op_sel_hi:[0,1,0]
	v_fma_mix_f32 v64, v84, v54, 0 op_sel:[0,0,0] op_sel_hi:[0,1,0]
	v_fma_mix_f32 v57, v84, v58, 0 op_sel:[0,0,0] op_sel_hi:[0,1,0]
	v_fma_mix_f32 v64, v85, v54, v64 op_sel:[0,1,0] op_sel_hi:[0,1,0]
	v_fma_mix_f32 v57, v85, v58, v57 op_sel:[0,1,0] op_sel_hi:[0,1,0]
	v_fma_mix_f32 v64, v86, v55, v64 op_sel:[0,0,0] op_sel_hi:[0,1,0]
	v_fma_mix_f32 v57, v86, v59, v57 op_sel:[0,0,0] op_sel_hi:[0,1,0]
	v_fma_mix_f32 v64, v87, v55, v64 op_sel:[0,1,0] op_sel_hi:[0,1,0]
	v_fma_mix_f32 v57, v87, v59, v57 op_sel:[0,1,0] op_sel_hi:[0,1,0]
	v_fma_mix_f32 v66, v94, v62, 0 op_sel:[0,0,0] op_sel_hi:[1,1,0]
	v_fma_mix_f32 v67, v94, v62, 0 op_sel:[0,1,0] op_sel_hi:[1,1,0]
	v_add_f32_dpp v64, v64, v64 quad_perm:[1,0,3,2] row_mask:0xf bank_mask:0xf bound_ctrl:1
	v_fma_mix_f32 v68, v94, v63, 0 op_sel:[0,0,0] op_sel_hi:[1,1,0]
	v_fma_mix_f32 v69, v94, v63, 0 op_sel:[0,1,0] op_sel_hi:[1,1,0]
	v_add_f32_dpp v64, v64, v64 quad_perm:[2,3,0,1] row_mask:0xf bank_mask:0xf bound_ctrl:1
	v_fma_mix_f32 v84, v84, v52, v66 op_sel:[0,0,0] op_sel_hi:[0,1,0]
	v_fma_mix_f32 v85, v85, v52, v67 op_sel:[0,1,0] op_sel_hi:[0,1,0]
	v_add_f32_dpp v64, v64, v64 row_half_mirror row_mask:0xf bank_mask:0xf bound_ctrl:1
	v_fma_mix_f32 v86, v86, v53, v68 op_sel:[0,0,0] op_sel_hi:[0,1,0]
	v_fma_mix_f32 v87, v87, v53, v69 op_sel:[0,1,0] op_sel_hi:[0,1,0]
	v_add_f32_dpp v64, v64, v64 row_mirror row_mask:0xf bank_mask:0xf bound_ctrl:1
	v_fma_mix_f32 v84, -v64, v60, v84 op_sel:[0,0,0] op_sel_hi:[0,1,0]
	v_fma_mix_f32 v85, -v64, v60, v85 op_sel:[0,1,0] op_sel_hi:[0,1,0]
	v_fma_mix_f32 v86, -v64, v61, v86 op_sel:[0,0,0] op_sel_hi:[0,1,0]
	v_fma_mix_f32 v87, -v64, v61, v87 op_sel:[0,1,0] op_sel_hi:[0,1,0]
	v_fma_mix_f32 v53, v84, v46, 0 op_sel:[0,0,0] op_sel_hi:[0,1,0]
	v_fma_mix_f32 v59, v84, v40, 0 op_sel:[0,0,0] op_sel_hi:[0,1,0]
	v_fma_mix_f32 v53, v85, v46, v53 op_sel:[0,1,0] op_sel_hi:[0,1,0]
	v_fma_mix_f32 v40, v85, v40, v59 op_sel:[0,1,0] op_sel_hi:[0,1,0]
	v_fma_mix_f32 v53, v86, v47, v53 op_sel:[0,0,0] op_sel_hi:[0,1,0]
	v_fma_mix_f32 v40, v86, v41, v40 op_sel:[0,0,0] op_sel_hi:[0,1,0]
	v_fma_mix_f32 v53, v87, v47, v53 op_sel:[0,1,0] op_sel_hi:[0,1,0]
	v_fma_mix_f32 v40, v87, v41, v40 op_sel:[0,1,0] op_sel_hi:[0,1,0]
	v_fma_mix_f32 v55, v95, v50, 0 op_sel:[0,0,0] op_sel_hi:[1,1,0]
	v_fma_mix_f32 v58, v95, v50, 0 op_sel:[0,1,0] op_sel_hi:[1,1,0]
	v_add_f32_dpp v53, v53, v53 quad_perm:[1,0,3,2] row_mask:0xf bank_mask:0xf bound_ctrl:1
	v_fma_mix_f32 v59, v95, v51, 0 op_sel:[0,0,0] op_sel_hi:[1,1,0]
	v_fma_mix_f32 v60, v95, v51, 0 op_sel:[0,1,0] op_sel_hi:[1,1,0]
	v_add_f32_dpp v53, v53, v53 quad_perm:[2,3,0,1] row_mask:0xf bank_mask:0xf bound_ctrl:1
	v_fma_mix_f32 v84, v84, v44, v55 op_sel:[0,0,0] op_sel_hi:[0,1,0]
	v_fma_mix_f32 v85, v85, v44, v58 op_sel:[0,1,0] op_sel_hi:[0,1,0]
	v_add_f32_dpp v53, v53, v53 row_half_mirror row_mask:0xf bank_mask:0xf bound_ctrl:1
	v_fma_mix_f32 v86, v86, v45, v59 op_sel:[0,0,0] op_sel_hi:[0,1,0]
	v_fma_mix_f32 v87, v87, v45, v60 op_sel:[0,1,0] op_sel_hi:[0,1,0]
	v_add_f32_dpp v53, v53, v53 row_mirror row_mask:0xf bank_mask:0xf bound_ctrl:1
	v_fma_mix_f32 v84, -v53, v48, v84 op_sel:[0,0,0] op_sel_hi:[0,1,0]
	v_fma_mix_f32 v85, -v53, v48, v85 op_sel:[0,1,0] op_sel_hi:[0,1,0]
	v_fma_mix_f32 v86, -v53, v49, v86 op_sel:[0,0,0] op_sel_hi:[0,1,0]
	v_fma_mix_f32 v87, -v53, v49, v87 op_sel:[0,1,0] op_sel_hi:[0,1,0]
	v_fma_mix_f32 v41, v84, v42, 0 op_sel:[0,0,0] op_sel_hi:[0,1,0]
	v_add_u32_e32 v173, 4, v193
	v_fma_mix_f32 v41, v85, v42, v41 op_sel:[0,1,0] op_sel_hi:[0,1,0]
	ds_write_b32 v172, v173 offset:49216
	v_fma_mix_f32 v41, v86, v43, v41 op_sel:[0,0,0] op_sel_hi:[0,1,0]
	v_cndmask_b32_e64 v187, v57, v56, s[38:39]
	v_fma_mix_f32 v41, v87, v43, v41 op_sel:[0,1,0] op_sel_hi:[0,1,0]
	v_cndmask_b32_e64 v188, v56, v57, s[38:39]
	v_cndmask_b32_e64 v189, v41, v40, s[38:39]
	v_cndmask_b32_e64 v190, v40, v41, s[38:39]
	s_waitcnt lgkmcnt(1)
	v_fma_mix_f32 v98, v84, v6, 0 op_sel:[0,0,0] op_sel_hi:[0,1,0]
	v_fma_mix_f32 v98, v85, v6, v98 op_sel:[0,1,0] op_sel_hi:[0,1,0]
	v_add_f32_dpp v188, v188, v187 quad_perm:[1,0,3,2] row_mask:0xf bank_mask:0xf bound_ctrl:1
	v_add_f32_dpp v189, v190, v189 quad_perm:[1,0,3,2] row_mask:0xf bank_mask:0xf bound_ctrl:1
	v_fma_mix_f32 v98, v86, v7, v98 op_sel:[0,0,0] op_sel_hi:[0,1,0]
	v_fma_mix_f32 v98, v87, v7, v98 op_sel:[0,1,0] op_sel_hi:[0,1,0]
	v_cndmask_b32_e64 v191, v189, v188, s[40:41]
	v_cndmask_b32_e64 v192, v188, v189, s[40:41]
	v_fma_mix_f32 v100, v88, v14, 0 op_sel:[0,0,0] op_sel_hi:[1,1,0]
	v_fma_mix_f32 v101, v88, v14, 0 op_sel:[0,1,0] op_sel_hi:[1,1,0]
	v_add_f32_dpp v192, v192, v191 quad_perm:[2,3,0,1] row_mask:0xf bank_mask:0xf bound_ctrl:1
	v_add_f32_dpp v98, v98, v98 quad_perm:[1,0,3,2] row_mask:0xf bank_mask:0xf bound_ctrl:1
	v_fma_mix_f32 v102, v88, v15, 0 op_sel:[0,0,0] op_sel_hi:[1,1,0]
	v_add_f32_dpp v192, v192, v192 row_ror:4 row_mask:0xf bank_mask:0xf bound_ctrl:1
	v_fma_mix_f32 v103, v88, v15, 0 op_sel:[0,1,0] op_sel_hi:[1,1,0]
	v_add_f32_dpp v98, v98, v98 quad_perm:[2,3,0,1] row_mask:0xf bank_mask:0xf bound_ctrl:1
	v_add_f32_dpp v192, v192, v192 row_ror:8 row_mask:0xf bank_mask:0xf bound_ctrl:1
	v_cvt_f16_f32_e32 v192, v192
	global_store_short v83, v192, s[36:37]
	s_add_u32 s36, s36, s44
	s_addc_u32 s37, s37, s45
	global_load_ushort v208, v83, s[22:23]
	s_add_u32 s22, s22, s44
	s_addc_u32 s23, s23, s45
	ds_read_b128 v[56:59], v194 offset:17408
	ds_read_b128 v[72:75], v194 offset:15360
	ds_read_b128 v[64:67], v194 offset:15616
	ds_read_b128 v[76:79], v194 offset:16384
	ds_read_b128 v[68:71], v194 offset:16640
	ds_read_b128 v[40:43], v194 offset:17664
	ds_read_b128 v[52:55], v194 offset:15872
	ds_read_b128 v[44:47], v194 offset:16128
	ds_read_b128 v[60:63], v194 offset:16896
	ds_read_b128 v[48:51], v194 offset:17152
	s_waitcnt vmcnt(12)
	v_mov_b32_dpp v92, v202 quad_perm:[0,0,0,0] row_mask:0xf bank_mask:0xf
	v_mov_b32_dpp v93, v202 quad_perm:[1,1,1,1] row_mask:0xf bank_mask:0xf
	v_mov_b32_dpp v94, v202 quad_perm:[2,2,2,2] row_mask:0xf bank_mask:0xf
	v_mov_b32_dpp v95, v202 quad_perm:[3,3,3,3] row_mask:0xf bank_mask:0xf
	v_fma_mix_f32 v84, v84, v4, v100 op_sel:[0,0,0] op_sel_hi:[0,1,0]
	v_fma_mix_f32 v85, v85, v4, v101 op_sel:[0,1,0] op_sel_hi:[0,1,0]
	v_add_f32_dpp v98, v98, v98 row_half_mirror row_mask:0xf bank_mask:0xf bound_ctrl:1
	v_fma_mix_f32 v86, v86, v5, v102 op_sel:[0,0,0] op_sel_hi:[0,1,0]
	v_fma_mix_f32 v87, v87, v5, v103 op_sel:[0,1,0] op_sel_hi:[0,1,0]
	v_add_f32_dpp v98, v98, v98 row_mirror row_mask:0xf bank_mask:0xf bound_ctrl:1
	v_fma_mix_f32 v84, -v98, v12, v84 op_sel:[0,0,0] op_sel_hi:[0,1,0]
	v_fma_mix_f32 v85, -v98, v12, v85 op_sel:[0,1,0] op_sel_hi:[0,1,0]
	v_fma_mix_f32 v86, -v98, v13, v86 op_sel:[0,0,0] op_sel_hi:[0,1,0]
	v_fma_mix_f32 v87, -v98, v13, v87 op_sel:[0,1,0] op_sel_hi:[0,1,0]
	v_fma_mix_f32 v99, v84, v10, 0 op_sel:[0,0,0] op_sel_hi:[0,1,0]
	v_fma_mix_f32 v96, v84, v0, 0 op_sel:[0,0,0] op_sel_hi:[0,1,0]
	v_fma_mix_f32 v99, v85, v10, v99 op_sel:[0,1,0] op_sel_hi:[0,1,0]
	v_fma_mix_f32 v96, v85, v0, v96 op_sel:[0,1,0] op_sel_hi:[0,1,0]
	v_fma_mix_f32 v99, v86, v11, v99 op_sel:[0,0,0] op_sel_hi:[0,1,0]
	v_fma_mix_f32 v96, v86, v1, v96 op_sel:[0,0,0] op_sel_hi:[0,1,0]
	v_fma_mix_f32 v99, v87, v11, v99 op_sel:[0,1,0] op_sel_hi:[0,1,0]
	v_fma_mix_f32 v96, v87, v1, v96 op_sel:[0,1,0] op_sel_hi:[0,1,0]
	v_fma_mix_f32 v101, v89, v18, 0 op_sel:[0,0,0] op_sel_hi:[1,1,0]
	v_fma_mix_f32 v102, v89, v18, 0 op_sel:[0,1,0] op_sel_hi:[1,1,0]
	v_add_f32_dpp v99, v99, v99 quad_perm:[1,0,3,2] row_mask:0xf bank_mask:0xf bound_ctrl:1
	v_fma_mix_f32 v103, v89, v19, 0 op_sel:[0,0,0] op_sel_hi:[1,1,0]
	v_fma_mix_f32 v104, v89, v19, 0 op_sel:[0,1,0] op_sel_hi:[1,1,0]
	v_add_f32_dpp v99, v99, v99 quad_perm:[2,3,0,1] row_mask:0xf bank_mask:0xf bound_ctrl:1
	v_fma_mix_f32 v84, v84, v8, v101 op_sel:[0,0,0] op_sel_hi:[0,1,0]
	v_fma_mix_f32 v85, v85, v8, v102 op_sel:[0,1,0] op_sel_hi:[0,1,0]
	v_add_f32_dpp v99, v99, v99 row_half_mirror row_mask:0xf bank_mask:0xf bound_ctrl:1
	v_fma_mix_f32 v86, v86, v9, v103 op_sel:[0,0,0] op_sel_hi:[0,1,0]
	v_fma_mix_f32 v87, v87, v9, v104 op_sel:[0,1,0] op_sel_hi:[0,1,0]
	v_add_f32_dpp v99, v99, v99 row_mirror row_mask:0xf bank_mask:0xf bound_ctrl:1
	v_fma_mix_f32 v84, -v99, v16, v84 op_sel:[0,0,0] op_sel_hi:[0,1,0]
	v_fma_mix_f32 v85, -v99, v16, v85 op_sel:[0,1,0] op_sel_hi:[0,1,0]
	v_fma_mix_f32 v86, -v99, v17, v86 op_sel:[0,0,0] op_sel_hi:[0,1,0]
	v_fma_mix_f32 v87, -v99, v17, v87 op_sel:[0,1,0] op_sel_hi:[0,1,0]
	v_fma_mix_f32 v100, v84, v26, 0 op_sel:[0,0,0] op_sel_hi:[0,1,0]
	v_fma_mix_f32 v97, v84, v2, 0 op_sel:[0,0,0] op_sel_hi:[0,1,0]
	v_fma_mix_f32 v100, v85, v26, v100 op_sel:[0,1,0] op_sel_hi:[0,1,0]
	v_fma_mix_f32 v97, v85, v2, v97 op_sel:[0,1,0] op_sel_hi:[0,1,0]
	v_fma_mix_f32 v100, v86, v27, v100 op_sel:[0,0,0] op_sel_hi:[0,1,0]
	v_fma_mix_f32 v97, v86, v3, v97 op_sel:[0,0,0] op_sel_hi:[0,1,0]
	v_fma_mix_f32 v100, v87, v27, v100 op_sel:[0,1,0] op_sel_hi:[0,1,0]
	v_fma_mix_f32 v97, v87, v3, v97 op_sel:[0,1,0] op_sel_hi:[0,1,0]
	v_fma_mix_f32 v102, v90, v34, 0 op_sel:[0,0,0] op_sel_hi:[1,1,0]
	v_fma_mix_f32 v103, v90, v34, 0 op_sel:[0,1,0] op_sel_hi:[1,1,0]
	v_add_f32_dpp v100, v100, v100 quad_perm:[1,0,3,2] row_mask:0xf bank_mask:0xf bound_ctrl:1
	v_fma_mix_f32 v104, v90, v35, 0 op_sel:[0,0,0] op_sel_hi:[1,1,0]
	v_fma_mix_f32 v105, v90, v35, 0 op_sel:[0,1,0] op_sel_hi:[1,1,0]
	v_add_f32_dpp v100, v100, v100 quad_perm:[2,3,0,1] row_mask:0xf bank_mask:0xf bound_ctrl:1
	v_fma_mix_f32 v84, v84, v24, v102 op_sel:[0,0,0] op_sel_hi:[0,1,0]
	v_fma_mix_f32 v85, v85, v24, v103 op_sel:[0,1,0] op_sel_hi:[0,1,0]
	v_add_f32_dpp v100, v100, v100 row_half_mirror row_mask:0xf bank_mask:0xf bound_ctrl:1
	v_fma_mix_f32 v86, v86, v25, v104 op_sel:[0,0,0] op_sel_hi:[0,1,0]
	v_fma_mix_f32 v87, v87, v25, v105 op_sel:[0,1,0] op_sel_hi:[0,1,0]
	v_add_f32_dpp v100, v100, v100 row_mirror row_mask:0xf bank_mask:0xf bound_ctrl:1
	v_fma_mix_f32 v84, -v100, v32, v84 op_sel:[0,0,0] op_sel_hi:[0,1,0]
	v_fma_mix_f32 v85, -v100, v32, v85 op_sel:[0,1,0] op_sel_hi:[0,1,0]
	v_fma_mix_f32 v86, -v100, v33, v86 op_sel:[0,0,0] op_sel_hi:[0,1,0]
	v_fma_mix_f32 v87, -v100, v33, v87 op_sel:[0,1,0] op_sel_hi:[0,1,0]
	v_fma_mix_f32 v101, v84, v30, 0 op_sel:[0,0,0] op_sel_hi:[0,1,0]
	v_fma_mix_f32 v98, v84, v20, 0 op_sel:[0,0,0] op_sel_hi:[0,1,0]
	v_fma_mix_f32 v101, v85, v30, v101 op_sel:[0,1,0] op_sel_hi:[0,1,0]
	v_fma_mix_f32 v98, v85, v20, v98 op_sel:[0,1,0] op_sel_hi:[0,1,0]
	v_fma_mix_f32 v101, v86, v31, v101 op_sel:[0,0,0] op_sel_hi:[0,1,0]
	v_fma_mix_f32 v98, v86, v21, v98 op_sel:[0,0,0] op_sel_hi:[0,1,0]
	v_fma_mix_f32 v101, v87, v31, v101 op_sel:[0,1,0] op_sel_hi:[0,1,0]
	v_fma_mix_f32 v98, v87, v21, v98 op_sel:[0,1,0] op_sel_hi:[0,1,0]
	v_fma_mix_f32 v103, v91, v38, 0 op_sel:[0,0,0] op_sel_hi:[1,1,0]
	v_fma_mix_f32 v104, v91, v38, 0 op_sel:[0,1,0] op_sel_hi:[1,1,0]
	v_add_f32_dpp v101, v101, v101 quad_perm:[1,0,3,2] row_mask:0xf bank_mask:0xf bound_ctrl:1
	v_fma_mix_f32 v105, v91, v39, 0 op_sel:[0,0,0] op_sel_hi:[1,1,0]
	v_fma_mix_f32 v119, v91, v39, 0 op_sel:[0,1,0] op_sel_hi:[1,1,0]
	v_add_f32_dpp v101, v101, v101 quad_perm:[2,3,0,1] row_mask:0xf bank_mask:0xf bound_ctrl:1
	v_fma_mix_f32 v84, v84, v28, v103 op_sel:[0,0,0] op_sel_hi:[0,1,0]
	v_fma_mix_f32 v85, v85, v28, v104 op_sel:[0,1,0] op_sel_hi:[0,1,0]
	v_add_f32_dpp v101, v101, v101 row_half_mirror row_mask:0xf bank_mask:0xf bound_ctrl:1
	v_fma_mix_f32 v86, v86, v29, v105 op_sel:[0,0,0] op_sel_hi:[0,1,0]
	v_fma_mix_f32 v87, v87, v29, v119 op_sel:[0,1,0] op_sel_hi:[0,1,0]
	v_add_f32_dpp v101, v101, v101 row_mirror row_mask:0xf bank_mask:0xf bound_ctrl:1
	v_fma_mix_f32 v84, -v101, v36, v84 op_sel:[0,0,0] op_sel_hi:[0,1,0]
	v_fma_mix_f32 v85, -v101, v36, v85 op_sel:[0,1,0] op_sel_hi:[0,1,0]
	v_fma_mix_f32 v86, -v101, v37, v86 op_sel:[0,0,0] op_sel_hi:[0,1,0]
	v_fma_mix_f32 v87, -v101, v37, v87 op_sel:[0,1,0] op_sel_hi:[0,1,0]
	v_fma_mix_f32 v99, v84, v22, 0 op_sel:[0,0,0] op_sel_hi:[0,1,0]
	v_cndmask_b32_e64 v187, v97, v96, s[38:39]
	v_fma_mix_f32 v99, v85, v22, v99 op_sel:[0,1,0] op_sel_hi:[0,1,0]
	v_cndmask_b32_e64 v188, v96, v97, s[38:39]
	v_fma_mix_f32 v99, v86, v23, v99 op_sel:[0,0,0] op_sel_hi:[0,1,0]
	v_fma_mix_f32 v99, v87, v23, v99 op_sel:[0,1,0] op_sel_hi:[0,1,0]
	v_cndmask_b32_e64 v189, v99, v98, s[38:39]
	v_cndmask_b32_e64 v190, v98, v99, s[38:39]
	s_waitcnt lgkmcnt(0)
	v_fma_mix_f32 v98, v84, v74, 0 op_sel:[0,0,0] op_sel_hi:[0,1,0]
	v_fma_mix_f32 v98, v85, v74, v98 op_sel:[0,1,0] op_sel_hi:[0,1,0]
	v_add_f32_dpp v188, v188, v187 quad_perm:[1,0,3,2] row_mask:0xf bank_mask:0xf bound_ctrl:1
	v_add_f32_dpp v189, v190, v189 quad_perm:[1,0,3,2] row_mask:0xf bank_mask:0xf bound_ctrl:1
	v_fma_mix_f32 v98, v86, v75, v98 op_sel:[0,0,0] op_sel_hi:[0,1,0]
	v_fma_mix_f32 v98, v87, v75, v98 op_sel:[0,1,0] op_sel_hi:[0,1,0]
	v_cndmask_b32_e64 v191, v189, v188, s[40:41]
	v_cndmask_b32_e64 v192, v188, v189, s[40:41]
	v_fma_mix_f32 v100, v92, v78, 0 op_sel:[0,0,0] op_sel_hi:[1,1,0]
	v_fma_mix_f32 v101, v92, v78, 0 op_sel:[0,1,0] op_sel_hi:[1,1,0]
	v_add_f32_dpp v192, v192, v191 quad_perm:[2,3,0,1] row_mask:0xf bank_mask:0xf bound_ctrl:1
	v_add_f32_dpp v98, v98, v98 quad_perm:[1,0,3,2] row_mask:0xf bank_mask:0xf bound_ctrl:1
	v_fma_mix_f32 v102, v92, v79, 0 op_sel:[0,0,0] op_sel_hi:[1,1,0]
	v_add_f32_dpp v192, v192, v192 row_ror:4 row_mask:0xf bank_mask:0xf bound_ctrl:1
	v_fma_mix_f32 v103, v92, v79, 0 op_sel:[0,1,0] op_sel_hi:[1,1,0]
	v_add_f32_dpp v98, v98, v98 quad_perm:[2,3,0,1] row_mask:0xf bank_mask:0xf bound_ctrl:1
	v_add_f32_dpp v192, v192, v192 row_ror:8 row_mask:0xf bank_mask:0xf bound_ctrl:1
	v_cvt_f16_f32_e32 v192, v192
	global_store_short v83, v192, s[36:37]
	s_add_u32 s36, s36, s44
	s_addc_u32 s37, s37, s45
	global_load_ushort v209, v83, s[22:23]
	s_add_u32 s22, s22, s44
	s_addc_u32 s23, s23, s45
	s_cmp_gt_i32 s35, 7
	s_cbranch_scc0 .Lc_poll_A2
.Lc_ret_A2:
	ds_read_b128 v[0:3], v194 offset:20480
	ds_read_b128 v[4:7], v194 offset:18432
	ds_read_b128 v[8:11], v194 offset:18688
	ds_read_b128 v[12:15], v194 offset:19456
	ds_read_b128 v[16:19], v194 offset:19712
	ds_read_b128 v[20:23], v194 offset:20736
	ds_read_b128 v[24:27], v194 offset:18944
	ds_read_b128 v[28:31], v194 offset:19200
	ds_read_b128 v[32:35], v194 offset:19968
	ds_read_b128 v[36:39], v194 offset:20224
	s_waitcnt vmcnt(12)
	v_mov_b32_dpp v88, v203 quad_perm:[0,0,0,0] row_mask:0xf bank_mask:0xf
	v_mov_b32_dpp v89, v203 quad_perm:[1,1,1,1] row_mask:0xf bank_mask:0xf
	v_mov_b32_dpp v90, v203 quad_perm:[2,2,2,2] row_mask:0xf bank_mask:0xf
	v_mov_b32_dpp v91, v203 quad_perm:[3,3,3,3] row_mask:0xf bank_mask:0xf
	v_fma_mix_f32 v84, v84, v72, v100 op_sel:[0,0,0] op_sel_hi:[0,1,0]
	v_fma_mix_f32 v85, v85, v72, v101 op_sel:[0,1,0] op_sel_hi:[0,1,0]
	v_add_f32_dpp v98, v98, v98 row_half_mirror row_mask:0xf bank_mask:0xf bound_ctrl:1
	v_fma_mix_f32 v86, v86, v73, v102 op_sel:[0,0,0] op_sel_hi:[0,1,0]
	v_fma_mix_f32 v87, v87, v73, v103 op_sel:[0,1,0] op_sel_hi:[0,1,0]
	v_add_f32_dpp v98, v98, v98 row_mirror row_mask:0xf bank_mask:0xf bound_ctrl:1
	v_fma_mix_f32 v84, -v98, v76, v84 op_sel:[0,0,0] op_sel_hi:[0,1,0]
	v_fma_mix_f32 v85, -v98, v76, v85 op_sel:[0,1,0] op_sel_hi:[0,1,0]
	v_fma_mix_f32 v86, -v98, v77, v86 op_sel:[0,0,0] op_sel_hi:[0,1,0]
	v_fma_mix_f32 v87, -v98, v77, v87 op_sel:[0,1,0] op_sel_hi:[0,1,0]
	v_fma_mix_f32 v73, v84, v66, 0 op_sel:[0,0,0] op_sel_hi:[0,1,0]
	v_fma_mix_f32 v97, v84, v56, 0 op_sel:[0,0,0] op_sel_hi:[0,1,0]
	v_fma_mix_f32 v73, v85, v66, v73 op_sel:[0,1,0] op_sel_hi:[0,1,0]
	v_fma_mix_f32 v56, v85, v56, v97 op_sel:[0,1,0] op_sel_hi:[0,1,0]
	v_fma_mix_f32 v73, v86, v67, v73 op_sel:[0,0,0] op_sel_hi:[0,1,0]
	v_fma_mix_f32 v56, v86, v57, v56 op_sel:[0,0,0] op_sel_hi:[0,1,0]
	v_fma_mix_f32 v73, v87, v67, v73 op_sel:[0,1,0] op_sel_hi:[0,1,0]
	v_fma_mix_f32 v56, v87, v57, v56 op_sel:[0,1,0] op_sel_hi:[0,1,0]
	v_fma_mix_f32 v75, v93, v70, 0 op_sel:[0,0,0] op_sel_hi:[1,1,0]
	v_fma_mix_f32 v76, v93, v70, 0 op_sel:[0,1,0] op_sel_hi:[1,1,0]
	v_add_f32_dpp v73, v73, v73 quad_perm:[1,0,3,2] row_mask:0xf bank_mask:0xf bound_ctrl:1
	v_fma_mix_f32 v77, v93, v71, 0 op_sel:[0,0,0] op_sel_hi:[1,1,0]
	v_fma_mix_f32 v78, v93, v71, 0 op_sel:[0,1,0] op_sel_hi:[1,1,0]
	v_add_f32_dpp v73, v73, v73 quad_perm:[2,3,0,1] row_mask:0xf bank_mask:0xf bound_ctrl:1
	v_fma_mix_f32 v84, v84, v64, v75 op_sel:[0,0,0] op_sel_hi:[0,1,0]
	v_fma_mix_f32 v85, v85, v64, v76 op_sel:[0,1,0] op_sel_hi:[0,1,0]
	v_add_f32_dpp v73, v73, v73 row_half_mirror row_mask:0xf bank_mask:0xf bound_ctrl:1
	v_fma_mix_f32 v86, v86, v65, v77 op_sel:[0,0,0] op_sel_hi:[0,1,0]
	v_fma_mix_f32 v87, v87, v65, v78 op_sel:[0,1,0] op_sel_hi:[0,1,0]
	v_add_f32_dpp v73, v73, v73 row_mirror row_mask:0xf bank_mask:0xf bound_ctrl:1
	v_fma_mix_f32 v84, -v73, v68, v84 op_sel:[0,0,0] op_sel_hi:[0,1,0]
	v_fma_mix_f32 v85, -v73, v68, v85 op_sel:[0,1,0] op_sel_hi:[0,1,0]
	v_fma_mix_f32 v86, -v73, v69, v86 op_sel:[0,0,0] op_sel_hi:[0,1,0]
	v_fma_mix_f32 v87, -v73, v69, v87 op_sel:[0,1,0] op_sel_hi:[0,1,0]
	v_fma_mix_f32 v64, v84, v54, 0 op_sel:[0,0,0] op_sel_hi:[0,1,0]
	v_fma_mix_f32 v57, v84, v58, 0 op_sel:[0,0,0] op_sel_hi:[0,1,0]
	v_fma_mix_f32 v64, v85, v54, v64 op_sel:[0,1,0] op_sel_hi:[0,1,0]
	v_fma_mix_f32 v57, v85, v58, v57 op_sel:[0,1,0] op_sel_hi:[0,1,0]
	v_fma_mix_f32 v64, v86, v55, v64 op_sel:[0,0,0] op_sel_hi:[0,1,0]
	v_fma_mix_f32 v57, v86, v59, v57 op_sel:[0,0,0] op_sel_hi:[0,1,0]
	v_fma_mix_f32 v64, v87, v55, v64 op_sel:[0,1,0] op_sel_hi:[0,1,0]
	v_fma_mix_f32 v57, v87, v59, v57 op_sel:[0,1,0] op_sel_hi:[0,1,0]
	v_fma_mix_f32 v66, v94, v62, 0 op_sel:[0,0,0] op_sel_hi:[1,1,0]
	v_fma_mix_f32 v67, v94, v62, 0 op_sel:[0,1,0] op_sel_hi:[1,1,0]
	v_add_f32_dpp v64, v64, v64 quad_perm:[1,0,3,2] row_mask:0xf bank_mask:0xf bound_ctrl:1
	v_fma_mix_f32 v68, v94, v63, 0 op_sel:[0,0,0] op_sel_hi:[1,1,0]
	v_fma_mix_f32 v69, v94, v63, 0 op_sel:[0,1,0] op_sel_hi:[1,1,0]
	v_add_f32_dpp v64, v64, v64 quad_perm:[2,3,0,1] row_mask:0xf bank_mask:0xf bound_ctrl:1
	v_fma_mix_f32 v84, v84, v52, v66 op_sel:[0,0,0] op_sel_hi:[0,1,0]
	v_fma_mix_f32 v85, v85, v52, v67 op_sel:[0,1,0] op_sel_hi:[0,1,0]
	v_add_f32_dpp v64, v64, v64 row_half_mirror row_mask:0xf bank_mask:0xf bound_ctrl:1
	v_fma_mix_f32 v86, v86, v53, v68 op_sel:[0,0,0] op_sel_hi:[0,1,0]
	v_fma_mix_f32 v87, v87, v53, v69 op_sel:[0,1,0] op_sel_hi:[0,1,0]
	v_add_f32_dpp v64, v64, v64 row_mirror row_mask:0xf bank_mask:0xf bound_ctrl:1
	v_fma_mix_f32 v84, -v64, v60, v84 op_sel:[0,0,0] op_sel_hi:[0,1,0]
	v_fma_mix_f32 v85, -v64, v60, v85 op_sel:[0,1,0] op_sel_hi:[0,1,0]
	v_fma_mix_f32 v86, -v64, v61, v86 op_sel:[0,0,0] op_sel_hi:[0,1,0]
	v_fma_mix_f32 v87, -v64, v61, v87 op_sel:[0,1,0] op_sel_hi:[0,1,0]
	v_fma_mix_f32 v53, v84, v46, 0 op_sel:[0,0,0] op_sel_hi:[0,1,0]
	v_fma_mix_f32 v59, v84, v40, 0 op_sel:[0,0,0] op_sel_hi:[0,1,0]
	v_fma_mix_f32 v53, v85, v46, v53 op_sel:[0,1,0] op_sel_hi:[0,1,0]
	v_fma_mix_f32 v40, v85, v40, v59 op_sel:[0,1,0] op_sel_hi:[0,1,0]
	v_fma_mix_f32 v53, v86, v47, v53 op_sel:[0,0,0] op_sel_hi:[0,1,0]
	v_fma_mix_f32 v40, v86, v41, v40 op_sel:[0,0,0] op_sel_hi:[0,1,0]
	v_fma_mix_f32 v53, v87, v47, v53 op_sel:[0,1,0] op_sel_hi:[0,1,0]
	v_fma_mix_f32 v40, v87, v41, v40 op_sel:[0,1,0] op_sel_hi:[0,1,0]
	v_fma_mix_f32 v55, v95, v50, 0 op_sel:[0,0,0] op_sel_hi:[1,1,0]
	v_fma_mix_f32 v58, v95, v50, 0 op_sel:[0,1,0] op_sel_hi:[1,1,0]
	v_add_f32_dpp v53, v53, v53 quad_perm:[1,0,3,2] row_mask:0xf bank_mask:0xf bound_ctrl:1
	v_fma_mix_f32 v59, v95, v51, 0 op_sel:[0,0,0] op_sel_hi:[1,1,0]
	v_fma_mix_f32 v60, v95, v51, 0 op_sel:[0,1,0] op_sel_hi:[1,1,0]
	v_add_f32_dpp v53, v53, v53 quad_perm:[2,3,0,1] row_mask:0xf bank_mask:0xf bound_ctrl:1
	v_fma_mix_f32 v84, v84, v44, v55 op_sel:[0,0,0] op_sel_hi:[0,1,0]
	v_fma_mix_f32 v85, v85, v44, v58 op_sel:[0,1,0] op_sel_hi:[0,1,0]
	v_add_f32_dpp v53, v53, v53 row_half_mirror row_mask:0xf bank_mask:0xf bound_ctrl:1
	v_fma_mix_f32 v86, v86, v45, v59 op_sel:[0,0,0] op_sel_hi:[0,1,0]
	v_fma_mix_f32 v87, v87, v45, v60 op_sel:[0,1,0] op_sel_hi:[0,1,0]
	v_add_f32_dpp v53, v53, v53 row_mirror row_mask:0xf bank_mask:0xf bound_ctrl:1
	v_fma_mix_f32 v84, -v53, v48, v84 op_sel:[0,0,0] op_sel_hi:[0,1,0]
	v_fma_mix_f32 v85, -v53, v48, v85 op_sel:[0,1,0] op_sel_hi:[0,1,0]
	v_fma_mix_f32 v86, -v53, v49, v86 op_sel:[0,0,0] op_sel_hi:[0,1,0]
	v_fma_mix_f32 v87, -v53, v49, v87 op_sel:[0,1,0] op_sel_hi:[0,1,0]
	v_fma_mix_f32 v41, v84, v42, 0 op_sel:[0,0,0] op_sel_hi:[0,1,0]
	v_cndmask_b32_e64 v187, v57, v56, s[38:39]
	v_fma_mix_f32 v41, v85, v42, v41 op_sel:[0,1,0] op_sel_hi:[0,1,0]
	v_cndmask_b32_e64 v188, v56, v57, s[38:39]
	v_fma_mix_f32 v41, v86, v43, v41 op_sel:[0,0,0] op_sel_hi:[0,1,0]
	v_fma_mix_f32 v41, v87, v43, v41 op_sel:[0,1,0] op_sel_hi:[0,1,0]
	v_cndmask_b32_e64 v189, v41, v40, s[38:39]
	v_cndmask_b32_e64 v190, v40, v41, s[38:39]
	s_waitcnt lgkmcnt(0)
	v_fma_mix_f32 v98, v84, v6, 0 op_sel:[0,0,0] op_sel_hi:[0,1,0]
	v_fma_mix_f32 v98, v85, v6, v98 op_sel:[0,1,0] op_sel_hi:[0,1,0]
	v_add_f32_dpp v188, v188, v187 quad_perm:[1,0,3,2] row_mask:0xf bank_mask:0xf bound_ctrl:1
	v_add_f32_dpp v189, v190, v189 quad_perm:[1,0,3,2] row_mask:0xf bank_mask:0xf bound_ctrl:1
	v_fma_mix_f32 v98, v86, v7, v98 op_sel:[0,0,0] op_sel_hi:[0,1,0]
	v_fma_mix_f32 v98, v87, v7, v98 op_sel:[0,1,0] op_sel_hi:[0,1,0]
	v_cndmask_b32_e64 v191, v189, v188, s[40:41]
	v_cndmask_b32_e64 v192, v188, v189, s[40:41]
	v_fma_mix_f32 v100, v88, v14, 0 op_sel:[0,0,0] op_sel_hi:[1,1,0]
	v_fma_mix_f32 v101, v88, v14, 0 op_sel:[0,1,0] op_sel_hi:[1,1,0]
	v_add_f32_dpp v192, v192, v191 quad_perm:[2,3,0,1] row_mask:0xf bank_mask:0xf bound_ctrl:1
	v_add_f32_dpp v98, v98, v98 quad_perm:[1,0,3,2] row_mask:0xf bank_mask:0xf bound_ctrl:1
	v_fma_mix_f32 v102, v88, v15, 0 op_sel:[0,0,0] op_sel_hi:[1,1,0]
	v_add_f32_dpp v192, v192, v192 row_ror:4 row_mask:0xf bank_mask:0xf bound_ctrl:1
	v_fma_mix_f32 v103, v88, v15, 0 op_sel:[0,1,0] op_sel_hi:[1,1,0]
	v_add_f32_dpp v98, v98, v98 quad_perm:[2,3,0,1] row_mask:0xf bank_mask:0xf bound_ctrl:1
	v_add_f32_dpp v192, v192, v192 row_ror:8 row_mask:0xf bank_mask:0xf bound_ctrl:1
	v_cvt_f16_f32_e32 v192, v192
	global_store_short v83, v192, s[36:37]
	s_add_u32 s36, s36, s44
	s_addc_u32 s37, s37, s45
	global_load_ushort v210, v83, s[22:23]
	s_add_u32 s22, s22, s44
	s_addc_u32 s23, s23, s45
	ds_read_b128 v[56:59], v194 offset:23552
	ds_read_b128 v[72:75], v194 offset:21504
	ds_read_b128 v[64:67], v194 offset:21760
	ds_read_b128 v[76:79], v194 offset:22528
	ds_read_b128 v[68:71], v194 offset:22784
	ds_read_b128 v[40:43], v194 offset:23808
	ds_read_b128 v[52:55], v194 offset:22016
	ds_read_b128 v[44:47], v194 offset:22272
	ds_read_b128 v[60:63], v194 offset:23040
	ds_read_b128 v[48:51], v194 offset:23296
	s_waitcnt vmcnt(12)
	v_mov_b32_dpp v92, v204 quad_perm:[0,0,0,0] row_mask:0xf bank_mask:0xf
	v_mov_b32_dpp v93, v204 quad_perm:[1,1,1,1] row_mask:0xf bank_mask:0xf
	v_mov_b32_dpp v94, v204 quad_perm:[2,2,2,2] row_mask:0xf bank_mask:0xf
	v_mov_b32_dpp v95, v204 quad_perm:[3,3,3,3] row_mask:0xf bank_mask:0xf
	v_fma_mix_f32 v84, v84, v4, v100 op_sel:[0,0,0] op_sel_hi:[0,1,0]
	v_fma_mix_f32 v85, v85, v4, v101 op_sel:[0,1,0] op_sel_hi:[0,1,0]
	v_add_f32_dpp v98, v98, v98 row_half_mirror row_mask:0xf bank_mask:0xf bound_ctrl:1
	v_fma_mix_f32 v86, v86, v5, v102 op_sel:[0,0,0] op_sel_hi:[0,1,0]
	v_fma_mix_f32 v87, v87, v5, v103 op_sel:[0,1,0] op_sel_hi:[0,1,0]
	v_add_f32_dpp v98, v98, v98 row_mirror row_mask:0xf bank_mask:0xf bound_ctrl:1
	v_fma_mix_f32 v84, -v98, v12, v84 op_sel:[0,0,0] op_sel_hi:[0,1,0]
	v_fma_mix_f32 v85, -v98, v12, v85 op_sel:[0,1,0] op_sel_hi:[0,1,0]
	v_fma_mix_f32 v86, -v98, v13, v86 op_sel:[0,0,0] op_sel_hi:[0,1,0]
	v_fma_mix_f32 v87, -v98, v13, v87 op_sel:[0,1,0] op_sel_hi:[0,1,0]
	v_fma_mix_f32 v99, v84, v10, 0 op_sel:[0,0,0] op_sel_hi:[0,1,0]
	v_fma_mix_f32 v96, v84, v0, 0 op_sel:[0,0,0] op_sel_hi:[0,1,0]
	v_fma_mix_f32 v99, v85, v10, v99 op_sel:[0,1,0] op_sel_hi:[0,1,0]
	v_fma_mix_f32 v96, v85, v0, v96 op_sel:[0,1,0] op_sel_hi:[0,1,0]
	v_fma_mix_f32 v99, v86, v11, v99 op_sel:[0,0,0] op_sel_hi:[0,1,0]
	v_fma_mix_f32 v96, v86, v1, v96 op_sel:[0,0,0] op_sel_hi:[0,1,0]
	v_fma_mix_f32 v99, v87, v11, v99 op_sel:[0,1,0] op_sel_hi:[0,1,0]
	v_fma_mix_f32 v96, v87, v1, v96 op_sel:[0,1,0] op_sel_hi:[0,1,0]
	v_fma_mix_f32 v101, v89, v18, 0 op_sel:[0,0,0] op_sel_hi:[1,1,0]
	v_fma_mix_f32 v102, v89, v18, 0 op_sel:[0,1,0] op_sel_hi:[1,1,0]
	v_add_f32_dpp v99, v99, v99 quad_perm:[1,0,3,2] row_mask:0xf bank_mask:0xf bound_ctrl:1
	v_fma_mix_f32 v103, v89, v19, 0 op_sel:[0,0,0] op_sel_hi:[1,1,0]
	v_fma_mix_f32 v104, v89, v19, 0 op_sel:[0,1,0] op_sel_hi:[1,1,0]
	v_add_f32_dpp v99, v99, v99 quad_perm:[2,3,0,1] row_mask:0xf bank_mask:0xf bound_ctrl:1
	v_fma_mix_f32 v84, v84, v8, v101 op_sel:[0,0,0] op_sel_hi:[0,1,0]
	v_fma_mix_f32 v85, v85, v8, v102 op_sel:[0,1,0] op_sel_hi:[0,1,0]
	v_add_f32_dpp v99, v99, v99 row_half_mirror row_mask:0xf bank_mask:0xf bound_ctrl:1
	v_fma_mix_f32 v86, v86, v9, v103 op_sel:[0,0,0] op_sel_hi:[0,1,0]
	v_fma_mix_f32 v87, v87, v9, v104 op_sel:[0,1,0] op_sel_hi:[0,1,0]
	v_add_f32_dpp v99, v99, v99 row_mirror row_mask:0xf bank_mask:0xf bound_ctrl:1
	v_fma_mix_f32 v84, -v99, v16, v84 op_sel:[0,0,0] op_sel_hi:[0,1,0]
	v_fma_mix_f32 v85, -v99, v16, v85 op_sel:[0,1,0] op_sel_hi:[0,1,0]
	v_fma_mix_f32 v86, -v99, v17, v86 op_sel:[0,0,0] op_sel_hi:[0,1,0]
	v_fma_mix_f32 v87, -v99, v17, v87 op_sel:[0,1,0] op_sel_hi:[0,1,0]
	v_fma_mix_f32 v100, v84, v26, 0 op_sel:[0,0,0] op_sel_hi:[0,1,0]
	v_fma_mix_f32 v97, v84, v2, 0 op_sel:[0,0,0] op_sel_hi:[0,1,0]
	v_fma_mix_f32 v100, v85, v26, v100 op_sel:[0,1,0] op_sel_hi:[0,1,0]
	v_fma_mix_f32 v97, v85, v2, v97 op_sel:[0,1,0] op_sel_hi:[0,1,0]
	v_fma_mix_f32 v100, v86, v27, v100 op_sel:[0,0,0] op_sel_hi:[0,1,0]
	v_fma_mix_f32 v97, v86, v3, v97 op_sel:[0,0,0] op_sel_hi:[0,1,0]
	v_fma_mix_f32 v100, v87, v27, v100 op_sel:[0,1,0] op_sel_hi:[0,1,0]
	v_fma_mix_f32 v97, v87, v3, v97 op_sel:[0,1,0] op_sel_hi:[0,1,0]
	v_fma_mix_f32 v102, v90, v34, 0 op_sel:[0,0,0] op_sel_hi:[1,1,0]
	v_fma_mix_f32 v103, v90, v34, 0 op_sel:[0,1,0] op_sel_hi:[1,1,0]
	v_add_f32_dpp v100, v100, v100 quad_perm:[1,0,3,2] row_mask:0xf bank_mask:0xf bound_ctrl:1
	v_fma_mix_f32 v104, v90, v35, 0 op_sel:[0,0,0] op_sel_hi:[1,1,0]
	v_fma_mix_f32 v105, v90, v35, 0 op_sel:[0,1,0] op_sel_hi:[1,1,0]
	v_add_f32_dpp v100, v100, v100 quad_perm:[2,3,0,1] row_mask:0xf bank_mask:0xf bound_ctrl:1
	v_fma_mix_f32 v84, v84, v24, v102 op_sel:[0,0,0] op_sel_hi:[0,1,0]
	v_fma_mix_f32 v85, v85, v24, v103 op_sel:[0,1,0] op_sel_hi:[0,1,0]
	v_add_f32_dpp v100, v100, v100 row_half_mirror row_mask:0xf bank_mask:0xf bound_ctrl:1
	v_fma_mix_f32 v86, v86, v25, v104 op_sel:[0,0,0] op_sel_hi:[0,1,0]
	v_fma_mix_f32 v87, v87, v25, v105 op_sel:[0,1,0] op_sel_hi:[0,1,0]
	v_add_f32_dpp v100, v100, v100 row_mirror row_mask:0xf bank_mask:0xf bound_ctrl:1
	v_fma_mix_f32 v84, -v100, v32, v84 op_sel:[0,0,0] op_sel_hi:[0,1,0]
	v_fma_mix_f32 v85, -v100, v32, v85 op_sel:[0,1,0] op_sel_hi:[0,1,0]
	v_fma_mix_f32 v86, -v100, v33, v86 op_sel:[0,0,0] op_sel_hi:[0,1,0]
	v_fma_mix_f32 v87, -v100, v33, v87 op_sel:[0,1,0] op_sel_hi:[0,1,0]
	v_fma_mix_f32 v101, v84, v30, 0 op_sel:[0,0,0] op_sel_hi:[0,1,0]
	v_fma_mix_f32 v98, v84, v20, 0 op_sel:[0,0,0] op_sel_hi:[0,1,0]
	v_fma_mix_f32 v101, v85, v30, v101 op_sel:[0,1,0] op_sel_hi:[0,1,0]
	v_fma_mix_f32 v98, v85, v20, v98 op_sel:[0,1,0] op_sel_hi:[0,1,0]
	v_fma_mix_f32 v101, v86, v31, v101 op_sel:[0,0,0] op_sel_hi:[0,1,0]
	v_fma_mix_f32 v98, v86, v21, v98 op_sel:[0,0,0] op_sel_hi:[0,1,0]
	v_fma_mix_f32 v101, v87, v31, v101 op_sel:[0,1,0] op_sel_hi:[0,1,0]
	v_fma_mix_f32 v98, v87, v21, v98 op_sel:[0,1,0] op_sel_hi:[0,1,0]
	v_fma_mix_f32 v103, v91, v38, 0 op_sel:[0,0,0] op_sel_hi:[1,1,0]
	v_fma_mix_f32 v104, v91, v38, 0 op_sel:[0,1,0] op_sel_hi:[1,1,0]
	v_add_f32_dpp v101, v101, v101 quad_perm:[1,0,3,2] row_mask:0xf bank_mask:0xf bound_ctrl:1
	v_fma_mix_f32 v105, v91, v39, 0 op_sel:[0,0,0] op_sel_hi:[1,1,0]
	v_fma_mix_f32 v119, v91, v39, 0 op_sel:[0,1,0] op_sel_hi:[1,1,0]
	v_add_f32_dpp v101, v101, v101 quad_perm:[2,3,0,1] row_mask:0xf bank_mask:0xf bound_ctrl:1
	v_fma_mix_f32 v84, v84, v28, v103 op_sel:[0,0,0] op_sel_hi:[0,1,0]
	v_fma_mix_f32 v85, v85, v28, v104 op_sel:[0,1,0] op_sel_hi:[0,1,0]
	v_add_f32_dpp v101, v101, v101 row_half_mirror row_mask:0xf bank_mask:0xf bound_ctrl:1
	v_fma_mix_f32 v86, v86, v29, v105 op_sel:[0,0,0] op_sel_hi:[0,1,0]
	v_fma_mix_f32 v87, v87, v29, v119 op_sel:[0,1,0] op_sel_hi:[0,1,0]
	v_add_f32_dpp v101, v101, v101 row_mirror row_mask:0xf bank_mask:0xf bound_ctrl:1
	v_fma_mix_f32 v84, -v101, v36, v84 op_sel:[0,0,0] op_sel_hi:[0,1,0]
	v_fma_mix_f32 v85, -v101, v36, v85 op_sel:[0,1,0] op_sel_hi:[0,1,0]
	v_fma_mix_f32 v86, -v101, v37, v86 op_sel:[0,0,0] op_sel_hi:[0,1,0]
	v_fma_mix_f32 v87, -v101, v37, v87 op_sel:[0,1,0] op_sel_hi:[0,1,0]
	v_fma_mix_f32 v99, v84, v22, 0 op_sel:[0,0,0] op_sel_hi:[0,1,0]
	v_cndmask_b32_e64 v187, v97, v96, s[38:39]
	v_fma_mix_f32 v99, v85, v22, v99 op_sel:[0,1,0] op_sel_hi:[0,1,0]
	v_cndmask_b32_e64 v188, v96, v97, s[38:39]
	v_fma_mix_f32 v99, v86, v23, v99 op_sel:[0,0,0] op_sel_hi:[0,1,0]
	v_fma_mix_f32 v99, v87, v23, v99 op_sel:[0,1,0] op_sel_hi:[0,1,0]
	v_cndmask_b32_e64 v189, v99, v98, s[38:39]
	v_cndmask_b32_e64 v190, v98, v99, s[38:39]
	s_waitcnt lgkmcnt(0)
	v_fma_mix_f32 v98, v84, v74, 0 op_sel:[0,0,0] op_sel_hi:[0,1,0]
	v_fma_mix_f32 v98, v85, v74, v98 op_sel:[0,1,0] op_sel_hi:[0,1,0]
	v_add_f32_dpp v188, v188, v187 quad_perm:[1,0,3,2] row_mask:0xf bank_mask:0xf bound_ctrl:1
	v_add_f32_dpp v189, v190, v189 quad_perm:[1,0,3,2] row_mask:0xf bank_mask:0xf bound_ctrl:1
	v_fma_mix_f32 v98, v86, v75, v98 op_sel:[0,0,0] op_sel_hi:[0,1,0]
	v_fma_mix_f32 v98, v87, v75, v98 op_sel:[0,1,0] op_sel_hi:[0,1,0]
	v_cndmask_b32_e64 v191, v189, v188, s[40:41]
	v_cndmask_b32_e64 v192, v188, v189, s[40:41]
	v_fma_mix_f32 v100, v92, v78, 0 op_sel:[0,0,0] op_sel_hi:[1,1,0]
	v_fma_mix_f32 v101, v92, v78, 0 op_sel:[0,1,0] op_sel_hi:[1,1,0]
	v_add_f32_dpp v192, v192, v191 quad_perm:[2,3,0,1] row_mask:0xf bank_mask:0xf bound_ctrl:1
	v_add_f32_dpp v98, v98, v98 quad_perm:[1,0,3,2] row_mask:0xf bank_mask:0xf bound_ctrl:1
	v_fma_mix_f32 v102, v92, v79, 0 op_sel:[0,0,0] op_sel_hi:[1,1,0]
	v_add_f32_dpp v192, v192, v192 row_ror:4 row_mask:0xf bank_mask:0xf bound_ctrl:1
	v_fma_mix_f32 v103, v92, v79, 0 op_sel:[0,1,0] op_sel_hi:[1,1,0]
	v_add_f32_dpp v98, v98, v98 quad_perm:[2,3,0,1] row_mask:0xf bank_mask:0xf bound_ctrl:1
	v_add_f32_dpp v192, v192, v192 row_ror:8 row_mask:0xf bank_mask:0xf bound_ctrl:1
	v_cvt_f16_f32_e32 v192, v192
	global_store_short v83, v192, s[36:37]
	s_add_u32 s36, s36, s44
	s_addc_u32 s37, s37, s45
	global_load_ushort v211, v83, s[22:23]
	s_add_u32 s22, s22, s44
	s_addc_u32 s23, s23, s45
	s_cmp_gt_i32 s35, 9
	s_cbranch_scc0 .Lc_poll_A3
.Lc_ret_A3:
	ds_read_b128 v[0:3], v194 offset:26624
	ds_read_b128 v[4:7], v194 offset:24576
	ds_read_b128 v[8:11], v194 offset:24832
	ds_read_b128 v[12:15], v194 offset:25600
	ds_read_b128 v[16:19], v194 offset:25856
	ds_read_b128 v[20:23], v194 offset:26880
	ds_read_b128 v[24:27], v194 offset:25088
	ds_read_b128 v[28:31], v194 offset:25344
	ds_read_b128 v[32:35], v194 offset:26112
	ds_read_b128 v[36:39], v194 offset:26368
	s_waitcnt vmcnt(12)
	v_mov_b32_dpp v88, v205 quad_perm:[0,0,0,0] row_mask:0xf bank_mask:0xf
	v_mov_b32_dpp v89, v205 quad_perm:[1,1,1,1] row_mask:0xf bank_mask:0xf
	v_mov_b32_dpp v90, v205 quad_perm:[2,2,2,2] row_mask:0xf bank_mask:0xf
	v_mov_b32_dpp v91, v205 quad_perm:[3,3,3,3] row_mask:0xf bank_mask:0xf
	v_fma_mix_f32 v84, v84, v72, v100 op_sel:[0,0,0] op_sel_hi:[0,1,0]
	v_fma_mix_f32 v85, v85, v72, v101 op_sel:[0,1,0] op_sel_hi:[0,1,0]
	v_add_f32_dpp v98, v98, v98 row_half_mirror row_mask:0xf bank_mask:0xf bound_ctrl:1
	v_fma_mix_f32 v86, v86, v73, v102 op_sel:[0,0,0] op_sel_hi:[0,1,0]
	v_fma_mix_f32 v87, v87, v73, v103 op_sel:[0,1,0] op_sel_hi:[0,1,0]
	v_add_f32_dpp v98, v98, v98 row_mirror row_mask:0xf bank_mask:0xf bound_ctrl:1
	v_fma_mix_f32 v84, -v98, v76, v84 op_sel:[0,0,0] op_sel_hi:[0,1,0]
	v_fma_mix_f32 v85, -v98, v76, v85 op_sel:[0,1,0] op_sel_hi:[0,1,0]
	v_fma_mix_f32 v86, -v98, v77, v86 op_sel:[0,0,0] op_sel_hi:[0,1,0]
	v_fma_mix_f32 v87, -v98, v77, v87 op_sel:[0,1,0] op_sel_hi:[0,1,0]
	v_fma_mix_f32 v73, v84, v66, 0 op_sel:[0,0,0] op_sel_hi:[0,1,0]
	v_fma_mix_f32 v97, v84, v56, 0 op_sel:[0,0,0] op_sel_hi:[0,1,0]
	v_fma_mix_f32 v73, v85, v66, v73 op_sel:[0,1,0] op_sel_hi:[0,1,0]
	v_fma_mix_f32 v56, v85, v56, v97 op_sel:[0,1,0] op_sel_hi:[0,1,0]
	v_fma_mix_f32 v73, v86, v67, v73 op_sel:[0,0,0] op_sel_hi:[0,1,0]
	v_fma_mix_f32 v56, v86, v57, v56 op_sel:[0,0,0] op_sel_hi:[0,1,0]
	v_fma_mix_f32 v73, v87, v67, v73 op_sel:[0,1,0] op_sel_hi:[0,1,0]
	v_fma_mix_f32 v56, v87, v57, v56 op_sel:[0,1,0] op_sel_hi:[0,1,0]
	v_fma_mix_f32 v75, v93, v70, 0 op_sel:[0,0,0] op_sel_hi:[1,1,0]
	v_fma_mix_f32 v76, v93, v70, 0 op_sel:[0,1,0] op_sel_hi:[1,1,0]
	v_add_f32_dpp v73, v73, v73 quad_perm:[1,0,3,2] row_mask:0xf bank_mask:0xf bound_ctrl:1
	v_fma_mix_f32 v77, v93, v71, 0 op_sel:[0,0,0] op_sel_hi:[1,1,0]
	v_fma_mix_f32 v78, v93, v71, 0 op_sel:[0,1,0] op_sel_hi:[1,1,0]
	v_add_f32_dpp v73, v73, v73 quad_perm:[2,3,0,1] row_mask:0xf bank_mask:0xf bound_ctrl:1
	v_fma_mix_f32 v84, v84, v64, v75 op_sel:[0,0,0] op_sel_hi:[0,1,0]
	v_fma_mix_f32 v85, v85, v64, v76 op_sel:[0,1,0] op_sel_hi:[0,1,0]
	v_add_f32_dpp v73, v73, v73 row_half_mirror row_mask:0xf bank_mask:0xf bound_ctrl:1
	v_fma_mix_f32 v86, v86, v65, v77 op_sel:[0,0,0] op_sel_hi:[0,1,0]
	v_fma_mix_f32 v87, v87, v65, v78 op_sel:[0,1,0] op_sel_hi:[0,1,0]
	v_add_f32_dpp v73, v73, v73 row_mirror row_mask:0xf bank_mask:0xf bound_ctrl:1
	v_fma_mix_f32 v84, -v73, v68, v84 op_sel:[0,0,0] op_sel_hi:[0,1,0]
	v_fma_mix_f32 v85, -v73, v68, v85 op_sel:[0,1,0] op_sel_hi:[0,1,0]
	v_fma_mix_f32 v86, -v73, v69, v86 op_sel:[0,0,0] op_sel_hi:[0,1,0]
	v_fma_mix_f32 v87, -v73, v69, v87 op_sel:[0,1,0] op_sel_hi:[0,1,0]
	v_fma_mix_f32 v64, v84, v54, 0 op_sel:[0,0,0] op_sel_hi:[0,1,0]
	v_fma_mix_f32 v57, v84, v58, 0 op_sel:[0,0,0] op_sel_hi:[0,1,0]
	v_fma_mix_f32 v64, v85, v54, v64 op_sel:[0,1,0] op_sel_hi:[0,1,0]
	v_fma_mix_f32 v57, v85, v58, v57 op_sel:[0,1,0] op_sel_hi:[0,1,0]
	v_fma_mix_f32 v64, v86, v55, v64 op_sel:[0,0,0] op_sel_hi:[0,1,0]
	v_fma_mix_f32 v57, v86, v59, v57 op_sel:[0,0,0] op_sel_hi:[0,1,0]
	v_fma_mix_f32 v64, v87, v55, v64 op_sel:[0,1,0] op_sel_hi:[0,1,0]
	v_fma_mix_f32 v57, v87, v59, v57 op_sel:[0,1,0] op_sel_hi:[0,1,0]
	v_fma_mix_f32 v66, v94, v62, 0 op_sel:[0,0,0] op_sel_hi:[1,1,0]
	v_fma_mix_f32 v67, v94, v62, 0 op_sel:[0,1,0] op_sel_hi:[1,1,0]
	v_add_f32_dpp v64, v64, v64 quad_perm:[1,0,3,2] row_mask:0xf bank_mask:0xf bound_ctrl:1
	v_fma_mix_f32 v68, v94, v63, 0 op_sel:[0,0,0] op_sel_hi:[1,1,0]
	v_fma_mix_f32 v69, v94, v63, 0 op_sel:[0,1,0] op_sel_hi:[1,1,0]
	v_add_f32_dpp v64, v64, v64 quad_perm:[2,3,0,1] row_mask:0xf bank_mask:0xf bound_ctrl:1
	v_fma_mix_f32 v84, v84, v52, v66 op_sel:[0,0,0] op_sel_hi:[0,1,0]
	v_fma_mix_f32 v85, v85, v52, v67 op_sel:[0,1,0] op_sel_hi:[0,1,0]
	v_add_f32_dpp v64, v64, v64 row_half_mirror row_mask:0xf bank_mask:0xf bound_ctrl:1
	v_fma_mix_f32 v86, v86, v53, v68 op_sel:[0,0,0] op_sel_hi:[0,1,0]
	v_fma_mix_f32 v87, v87, v53, v69 op_sel:[0,1,0] op_sel_hi:[0,1,0]
	v_add_f32_dpp v64, v64, v64 row_mirror row_mask:0xf bank_mask:0xf bound_ctrl:1
	v_fma_mix_f32 v84, -v64, v60, v84 op_sel:[0,0,0] op_sel_hi:[0,1,0]
	v_fma_mix_f32 v85, -v64, v60, v85 op_sel:[0,1,0] op_sel_hi:[0,1,0]
	v_fma_mix_f32 v86, -v64, v61, v86 op_sel:[0,0,0] op_sel_hi:[0,1,0]
	v_fma_mix_f32 v87, -v64, v61, v87 op_sel:[0,1,0] op_sel_hi:[0,1,0]
	v_fma_mix_f32 v53, v84, v46, 0 op_sel:[0,0,0] op_sel_hi:[0,1,0]
	v_fma_mix_f32 v59, v84, v40, 0 op_sel:[0,0,0] op_sel_hi:[0,1,0]
	v_fma_mix_f32 v53, v85, v46, v53 op_sel:[0,1,0] op_sel_hi:[0,1,0]
	v_fma_mix_f32 v40, v85, v40, v59 op_sel:[0,1,0] op_sel_hi:[0,1,0]
	v_fma_mix_f32 v53, v86, v47, v53 op_sel:[0,0,0] op_sel_hi:[0,1,0]
	v_fma_mix_f32 v40, v86, v41, v40 op_sel:[0,0,0] op_sel_hi:[0,1,0]
	v_fma_mix_f32 v53, v87, v47, v53 op_sel:[0,1,0] op_sel_hi:[0,1,0]
	v_fma_mix_f32 v40, v87, v41, v40 op_sel:[0,1,0] op_sel_hi:[0,1,0]
	v_fma_mix_f32 v55, v95, v50, 0 op_sel:[0,0,0] op_sel_hi:[1,1,0]
	v_fma_mix_f32 v58, v95, v50, 0 op_sel:[0,1,0] op_sel_hi:[1,1,0]
	v_add_f32_dpp v53, v53, v53 quad_perm:[1,0,3,2] row_mask:0xf bank_mask:0xf bound_ctrl:1
	v_fma_mix_f32 v59, v95, v51, 0 op_sel:[0,0,0] op_sel_hi:[1,1,0]
	v_fma_mix_f32 v60, v95, v51, 0 op_sel:[0,1,0] op_sel_hi:[1,1,0]
	v_add_f32_dpp v53, v53, v53 quad_perm:[2,3,0,1] row_mask:0xf bank_mask:0xf bound_ctrl:1
	v_fma_mix_f32 v84, v84, v44, v55 op_sel:[0,0,0] op_sel_hi:[0,1,0]
	v_fma_mix_f32 v85, v85, v44, v58 op_sel:[0,1,0] op_sel_hi:[0,1,0]
	v_add_f32_dpp v53, v53, v53 row_half_mirror row_mask:0xf bank_mask:0xf bound_ctrl:1
	v_fma_mix_f32 v86, v86, v45, v59 op_sel:[0,0,0] op_sel_hi:[0,1,0]
	v_fma_mix_f32 v87, v87, v45, v60 op_sel:[0,1,0] op_sel_hi:[0,1,0]
	v_add_f32_dpp v53, v53, v53 row_mirror row_mask:0xf bank_mask:0xf bound_ctrl:1
	v_fma_mix_f32 v84, -v53, v48, v84 op_sel:[0,0,0] op_sel_hi:[0,1,0]
	v_fma_mix_f32 v85, -v53, v48, v85 op_sel:[0,1,0] op_sel_hi:[0,1,0]
	v_fma_mix_f32 v86, -v53, v49, v86 op_sel:[0,0,0] op_sel_hi:[0,1,0]
	v_fma_mix_f32 v87, -v53, v49, v87 op_sel:[0,1,0] op_sel_hi:[0,1,0]
	v_fma_mix_f32 v41, v84, v42, 0 op_sel:[0,0,0] op_sel_hi:[0,1,0]
	v_add_u32_e32 v173, 8, v193
	v_fma_mix_f32 v41, v85, v42, v41 op_sel:[0,1,0] op_sel_hi:[0,1,0]
	ds_write_b32 v172, v173 offset:49216
	v_fma_mix_f32 v41, v86, v43, v41 op_sel:[0,0,0] op_sel_hi:[0,1,0]
	v_cndmask_b32_e64 v187, v57, v56, s[38:39]
	v_fma_mix_f32 v41, v87, v43, v41 op_sel:[0,1,0] op_sel_hi:[0,1,0]
	v_cndmask_b32_e64 v188, v56, v57, s[38:39]
	v_cndmask_b32_e64 v189, v41, v40, s[38:39]
	v_cndmask_b32_e64 v190, v40, v41, s[38:39]
	s_waitcnt lgkmcnt(1)
	v_fma_mix_f32 v98, v84, v6, 0 op_sel:[0,0,0] op_sel_hi:[0,1,0]
	v_fma_mix_f32 v98, v85, v6, v98 op_sel:[0,1,0] op_sel_hi:[0,1,0]
	v_add_f32_dpp v188, v188, v187 quad_perm:[1,0,3,2] row_mask:0xf bank_mask:0xf bound_ctrl:1
	v_add_f32_dpp v189, v190, v189 quad_perm:[1,0,3,2] row_mask:0xf bank_mask:0xf bound_ctrl:1
	v_fma_mix_f32 v98, v86, v7, v98 op_sel:[0,0,0] op_sel_hi:[0,1,0]
	v_fma_mix_f32 v98, v87, v7, v98 op_sel:[0,1,0] op_sel_hi:[0,1,0]
	v_cndmask_b32_e64 v191, v189, v188, s[40:41]
	v_cndmask_b32_e64 v192, v188, v189, s[40:41]
	v_fma_mix_f32 v100, v88, v14, 0 op_sel:[0,0,0] op_sel_hi:[1,1,0]
	v_fma_mix_f32 v101, v88, v14, 0 op_sel:[0,1,0] op_sel_hi:[1,1,0]
	v_add_f32_dpp v192, v192, v191 quad_perm:[2,3,0,1] row_mask:0xf bank_mask:0xf bound_ctrl:1
	v_add_f32_dpp v98, v98, v98 quad_perm:[1,0,3,2] row_mask:0xf bank_mask:0xf bound_ctrl:1
	v_fma_mix_f32 v102, v88, v15, 0 op_sel:[0,0,0] op_sel_hi:[1,1,0]
	v_add_f32_dpp v192, v192, v192 row_ror:4 row_mask:0xf bank_mask:0xf bound_ctrl:1
	v_fma_mix_f32 v103, v88, v15, 0 op_sel:[0,1,0] op_sel_hi:[1,1,0]
	v_add_f32_dpp v98, v98, v98 quad_perm:[2,3,0,1] row_mask:0xf bank_mask:0xf bound_ctrl:1
	v_add_f32_dpp v192, v192, v192 row_ror:8 row_mask:0xf bank_mask:0xf bound_ctrl:1
	v_cvt_f16_f32_e32 v192, v192
	global_store_short v83, v192, s[36:37]
	s_add_u32 s36, s36, s44
	s_addc_u32 s37, s37, s45
	global_load_ushort v212, v83, s[22:23]
	s_add_u32 s22, s22, s44
	s_addc_u32 s23, s23, s45
	ds_read_b128 v[56:59], v194 offset:29696
	ds_read_b128 v[72:75], v194 offset:27648
	ds_read_b128 v[64:67], v194 offset:27904
	ds_read_b128 v[76:79], v194 offset:28672
	ds_read_b128 v[68:71], v194 offset:28928
	ds_read_b128 v[40:43], v194 offset:29952
	ds_read_b128 v[52:55], v194 offset:28160
	ds_read_b128 v[44:47], v194 offset:28416
	ds_read_b128 v[60:63], v194 offset:29184
	ds_read_b128 v[48:51], v194 offset:29440
	s_waitcnt vmcnt(12)
	v_mov_b32_dpp v92, v206 quad_perm:[0,0,0,0] row_mask:0xf bank_mask:0xf
	v_mov_b32_dpp v93, v206 quad_perm:[1,1,1,1] row_mask:0xf bank_mask:0xf
	v_mov_b32_dpp v94, v206 quad_perm:[2,2,2,2] row_mask:0xf bank_mask:0xf
	v_mov_b32_dpp v95, v206 quad_perm:[3,3,3,3] row_mask:0xf bank_mask:0xf
	v_fma_mix_f32 v84, v84, v4, v100 op_sel:[0,0,0] op_sel_hi:[0,1,0]
	v_fma_mix_f32 v85, v85, v4, v101 op_sel:[0,1,0] op_sel_hi:[0,1,0]
	v_add_f32_dpp v98, v98, v98 row_half_mirror row_mask:0xf bank_mask:0xf bound_ctrl:1
	v_fma_mix_f32 v86, v86, v5, v102 op_sel:[0,0,0] op_sel_hi:[0,1,0]
	v_fma_mix_f32 v87, v87, v5, v103 op_sel:[0,1,0] op_sel_hi:[0,1,0]
	v_add_f32_dpp v98, v98, v98 row_mirror row_mask:0xf bank_mask:0xf bound_ctrl:1
	v_fma_mix_f32 v84, -v98, v12, v84 op_sel:[0,0,0] op_sel_hi:[0,1,0]
	v_fma_mix_f32 v85, -v98, v12, v85 op_sel:[0,1,0] op_sel_hi:[0,1,0]
	v_fma_mix_f32 v86, -v98, v13, v86 op_sel:[0,0,0] op_sel_hi:[0,1,0]
	v_fma_mix_f32 v87, -v98, v13, v87 op_sel:[0,1,0] op_sel_hi:[0,1,0]
	v_fma_mix_f32 v99, v84, v10, 0 op_sel:[0,0,0] op_sel_hi:[0,1,0]
	v_fma_mix_f32 v96, v84, v0, 0 op_sel:[0,0,0] op_sel_hi:[0,1,0]
	v_fma_mix_f32 v99, v85, v10, v99 op_sel:[0,1,0] op_sel_hi:[0,1,0]
	v_fma_mix_f32 v96, v85, v0, v96 op_sel:[0,1,0] op_sel_hi:[0,1,0]
	v_fma_mix_f32 v99, v86, v11, v99 op_sel:[0,0,0] op_sel_hi:[0,1,0]
	v_fma_mix_f32 v96, v86, v1, v96 op_sel:[0,0,0] op_sel_hi:[0,1,0]
	v_fma_mix_f32 v99, v87, v11, v99 op_sel:[0,1,0] op_sel_hi:[0,1,0]
	v_fma_mix_f32 v96, v87, v1, v96 op_sel:[0,1,0] op_sel_hi:[0,1,0]
	v_fma_mix_f32 v101, v89, v18, 0 op_sel:[0,0,0] op_sel_hi:[1,1,0]
	v_fma_mix_f32 v102, v89, v18, 0 op_sel:[0,1,0] op_sel_hi:[1,1,0]
	v_add_f32_dpp v99, v99, v99 quad_perm:[1,0,3,2] row_mask:0xf bank_mask:0xf bound_ctrl:1
	v_fma_mix_f32 v103, v89, v19, 0 op_sel:[0,0,0] op_sel_hi:[1,1,0]
	v_fma_mix_f32 v104, v89, v19, 0 op_sel:[0,1,0] op_sel_hi:[1,1,0]
	v_add_f32_dpp v99, v99, v99 quad_perm:[2,3,0,1] row_mask:0xf bank_mask:0xf bound_ctrl:1
	v_fma_mix_f32 v84, v84, v8, v101 op_sel:[0,0,0] op_sel_hi:[0,1,0]
	v_fma_mix_f32 v85, v85, v8, v102 op_sel:[0,1,0] op_sel_hi:[0,1,0]
	v_add_f32_dpp v99, v99, v99 row_half_mirror row_mask:0xf bank_mask:0xf bound_ctrl:1
	v_fma_mix_f32 v86, v86, v9, v103 op_sel:[0,0,0] op_sel_hi:[0,1,0]
	v_fma_mix_f32 v87, v87, v9, v104 op_sel:[0,1,0] op_sel_hi:[0,1,0]
	v_add_f32_dpp v99, v99, v99 row_mirror row_mask:0xf bank_mask:0xf bound_ctrl:1
	v_fma_mix_f32 v84, -v99, v16, v84 op_sel:[0,0,0] op_sel_hi:[0,1,0]
	v_fma_mix_f32 v85, -v99, v16, v85 op_sel:[0,1,0] op_sel_hi:[0,1,0]
	v_fma_mix_f32 v86, -v99, v17, v86 op_sel:[0,0,0] op_sel_hi:[0,1,0]
	v_fma_mix_f32 v87, -v99, v17, v87 op_sel:[0,1,0] op_sel_hi:[0,1,0]
	v_fma_mix_f32 v100, v84, v26, 0 op_sel:[0,0,0] op_sel_hi:[0,1,0]
	v_fma_mix_f32 v97, v84, v2, 0 op_sel:[0,0,0] op_sel_hi:[0,1,0]
	v_fma_mix_f32 v100, v85, v26, v100 op_sel:[0,1,0] op_sel_hi:[0,1,0]
	v_fma_mix_f32 v97, v85, v2, v97 op_sel:[0,1,0] op_sel_hi:[0,1,0]
	v_fma_mix_f32 v100, v86, v27, v100 op_sel:[0,0,0] op_sel_hi:[0,1,0]
	v_fma_mix_f32 v97, v86, v3, v97 op_sel:[0,0,0] op_sel_hi:[0,1,0]
	v_fma_mix_f32 v100, v87, v27, v100 op_sel:[0,1,0] op_sel_hi:[0,1,0]
	v_fma_mix_f32 v97, v87, v3, v97 op_sel:[0,1,0] op_sel_hi:[0,1,0]
	v_fma_mix_f32 v102, v90, v34, 0 op_sel:[0,0,0] op_sel_hi:[1,1,0]
	v_fma_mix_f32 v103, v90, v34, 0 op_sel:[0,1,0] op_sel_hi:[1,1,0]
	v_add_f32_dpp v100, v100, v100 quad_perm:[1,0,3,2] row_mask:0xf bank_mask:0xf bound_ctrl:1
	v_fma_mix_f32 v104, v90, v35, 0 op_sel:[0,0,0] op_sel_hi:[1,1,0]
	v_fma_mix_f32 v105, v90, v35, 0 op_sel:[0,1,0] op_sel_hi:[1,1,0]
	v_add_f32_dpp v100, v100, v100 quad_perm:[2,3,0,1] row_mask:0xf bank_mask:0xf bound_ctrl:1
	v_fma_mix_f32 v84, v84, v24, v102 op_sel:[0,0,0] op_sel_hi:[0,1,0]
	v_fma_mix_f32 v85, v85, v24, v103 op_sel:[0,1,0] op_sel_hi:[0,1,0]
	v_add_f32_dpp v100, v100, v100 row_half_mirror row_mask:0xf bank_mask:0xf bound_ctrl:1
	v_fma_mix_f32 v86, v86, v25, v104 op_sel:[0,0,0] op_sel_hi:[0,1,0]
	v_fma_mix_f32 v87, v87, v25, v105 op_sel:[0,1,0] op_sel_hi:[0,1,0]
	v_add_f32_dpp v100, v100, v100 row_mirror row_mask:0xf bank_mask:0xf bound_ctrl:1
	v_fma_mix_f32 v84, -v100, v32, v84 op_sel:[0,0,0] op_sel_hi:[0,1,0]
	v_fma_mix_f32 v85, -v100, v32, v85 op_sel:[0,1,0] op_sel_hi:[0,1,0]
	v_fma_mix_f32 v86, -v100, v33, v86 op_sel:[0,0,0] op_sel_hi:[0,1,0]
	v_fma_mix_f32 v87, -v100, v33, v87 op_sel:[0,1,0] op_sel_hi:[0,1,0]
	v_fma_mix_f32 v101, v84, v30, 0 op_sel:[0,0,0] op_sel_hi:[0,1,0]
	v_fma_mix_f32 v98, v84, v20, 0 op_sel:[0,0,0] op_sel_hi:[0,1,0]
	v_fma_mix_f32 v101, v85, v30, v101 op_sel:[0,1,0] op_sel_hi:[0,1,0]
	v_fma_mix_f32 v98, v85, v20, v98 op_sel:[0,1,0] op_sel_hi:[0,1,0]
	v_fma_mix_f32 v101, v86, v31, v101 op_sel:[0,0,0] op_sel_hi:[0,1,0]
	v_fma_mix_f32 v98, v86, v21, v98 op_sel:[0,0,0] op_sel_hi:[0,1,0]
	v_fma_mix_f32 v101, v87, v31, v101 op_sel:[0,1,0] op_sel_hi:[0,1,0]
	v_fma_mix_f32 v98, v87, v21, v98 op_sel:[0,1,0] op_sel_hi:[0,1,0]
	v_fma_mix_f32 v103, v91, v38, 0 op_sel:[0,0,0] op_sel_hi:[1,1,0]
	v_fma_mix_f32 v104, v91, v38, 0 op_sel:[0,1,0] op_sel_hi:[1,1,0]
	v_add_f32_dpp v101, v101, v101 quad_perm:[1,0,3,2] row_mask:0xf bank_mask:0xf bound_ctrl:1
	v_fma_mix_f32 v105, v91, v39, 0 op_sel:[0,0,0] op_sel_hi:[1,1,0]
	v_fma_mix_f32 v119, v91, v39, 0 op_sel:[0,1,0] op_sel_hi:[1,1,0]
	v_add_f32_dpp v101, v101, v101 quad_perm:[2,3,0,1] row_mask:0xf bank_mask:0xf bound_ctrl:1
	v_fma_mix_f32 v84, v84, v28, v103 op_sel:[0,0,0] op_sel_hi:[0,1,0]
	v_fma_mix_f32 v85, v85, v28, v104 op_sel:[0,1,0] op_sel_hi:[0,1,0]
	v_add_f32_dpp v101, v101, v101 row_half_mirror row_mask:0xf bank_mask:0xf bound_ctrl:1
	v_fma_mix_f32 v86, v86, v29, v105 op_sel:[0,0,0] op_sel_hi:[0,1,0]
	v_fma_mix_f32 v87, v87, v29, v119 op_sel:[0,1,0] op_sel_hi:[0,1,0]
	v_add_f32_dpp v101, v101, v101 row_mirror row_mask:0xf bank_mask:0xf bound_ctrl:1
	v_fma_mix_f32 v84, -v101, v36, v84 op_sel:[0,0,0] op_sel_hi:[0,1,0]
	v_fma_mix_f32 v85, -v101, v36, v85 op_sel:[0,1,0] op_sel_hi:[0,1,0]
	v_fma_mix_f32 v86, -v101, v37, v86 op_sel:[0,0,0] op_sel_hi:[0,1,0]
	v_fma_mix_f32 v87, -v101, v37, v87 op_sel:[0,1,0] op_sel_hi:[0,1,0]
	v_fma_mix_f32 v99, v84, v22, 0 op_sel:[0,0,0] op_sel_hi:[0,1,0]
	v_cndmask_b32_e64 v187, v97, v96, s[38:39]
	v_fma_mix_f32 v99, v85, v22, v99 op_sel:[0,1,0] op_sel_hi:[0,1,0]
	v_cndmask_b32_e64 v188, v96, v97, s[38:39]
	v_fma_mix_f32 v99, v86, v23, v99 op_sel:[0,0,0] op_sel_hi:[0,1,0]
	v_fma_mix_f32 v99, v87, v23, v99 op_sel:[0,1,0] op_sel_hi:[0,1,0]
	v_cndmask_b32_e64 v189, v99, v98, s[38:39]
	v_cndmask_b32_e64 v190, v98, v99, s[38:39]
	s_waitcnt lgkmcnt(0)
	v_fma_mix_f32 v98, v84, v74, 0 op_sel:[0,0,0] op_sel_hi:[0,1,0]
	v_fma_mix_f32 v98, v85, v74, v98 op_sel:[0,1,0] op_sel_hi:[0,1,0]
	v_add_f32_dpp v188, v188, v187 quad_perm:[1,0,3,2] row_mask:0xf bank_mask:0xf bound_ctrl:1
	v_add_f32_dpp v189, v190, v189 quad_perm:[1,0,3,2] row_mask:0xf bank_mask:0xf bound_ctrl:1
	v_fma_mix_f32 v98, v86, v75, v98 op_sel:[0,0,0] op_sel_hi:[0,1,0]
	v_fma_mix_f32 v98, v87, v75, v98 op_sel:[0,1,0] op_sel_hi:[0,1,0]
	v_cndmask_b32_e64 v191, v189, v188, s[40:41]
	v_cndmask_b32_e64 v192, v188, v189, s[40:41]
	v_fma_mix_f32 v100, v92, v78, 0 op_sel:[0,0,0] op_sel_hi:[1,1,0]
	v_fma_mix_f32 v101, v92, v78, 0 op_sel:[0,1,0] op_sel_hi:[1,1,0]
	v_add_f32_dpp v192, v192, v191 quad_perm:[2,3,0,1] row_mask:0xf bank_mask:0xf bound_ctrl:1
	v_add_f32_dpp v98, v98, v98 quad_perm:[1,0,3,2] row_mask:0xf bank_mask:0xf bound_ctrl:1
	v_fma_mix_f32 v102, v92, v79, 0 op_sel:[0,0,0] op_sel_hi:[1,1,0]
	v_add_f32_dpp v192, v192, v192 row_ror:4 row_mask:0xf bank_mask:0xf bound_ctrl:1
	v_fma_mix_f32 v103, v92, v79, 0 op_sel:[0,1,0] op_sel_hi:[1,1,0]
	v_add_f32_dpp v98, v98, v98 quad_perm:[2,3,0,1] row_mask:0xf bank_mask:0xf bound_ctrl:1
	v_add_f32_dpp v192, v192, v192 row_ror:8 row_mask:0xf bank_mask:0xf bound_ctrl:1
	v_cvt_f16_f32_e32 v192, v192
	global_store_short v83, v192, s[36:37]
	s_add_u32 s36, s36, s44
	s_addc_u32 s37, s37, s45
	s_cmp_eq_u32 s33, 48
	s_cbranch_scc0 .Lc_pv_nofix
	s_mov_b64 s[22:23], s[90:91]
.Lc_pv_nofix:
	global_load_ushort v197, v83, s[22:23]
	s_add_u32 s22, s22, s44
	s_addc_u32 s23, s23, s45
	s_cmp_gt_i32 s35, 11
	s_cbranch_scc0 .Lc_poll_A4
.Lc_ret_A4:
	ds_read_b128 v[0:3], v194 offset:32768
	ds_read_b128 v[4:7], v194 offset:30720
	ds_read_b128 v[8:11], v194 offset:30976
	ds_read_b128 v[12:15], v194 offset:31744
	ds_read_b128 v[16:19], v194 offset:32000
	ds_read_b128 v[20:23], v194 offset:33024
	ds_read_b128 v[24:27], v194 offset:31232
	ds_read_b128 v[28:31], v194 offset:31488
	ds_read_b128 v[32:35], v194 offset:32256
	ds_read_b128 v[36:39], v194 offset:32512
	s_waitcnt vmcnt(12)
	v_mov_b32_dpp v88, v207 quad_perm:[0,0,0,0] row_mask:0xf bank_mask:0xf
	v_mov_b32_dpp v89, v207 quad_perm:[1,1,1,1] row_mask:0xf bank_mask:0xf
	v_mov_b32_dpp v90, v207 quad_perm:[2,2,2,2] row_mask:0xf bank_mask:0xf
	v_mov_b32_dpp v91, v207 quad_perm:[3,3,3,3] row_mask:0xf bank_mask:0xf
	v_fma_mix_f32 v84, v84, v72, v100 op_sel:[0,0,0] op_sel_hi:[0,1,0]
	v_fma_mix_f32 v85, v85, v72, v101 op_sel:[0,1,0] op_sel_hi:[0,1,0]
	v_add_f32_dpp v98, v98, v98 row_half_mirror row_mask:0xf bank_mask:0xf bound_ctrl:1
	v_fma_mix_f32 v86, v86, v73, v102 op_sel:[0,0,0] op_sel_hi:[0,1,0]
	v_fma_mix_f32 v87, v87, v73, v103 op_sel:[0,1,0] op_sel_hi:[0,1,0]
	v_add_f32_dpp v98, v98, v98 row_mirror row_mask:0xf bank_mask:0xf bound_ctrl:1
	v_fma_mix_f32 v84, -v98, v76, v84 op_sel:[0,0,0] op_sel_hi:[0,1,0]
	v_fma_mix_f32 v85, -v98, v76, v85 op_sel:[0,1,0] op_sel_hi:[0,1,0]
	v_fma_mix_f32 v86, -v98, v77, v86 op_sel:[0,0,0] op_sel_hi:[0,1,0]
	v_fma_mix_f32 v87, -v98, v77, v87 op_sel:[0,1,0] op_sel_hi:[0,1,0]
	v_fma_mix_f32 v73, v84, v66, 0 op_sel:[0,0,0] op_sel_hi:[0,1,0]
	v_fma_mix_f32 v97, v84, v56, 0 op_sel:[0,0,0] op_sel_hi:[0,1,0]
	v_fma_mix_f32 v73, v85, v66, v73 op_sel:[0,1,0] op_sel_hi:[0,1,0]
	v_fma_mix_f32 v56, v85, v56, v97 op_sel:[0,1,0] op_sel_hi:[0,1,0]
	v_fma_mix_f32 v73, v86, v67, v73 op_sel:[0,0,0] op_sel_hi:[0,1,0]
	v_fma_mix_f32 v56, v86, v57, v56 op_sel:[0,0,0] op_sel_hi:[0,1,0]
	v_fma_mix_f32 v73, v87, v67, v73 op_sel:[0,1,0] op_sel_hi:[0,1,0]
	v_fma_mix_f32 v56, v87, v57, v56 op_sel:[0,1,0] op_sel_hi:[0,1,0]
	v_fma_mix_f32 v75, v93, v70, 0 op_sel:[0,0,0] op_sel_hi:[1,1,0]
	v_fma_mix_f32 v76, v93, v70, 0 op_sel:[0,1,0] op_sel_hi:[1,1,0]
	v_add_f32_dpp v73, v73, v73 quad_perm:[1,0,3,2] row_mask:0xf bank_mask:0xf bound_ctrl:1
	v_fma_mix_f32 v77, v93, v71, 0 op_sel:[0,0,0] op_sel_hi:[1,1,0]
	v_fma_mix_f32 v78, v93, v71, 0 op_sel:[0,1,0] op_sel_hi:[1,1,0]
	v_add_f32_dpp v73, v73, v73 quad_perm:[2,3,0,1] row_mask:0xf bank_mask:0xf bound_ctrl:1
	v_fma_mix_f32 v84, v84, v64, v75 op_sel:[0,0,0] op_sel_hi:[0,1,0]
	v_fma_mix_f32 v85, v85, v64, v76 op_sel:[0,1,0] op_sel_hi:[0,1,0]
	v_add_f32_dpp v73, v73, v73 row_half_mirror row_mask:0xf bank_mask:0xf bound_ctrl:1
	v_fma_mix_f32 v86, v86, v65, v77 op_sel:[0,0,0] op_sel_hi:[0,1,0]
	v_fma_mix_f32 v87, v87, v65, v78 op_sel:[0,1,0] op_sel_hi:[0,1,0]
	v_add_f32_dpp v73, v73, v73 row_mirror row_mask:0xf bank_mask:0xf bound_ctrl:1
	v_fma_mix_f32 v84, -v73, v68, v84 op_sel:[0,0,0] op_sel_hi:[0,1,0]
	v_fma_mix_f32 v85, -v73, v68, v85 op_sel:[0,1,0] op_sel_hi:[0,1,0]
	v_fma_mix_f32 v86, -v73, v69, v86 op_sel:[0,0,0] op_sel_hi:[0,1,0]
	v_fma_mix_f32 v87, -v73, v69, v87 op_sel:[0,1,0] op_sel_hi:[0,1,0]
	v_fma_mix_f32 v64, v84, v54, 0 op_sel:[0,0,0] op_sel_hi:[0,1,0]
	v_fma_mix_f32 v57, v84, v58, 0 op_sel:[0,0,0] op_sel_hi:[0,1,0]
	v_fma_mix_f32 v64, v85, v54, v64 op_sel:[0,1,0] op_sel_hi:[0,1,0]
	v_fma_mix_f32 v57, v85, v58, v57 op_sel:[0,1,0] op_sel_hi:[0,1,0]
	v_fma_mix_f32 v64, v86, v55, v64 op_sel:[0,0,0] op_sel_hi:[0,1,0]
	v_fma_mix_f32 v57, v86, v59, v57 op_sel:[0,0,0] op_sel_hi:[0,1,0]
	v_fma_mix_f32 v64, v87, v55, v64 op_sel:[0,1,0] op_sel_hi:[0,1,0]
	v_fma_mix_f32 v57, v87, v59, v57 op_sel:[0,1,0] op_sel_hi:[0,1,0]
	v_fma_mix_f32 v66, v94, v62, 0 op_sel:[0,0,0] op_sel_hi:[1,1,0]
	v_fma_mix_f32 v67, v94, v62, 0 op_sel:[0,1,0] op_sel_hi:[1,1,0]
	v_add_f32_dpp v64, v64, v64 quad_perm:[1,0,3,2] row_mask:0xf bank_mask:0xf bound_ctrl:1
	v_fma_mix_f32 v68, v94, v63, 0 op_sel:[0,0,0] op_sel_hi:[1,1,0]
	v_fma_mix_f32 v69, v94, v63, 0 op_sel:[0,1,0] op_sel_hi:[1,1,0]
	v_add_f32_dpp v64, v64, v64 quad_perm:[2,3,0,1] row_mask:0xf bank_mask:0xf bound_ctrl:1
	v_fma_mix_f32 v84, v84, v52, v66 op_sel:[0,0,0] op_sel_hi:[0,1,0]
	v_fma_mix_f32 v85, v85, v52, v67 op_sel:[0,1,0] op_sel_hi:[0,1,0]
	v_add_f32_dpp v64, v64, v64 row_half_mirror row_mask:0xf bank_mask:0xf bound_ctrl:1
	v_fma_mix_f32 v86, v86, v53, v68 op_sel:[0,0,0] op_sel_hi:[0,1,0]
	v_fma_mix_f32 v87, v87, v53, v69 op_sel:[0,1,0] op_sel_hi:[0,1,0]
	v_add_f32_dpp v64, v64, v64 row_mirror row_mask:0xf bank_mask:0xf bound_ctrl:1
	v_fma_mix_f32 v84, -v64, v60, v84 op_sel:[0,0,0] op_sel_hi:[0,1,0]
	v_fma_mix_f32 v85, -v64, v60, v85 op_sel:[0,1,0] op_sel_hi:[0,1,0]
	v_fma_mix_f32 v86, -v64, v61, v86 op_sel:[0,0,0] op_sel_hi:[0,1,0]
	v_fma_mix_f32 v87, -v64, v61, v87 op_sel:[0,1,0] op_sel_hi:[0,1,0]
	v_fma_mix_f32 v53, v84, v46, 0 op_sel:[0,0,0] op_sel_hi:[0,1,0]
	v_fma_mix_f32 v59, v84, v40, 0 op_sel:[0,0,0] op_sel_hi:[0,1,0]
	v_fma_mix_f32 v53, v85, v46, v53 op_sel:[0,1,0] op_sel_hi:[0,1,0]
	v_fma_mix_f32 v40, v85, v40, v59 op_sel:[0,1,0] op_sel_hi:[0,1,0]
	v_fma_mix_f32 v53, v86, v47, v53 op_sel:[0,0,0] op_sel_hi:[0,1,0]
	v_fma_mix_f32 v40, v86, v41, v40 op_sel:[0,0,0] op_sel_hi:[0,1,0]
	v_fma_mix_f32 v53, v87, v47, v53 op_sel:[0,1,0] op_sel_hi:[0,1,0]
	v_fma_mix_f32 v40, v87, v41, v40 op_sel:[0,1,0] op_sel_hi:[0,1,0]
	v_fma_mix_f32 v55, v95, v50, 0 op_sel:[0,0,0] op_sel_hi:[1,1,0]
	v_fma_mix_f32 v58, v95, v50, 0 op_sel:[0,1,0] op_sel_hi:[1,1,0]
	v_add_f32_dpp v53, v53, v53 quad_perm:[1,0,3,2] row_mask:0xf bank_mask:0xf bound_ctrl:1
	v_fma_mix_f32 v59, v95, v51, 0 op_sel:[0,0,0] op_sel_hi:[1,1,0]
	v_fma_mix_f32 v60, v95, v51, 0 op_sel:[0,1,0] op_sel_hi:[1,1,0]
	v_add_f32_dpp v53, v53, v53 quad_perm:[2,3,0,1] row_mask:0xf bank_mask:0xf bound_ctrl:1
	v_fma_mix_f32 v84, v84, v44, v55 op_sel:[0,0,0] op_sel_hi:[0,1,0]
	v_fma_mix_f32 v85, v85, v44, v58 op_sel:[0,1,0] op_sel_hi:[0,1,0]
	v_add_f32_dpp v53, v53, v53 row_half_mirror row_mask:0xf bank_mask:0xf bound_ctrl:1
	v_fma_mix_f32 v86, v86, v45, v59 op_sel:[0,0,0] op_sel_hi:[0,1,0]
	v_fma_mix_f32 v87, v87, v45, v60 op_sel:[0,1,0] op_sel_hi:[0,1,0]
	v_add_f32_dpp v53, v53, v53 row_mirror row_mask:0xf bank_mask:0xf bound_ctrl:1
	v_fma_mix_f32 v84, -v53, v48, v84 op_sel:[0,0,0] op_sel_hi:[0,1,0]
	v_fma_mix_f32 v85, -v53, v48, v85 op_sel:[0,1,0] op_sel_hi:[0,1,0]
	v_fma_mix_f32 v86, -v53, v49, v86 op_sel:[0,0,0] op_sel_hi:[0,1,0]
	v_fma_mix_f32 v87, -v53, v49, v87 op_sel:[0,1,0] op_sel_hi:[0,1,0]
	v_fma_mix_f32 v41, v84, v42, 0 op_sel:[0,0,0] op_sel_hi:[0,1,0]
	v_cndmask_b32_e64 v187, v57, v56, s[38:39]
	v_fma_mix_f32 v41, v85, v42, v41 op_sel:[0,1,0] op_sel_hi:[0,1,0]
	v_cndmask_b32_e64 v188, v56, v57, s[38:39]
	v_fma_mix_f32 v41, v86, v43, v41 op_sel:[0,0,0] op_sel_hi:[0,1,0]
	v_fma_mix_f32 v41, v87, v43, v41 op_sel:[0,1,0] op_sel_hi:[0,1,0]
	v_cndmask_b32_e64 v189, v41, v40, s[38:39]
	v_cndmask_b32_e64 v190, v40, v41, s[38:39]
	s_waitcnt lgkmcnt(0)
	v_fma_mix_f32 v98, v84, v6, 0 op_sel:[0,0,0] op_sel_hi:[0,1,0]
	v_fma_mix_f32 v98, v85, v6, v98 op_sel:[0,1,0] op_sel_hi:[0,1,0]
	v_add_f32_dpp v188, v188, v187 quad_perm:[1,0,3,2] row_mask:0xf bank_mask:0xf bound_ctrl:1
	v_add_f32_dpp v189, v190, v189 quad_perm:[1,0,3,2] row_mask:0xf bank_mask:0xf bound_ctrl:1
	v_fma_mix_f32 v98, v86, v7, v98 op_sel:[0,0,0] op_sel_hi:[0,1,0]
	v_fma_mix_f32 v98, v87, v7, v98 op_sel:[0,1,0] op_sel_hi:[0,1,0]
	v_cndmask_b32_e64 v191, v189, v188, s[40:41]
	v_cndmask_b32_e64 v192, v188, v189, s[40:41]
	v_fma_mix_f32 v100, v88, v14, 0 op_sel:[0,0,0] op_sel_hi:[1,1,0]
	v_fma_mix_f32 v101, v88, v14, 0 op_sel:[0,1,0] op_sel_hi:[1,1,0]
	v_add_f32_dpp v192, v192, v191 quad_perm:[2,3,0,1] row_mask:0xf bank_mask:0xf bound_ctrl:1
	v_add_f32_dpp v98, v98, v98 quad_perm:[1,0,3,2] row_mask:0xf bank_mask:0xf bound_ctrl:1
	v_fma_mix_f32 v102, v88, v15, 0 op_sel:[0,0,0] op_sel_hi:[1,1,0]
	v_add_f32_dpp v192, v192, v192 row_ror:4 row_mask:0xf bank_mask:0xf bound_ctrl:1
	v_fma_mix_f32 v103, v88, v15, 0 op_sel:[0,1,0] op_sel_hi:[1,1,0]
	v_add_f32_dpp v98, v98, v98 quad_perm:[2,3,0,1] row_mask:0xf bank_mask:0xf bound_ctrl:1
	v_add_f32_dpp v192, v192, v192 row_ror:8 row_mask:0xf bank_mask:0xf bound_ctrl:1
	v_cvt_f16_f32_e32 v192, v192
	global_store_short v83, v192, s[36:37]
	s_add_u32 s36, s36, s44
	s_addc_u32 s37, s37, s45
	global_load_ushort v198, v83, s[22:23]
	s_add_u32 s22, s22, s44
	s_addc_u32 s23, s23, s45
	ds_read_b128 v[56:59], v194 offset:35840
	ds_read_b128 v[72:75], v194 offset:33792
	ds_read_b128 v[64:67], v194 offset:34048
	ds_read_b128 v[76:79], v194 offset:34816
	ds_read_b128 v[68:71], v194 offset:35072
	ds_read_b128 v[40:43], v194 offset:36096
	ds_read_b128 v[52:55], v194 offset:34304
	ds_read_b128 v[44:47], v194 offset:34560
	ds_read_b128 v[60:63], v194 offset:35328
	ds_read_b128 v[48:51], v194 offset:35584
	s_waitcnt vmcnt(12)
	v_mov_b32_dpp v92, v208 quad_perm:[0,0,0,0] row_mask:0xf bank_mask:0xf
	v_mov_b32_dpp v93, v208 quad_perm:[1,1,1,1] row_mask:0xf bank_mask:0xf
	v_mov_b32_dpp v94, v208 quad_perm:[2,2,2,2] row_mask:0xf bank_mask:0xf
	v_mov_b32_dpp v95, v208 quad_perm:[3,3,3,3] row_mask:0xf bank_mask:0xf
	v_fma_mix_f32 v84, v84, v4, v100 op_sel:[0,0,0] op_sel_hi:[0,1,0]
	v_fma_mix_f32 v85, v85, v4, v101 op_sel:[0,1,0] op_sel_hi:[0,1,0]
	v_add_f32_dpp v98, v98, v98 row_half_mirror row_mask:0xf bank_mask:0xf bound_ctrl:1
	v_fma_mix_f32 v86, v86, v5, v102 op_sel:[0,0,0] op_sel_hi:[0,1,0]
	v_fma_mix_f32 v87, v87, v5, v103 op_sel:[0,1,0] op_sel_hi:[0,1,0]
	v_add_f32_dpp v98, v98, v98 row_mirror row_mask:0xf bank_mask:0xf bound_ctrl:1
	v_fma_mix_f32 v84, -v98, v12, v84 op_sel:[0,0,0] op_sel_hi:[0,1,0]
	v_fma_mix_f32 v85, -v98, v12, v85 op_sel:[0,1,0] op_sel_hi:[0,1,0]
	v_fma_mix_f32 v86, -v98, v13, v86 op_sel:[0,0,0] op_sel_hi:[0,1,0]
	v_fma_mix_f32 v87, -v98, v13, v87 op_sel:[0,1,0] op_sel_hi:[0,1,0]
	v_fma_mix_f32 v99, v84, v10, 0 op_sel:[0,0,0] op_sel_hi:[0,1,0]
	v_fma_mix_f32 v96, v84, v0, 0 op_sel:[0,0,0] op_sel_hi:[0,1,0]
	v_fma_mix_f32 v99, v85, v10, v99 op_sel:[0,1,0] op_sel_hi:[0,1,0]
	v_fma_mix_f32 v96, v85, v0, v96 op_sel:[0,1,0] op_sel_hi:[0,1,0]
	v_fma_mix_f32 v99, v86, v11, v99 op_sel:[0,0,0] op_sel_hi:[0,1,0]
	v_fma_mix_f32 v96, v86, v1, v96 op_sel:[0,0,0] op_sel_hi:[0,1,0]
	v_fma_mix_f32 v99, v87, v11, v99 op_sel:[0,1,0] op_sel_hi:[0,1,0]
	v_fma_mix_f32 v96, v87, v1, v96 op_sel:[0,1,0] op_sel_hi:[0,1,0]
	v_fma_mix_f32 v101, v89, v18, 0 op_sel:[0,0,0] op_sel_hi:[1,1,0]
	v_fma_mix_f32 v102, v89, v18, 0 op_sel:[0,1,0] op_sel_hi:[1,1,0]
	v_add_f32_dpp v99, v99, v99 quad_perm:[1,0,3,2] row_mask:0xf bank_mask:0xf bound_ctrl:1
	v_fma_mix_f32 v103, v89, v19, 0 op_sel:[0,0,0] op_sel_hi:[1,1,0]
	v_fma_mix_f32 v104, v89, v19, 0 op_sel:[0,1,0] op_sel_hi:[1,1,0]
	v_add_f32_dpp v99, v99, v99 quad_perm:[2,3,0,1] row_mask:0xf bank_mask:0xf bound_ctrl:1
	v_fma_mix_f32 v84, v84, v8, v101 op_sel:[0,0,0] op_sel_hi:[0,1,0]
	v_fma_mix_f32 v85, v85, v8, v102 op_sel:[0,1,0] op_sel_hi:[0,1,0]
	v_add_f32_dpp v99, v99, v99 row_half_mirror row_mask:0xf bank_mask:0xf bound_ctrl:1
	v_fma_mix_f32 v86, v86, v9, v103 op_sel:[0,0,0] op_sel_hi:[0,1,0]
	v_fma_mix_f32 v87, v87, v9, v104 op_sel:[0,1,0] op_sel_hi:[0,1,0]
	v_add_f32_dpp v99, v99, v99 row_mirror row_mask:0xf bank_mask:0xf bound_ctrl:1
	v_fma_mix_f32 v84, -v99, v16, v84 op_sel:[0,0,0] op_sel_hi:[0,1,0]
	v_fma_mix_f32 v85, -v99, v16, v85 op_sel:[0,1,0] op_sel_hi:[0,1,0]
	v_fma_mix_f32 v86, -v99, v17, v86 op_sel:[0,0,0] op_sel_hi:[0,1,0]
	v_fma_mix_f32 v87, -v99, v17, v87 op_sel:[0,1,0] op_sel_hi:[0,1,0]
	v_fma_mix_f32 v100, v84, v26, 0 op_sel:[0,0,0] op_sel_hi:[0,1,0]
	v_fma_mix_f32 v97, v84, v2, 0 op_sel:[0,0,0] op_sel_hi:[0,1,0]
	v_fma_mix_f32 v100, v85, v26, v100 op_sel:[0,1,0] op_sel_hi:[0,1,0]
	v_fma_mix_f32 v97, v85, v2, v97 op_sel:[0,1,0] op_sel_hi:[0,1,0]
	v_fma_mix_f32 v100, v86, v27, v100 op_sel:[0,0,0] op_sel_hi:[0,1,0]
	v_fma_mix_f32 v97, v86, v3, v97 op_sel:[0,0,0] op_sel_hi:[0,1,0]
	v_fma_mix_f32 v100, v87, v27, v100 op_sel:[0,1,0] op_sel_hi:[0,1,0]
	v_fma_mix_f32 v97, v87, v3, v97 op_sel:[0,1,0] op_sel_hi:[0,1,0]
	v_fma_mix_f32 v102, v90, v34, 0 op_sel:[0,0,0] op_sel_hi:[1,1,0]
	v_fma_mix_f32 v103, v90, v34, 0 op_sel:[0,1,0] op_sel_hi:[1,1,0]
	v_add_f32_dpp v100, v100, v100 quad_perm:[1,0,3,2] row_mask:0xf bank_mask:0xf bound_ctrl:1
	v_fma_mix_f32 v104, v90, v35, 0 op_sel:[0,0,0] op_sel_hi:[1,1,0]
	v_fma_mix_f32 v105, v90, v35, 0 op_sel:[0,1,0] op_sel_hi:[1,1,0]
	v_add_f32_dpp v100, v100, v100 quad_perm:[2,3,0,1] row_mask:0xf bank_mask:0xf bound_ctrl:1
	v_fma_mix_f32 v84, v84, v24, v102 op_sel:[0,0,0] op_sel_hi:[0,1,0]
	v_fma_mix_f32 v85, v85, v24, v103 op_sel:[0,1,0] op_sel_hi:[0,1,0]
	v_add_f32_dpp v100, v100, v100 row_half_mirror row_mask:0xf bank_mask:0xf bound_ctrl:1
	v_fma_mix_f32 v86, v86, v25, v104 op_sel:[0,0,0] op_sel_hi:[0,1,0]
	v_fma_mix_f32 v87, v87, v25, v105 op_sel:[0,1,0] op_sel_hi:[0,1,0]
	v_add_f32_dpp v100, v100, v100 row_mirror row_mask:0xf bank_mask:0xf bound_ctrl:1
	v_fma_mix_f32 v84, -v100, v32, v84 op_sel:[0,0,0] op_sel_hi:[0,1,0]
	v_fma_mix_f32 v85, -v100, v32, v85 op_sel:[0,1,0] op_sel_hi:[0,1,0]
	v_fma_mix_f32 v86, -v100, v33, v86 op_sel:[0,0,0] op_sel_hi:[0,1,0]
	v_fma_mix_f32 v87, -v100, v33, v87 op_sel:[0,1,0] op_sel_hi:[0,1,0]
	v_fma_mix_f32 v101, v84, v30, 0 op_sel:[0,0,0] op_sel_hi:[0,1,0]
	v_fma_mix_f32 v98, v84, v20, 0 op_sel:[0,0,0] op_sel_hi:[0,1,0]
	v_fma_mix_f32 v101, v85, v30, v101 op_sel:[0,1,0] op_sel_hi:[0,1,0]
	v_fma_mix_f32 v98, v85, v20, v98 op_sel:[0,1,0] op_sel_hi:[0,1,0]
	v_fma_mix_f32 v101, v86, v31, v101 op_sel:[0,0,0] op_sel_hi:[0,1,0]
	v_fma_mix_f32 v98, v86, v21, v98 op_sel:[0,0,0] op_sel_hi:[0,1,0]
	v_fma_mix_f32 v101, v87, v31, v101 op_sel:[0,1,0] op_sel_hi:[0,1,0]
	v_fma_mix_f32 v98, v87, v21, v98 op_sel:[0,1,0] op_sel_hi:[0,1,0]
	v_fma_mix_f32 v103, v91, v38, 0 op_sel:[0,0,0] op_sel_hi:[1,1,0]
	v_fma_mix_f32 v104, v91, v38, 0 op_sel:[0,1,0] op_sel_hi:[1,1,0]
	v_add_f32_dpp v101, v101, v101 quad_perm:[1,0,3,2] row_mask:0xf bank_mask:0xf bound_ctrl:1
	v_fma_mix_f32 v105, v91, v39, 0 op_sel:[0,0,0] op_sel_hi:[1,1,0]
	v_fma_mix_f32 v119, v91, v39, 0 op_sel:[0,1,0] op_sel_hi:[1,1,0]
	v_add_f32_dpp v101, v101, v101 quad_perm:[2,3,0,1] row_mask:0xf bank_mask:0xf bound_ctrl:1
	v_fma_mix_f32 v84, v84, v28, v103 op_sel:[0,0,0] op_sel_hi:[0,1,0]
	v_fma_mix_f32 v85, v85, v28, v104 op_sel:[0,1,0] op_sel_hi:[0,1,0]
	v_add_f32_dpp v101, v101, v101 row_half_mirror row_mask:0xf bank_mask:0xf bound_ctrl:1
	v_fma_mix_f32 v86, v86, v29, v105 op_sel:[0,0,0] op_sel_hi:[0,1,0]
	v_fma_mix_f32 v87, v87, v29, v119 op_sel:[0,1,0] op_sel_hi:[0,1,0]
	v_add_f32_dpp v101, v101, v101 row_mirror row_mask:0xf bank_mask:0xf bound_ctrl:1
	v_fma_mix_f32 v84, -v101, v36, v84 op_sel:[0,0,0] op_sel_hi:[0,1,0]
	v_fma_mix_f32 v85, -v101, v36, v85 op_sel:[0,1,0] op_sel_hi:[0,1,0]
	v_fma_mix_f32 v86, -v101, v37, v86 op_sel:[0,0,0] op_sel_hi:[0,1,0]
	v_fma_mix_f32 v87, -v101, v37, v87 op_sel:[0,1,0] op_sel_hi:[0,1,0]
	v_fma_mix_f32 v99, v84, v22, 0 op_sel:[0,0,0] op_sel_hi:[0,1,0]
	v_cndmask_b32_e64 v187, v97, v96, s[38:39]
	v_fma_mix_f32 v99, v85, v22, v99 op_sel:[0,1,0] op_sel_hi:[0,1,0]
	v_cndmask_b32_e64 v188, v96, v97, s[38:39]
	v_fma_mix_f32 v99, v86, v23, v99 op_sel:[0,0,0] op_sel_hi:[0,1,0]
	v_fma_mix_f32 v99, v87, v23, v99 op_sel:[0,1,0] op_sel_hi:[0,1,0]
	v_cndmask_b32_e64 v189, v99, v98, s[38:39]
	v_cndmask_b32_e64 v190, v98, v99, s[38:39]
	s_waitcnt lgkmcnt(0)
	v_fma_mix_f32 v98, v84, v74, 0 op_sel:[0,0,0] op_sel_hi:[0,1,0]
	v_fma_mix_f32 v98, v85, v74, v98 op_sel:[0,1,0] op_sel_hi:[0,1,0]
	v_add_f32_dpp v188, v188, v187 quad_perm:[1,0,3,2] row_mask:0xf bank_mask:0xf bound_ctrl:1
	v_add_f32_dpp v189, v190, v189 quad_perm:[1,0,3,2] row_mask:0xf bank_mask:0xf bound_ctrl:1
	v_fma_mix_f32 v98, v86, v75, v98 op_sel:[0,0,0] op_sel_hi:[0,1,0]
	v_fma_mix_f32 v98, v87, v75, v98 op_sel:[0,1,0] op_sel_hi:[0,1,0]
	v_cndmask_b32_e64 v191, v189, v188, s[40:41]
	v_cndmask_b32_e64 v192, v188, v189, s[40:41]
	v_fma_mix_f32 v100, v92, v78, 0 op_sel:[0,0,0] op_sel_hi:[1,1,0]
	v_fma_mix_f32 v101, v92, v78, 0 op_sel:[0,1,0] op_sel_hi:[1,1,0]
	v_add_f32_dpp v192, v192, v191 quad_perm:[2,3,0,1] row_mask:0xf bank_mask:0xf bound_ctrl:1
	v_add_f32_dpp v98, v98, v98 quad_perm:[1,0,3,2] row_mask:0xf bank_mask:0xf bound_ctrl:1
	v_fma_mix_f32 v102, v92, v79, 0 op_sel:[0,0,0] op_sel_hi:[1,1,0]
	v_add_f32_dpp v192, v192, v192 row_ror:4 row_mask:0xf bank_mask:0xf bound_ctrl:1
	v_fma_mix_f32 v103, v92, v79, 0 op_sel:[0,1,0] op_sel_hi:[1,1,0]
	v_add_f32_dpp v98, v98, v98 quad_perm:[2,3,0,1] row_mask:0xf bank_mask:0xf bound_ctrl:1
	v_add_f32_dpp v192, v192, v192 row_ror:8 row_mask:0xf bank_mask:0xf bound_ctrl:1
	v_cvt_f16_f32_e32 v192, v192
	global_store_short v83, v192, s[36:37]
	s_add_u32 s36, s36, s44
	s_addc_u32 s37, s37, s45
	global_load_ushort v199, v83, s[22:23]
	s_add_u32 s22, s22, s44
	s_addc_u32 s23, s23, s45
	s_cmp_gt_i32 s35, 13
	s_cbranch_scc0 .Lc_poll_A5
.Lc_ret_A5:
	ds_read_b128 v[0:3], v194 offset:38912
	ds_read_b128 v[4:7], v194 offset:36864
	ds_read_b128 v[8:11], v194 offset:37120
	ds_read_b128 v[12:15], v194 offset:37888
	ds_read_b128 v[16:19], v194 offset:38144
	ds_read_b128 v[20:23], v194 offset:39168
	ds_read_b128 v[24:27], v194 offset:37376
	ds_read_b128 v[28:31], v194 offset:37632
	ds_read_b128 v[32:35], v194 offset:38400
	ds_read_b128 v[36:39], v194 offset:38656
	s_waitcnt vmcnt(12)
	v_mov_b32_dpp v88, v209 quad_perm:[0,0,0,0] row_mask:0xf bank_mask:0xf
	v_mov_b32_dpp v89, v209 quad_perm:[1,1,1,1] row_mask:0xf bank_mask:0xf
	v_mov_b32_dpp v90, v209 quad_perm:[2,2,2,2] row_mask:0xf bank_mask:0xf
	v_mov_b32_dpp v91, v209 quad_perm:[3,3,3,3] row_mask:0xf bank_mask:0xf
	v_fma_mix_f32 v84, v84, v72, v100 op_sel:[0,0,0] op_sel_hi:[0,1,0]
	v_fma_mix_f32 v85, v85, v72, v101 op_sel:[0,1,0] op_sel_hi:[0,1,0]
	v_add_f32_dpp v98, v98, v98 row_half_mirror row_mask:0xf bank_mask:0xf bound_ctrl:1
	v_fma_mix_f32 v86, v86, v73, v102 op_sel:[0,0,0] op_sel_hi:[0,1,0]
	v_fma_mix_f32 v87, v87, v73, v103 op_sel:[0,1,0] op_sel_hi:[0,1,0]
	v_add_f32_dpp v98, v98, v98 row_mirror row_mask:0xf bank_mask:0xf bound_ctrl:1
	v_fma_mix_f32 v84, -v98, v76, v84 op_sel:[0,0,0] op_sel_hi:[0,1,0]
	v_fma_mix_f32 v85, -v98, v76, v85 op_sel:[0,1,0] op_sel_hi:[0,1,0]
	v_fma_mix_f32 v86, -v98, v77, v86 op_sel:[0,0,0] op_sel_hi:[0,1,0]
	v_fma_mix_f32 v87, -v98, v77, v87 op_sel:[0,1,0] op_sel_hi:[0,1,0]
	v_fma_mix_f32 v73, v84, v66, 0 op_sel:[0,0,0] op_sel_hi:[0,1,0]
	v_fma_mix_f32 v97, v84, v56, 0 op_sel:[0,0,0] op_sel_hi:[0,1,0]
	v_fma_mix_f32 v73, v85, v66, v73 op_sel:[0,1,0] op_sel_hi:[0,1,0]
	v_fma_mix_f32 v56, v85, v56, v97 op_sel:[0,1,0] op_sel_hi:[0,1,0]
	v_fma_mix_f32 v73, v86, v67, v73 op_sel:[0,0,0] op_sel_hi:[0,1,0]
	v_fma_mix_f32 v56, v86, v57, v56 op_sel:[0,0,0] op_sel_hi:[0,1,0]
	v_fma_mix_f32 v73, v87, v67, v73 op_sel:[0,1,0] op_sel_hi:[0,1,0]
	v_fma_mix_f32 v56, v87, v57, v56 op_sel:[0,1,0] op_sel_hi:[0,1,0]
	v_fma_mix_f32 v75, v93, v70, 0 op_sel:[0,0,0] op_sel_hi:[1,1,0]
	v_fma_mix_f32 v76, v93, v70, 0 op_sel:[0,1,0] op_sel_hi:[1,1,0]
	v_add_f32_dpp v73, v73, v73 quad_perm:[1,0,3,2] row_mask:0xf bank_mask:0xf bound_ctrl:1
	v_fma_mix_f32 v77, v93, v71, 0 op_sel:[0,0,0] op_sel_hi:[1,1,0]
	v_fma_mix_f32 v78, v93, v71, 0 op_sel:[0,1,0] op_sel_hi:[1,1,0]
	v_add_f32_dpp v73, v73, v73 quad_perm:[2,3,0,1] row_mask:0xf bank_mask:0xf bound_ctrl:1
	v_fma_mix_f32 v84, v84, v64, v75 op_sel:[0,0,0] op_sel_hi:[0,1,0]
	v_fma_mix_f32 v85, v85, v64, v76 op_sel:[0,1,0] op_sel_hi:[0,1,0]
	v_add_f32_dpp v73, v73, v73 row_half_mirror row_mask:0xf bank_mask:0xf bound_ctrl:1
	v_fma_mix_f32 v86, v86, v65, v77 op_sel:[0,0,0] op_sel_hi:[0,1,0]
	v_fma_mix_f32 v87, v87, v65, v78 op_sel:[0,1,0] op_sel_hi:[0,1,0]
	v_add_f32_dpp v73, v73, v73 row_mirror row_mask:0xf bank_mask:0xf bound_ctrl:1
	v_fma_mix_f32 v84, -v73, v68, v84 op_sel:[0,0,0] op_sel_hi:[0,1,0]
	v_fma_mix_f32 v85, -v73, v68, v85 op_sel:[0,1,0] op_sel_hi:[0,1,0]
	v_fma_mix_f32 v86, -v73, v69, v86 op_sel:[0,0,0] op_sel_hi:[0,1,0]
	v_fma_mix_f32 v87, -v73, v69, v87 op_sel:[0,1,0] op_sel_hi:[0,1,0]
	v_fma_mix_f32 v64, v84, v54, 0 op_sel:[0,0,0] op_sel_hi:[0,1,0]
	v_fma_mix_f32 v57, v84, v58, 0 op_sel:[0,0,0] op_sel_hi:[0,1,0]
	v_fma_mix_f32 v64, v85, v54, v64 op_sel:[0,1,0] op_sel_hi:[0,1,0]
	v_fma_mix_f32 v57, v85, v58, v57 op_sel:[0,1,0] op_sel_hi:[0,1,0]
	v_fma_mix_f32 v64, v86, v55, v64 op_sel:[0,0,0] op_sel_hi:[0,1,0]
	v_fma_mix_f32 v57, v86, v59, v57 op_sel:[0,0,0] op_sel_hi:[0,1,0]
	v_fma_mix_f32 v64, v87, v55, v64 op_sel:[0,1,0] op_sel_hi:[0,1,0]
	v_fma_mix_f32 v57, v87, v59, v57 op_sel:[0,1,0] op_sel_hi:[0,1,0]
	v_fma_mix_f32 v66, v94, v62, 0 op_sel:[0,0,0] op_sel_hi:[1,1,0]
	v_fma_mix_f32 v67, v94, v62, 0 op_sel:[0,1,0] op_sel_hi:[1,1,0]
	v_add_f32_dpp v64, v64, v64 quad_perm:[1,0,3,2] row_mask:0xf bank_mask:0xf bound_ctrl:1
	v_fma_mix_f32 v68, v94, v63, 0 op_sel:[0,0,0] op_sel_hi:[1,1,0]
	v_fma_mix_f32 v69, v94, v63, 0 op_sel:[0,1,0] op_sel_hi:[1,1,0]
	v_add_f32_dpp v64, v64, v64 quad_perm:[2,3,0,1] row_mask:0xf bank_mask:0xf bound_ctrl:1
	v_fma_mix_f32 v84, v84, v52, v66 op_sel:[0,0,0] op_sel_hi:[0,1,0]
	v_fma_mix_f32 v85, v85, v52, v67 op_sel:[0,1,0] op_sel_hi:[0,1,0]
	v_add_f32_dpp v64, v64, v64 row_half_mirror row_mask:0xf bank_mask:0xf bound_ctrl:1
	v_fma_mix_f32 v86, v86, v53, v68 op_sel:[0,0,0] op_sel_hi:[0,1,0]
	v_fma_mix_f32 v87, v87, v53, v69 op_sel:[0,1,0] op_sel_hi:[0,1,0]
	v_add_f32_dpp v64, v64, v64 row_mirror row_mask:0xf bank_mask:0xf bound_ctrl:1
	v_fma_mix_f32 v84, -v64, v60, v84 op_sel:[0,0,0] op_sel_hi:[0,1,0]
	v_fma_mix_f32 v85, -v64, v60, v85 op_sel:[0,1,0] op_sel_hi:[0,1,0]
	v_fma_mix_f32 v86, -v64, v61, v86 op_sel:[0,0,0] op_sel_hi:[0,1,0]
	v_fma_mix_f32 v87, -v64, v61, v87 op_sel:[0,1,0] op_sel_hi:[0,1,0]
	v_fma_mix_f32 v53, v84, v46, 0 op_sel:[0,0,0] op_sel_hi:[0,1,0]
	v_fma_mix_f32 v59, v84, v40, 0 op_sel:[0,0,0] op_sel_hi:[0,1,0]
	v_fma_mix_f32 v53, v85, v46, v53 op_sel:[0,1,0] op_sel_hi:[0,1,0]
	v_fma_mix_f32 v40, v85, v40, v59 op_sel:[0,1,0] op_sel_hi:[0,1,0]
	v_fma_mix_f32 v53, v86, v47, v53 op_sel:[0,0,0] op_sel_hi:[0,1,0]
	v_fma_mix_f32 v40, v86, v41, v40 op_sel:[0,0,0] op_sel_hi:[0,1,0]
	v_fma_mix_f32 v53, v87, v47, v53 op_sel:[0,1,0] op_sel_hi:[0,1,0]
	v_fma_mix_f32 v40, v87, v41, v40 op_sel:[0,1,0] op_sel_hi:[0,1,0]
	v_fma_mix_f32 v55, v95, v50, 0 op_sel:[0,0,0] op_sel_hi:[1,1,0]
	v_fma_mix_f32 v58, v95, v50, 0 op_sel:[0,1,0] op_sel_hi:[1,1,0]
	v_add_f32_dpp v53, v53, v53 quad_perm:[1,0,3,2] row_mask:0xf bank_mask:0xf bound_ctrl:1
	v_fma_mix_f32 v59, v95, v51, 0 op_sel:[0,0,0] op_sel_hi:[1,1,0]
	v_fma_mix_f32 v60, v95, v51, 0 op_sel:[0,1,0] op_sel_hi:[1,1,0]
	v_add_f32_dpp v53, v53, v53 quad_perm:[2,3,0,1] row_mask:0xf bank_mask:0xf bound_ctrl:1
	v_fma_mix_f32 v84, v84, v44, v55 op_sel:[0,0,0] op_sel_hi:[0,1,0]
	v_fma_mix_f32 v85, v85, v44, v58 op_sel:[0,1,0] op_sel_hi:[0,1,0]
	v_add_f32_dpp v53, v53, v53 row_half_mirror row_mask:0xf bank_mask:0xf bound_ctrl:1
	v_fma_mix_f32 v86, v86, v45, v59 op_sel:[0,0,0] op_sel_hi:[0,1,0]
	v_fma_mix_f32 v87, v87, v45, v60 op_sel:[0,1,0] op_sel_hi:[0,1,0]
	v_add_f32_dpp v53, v53, v53 row_mirror row_mask:0xf bank_mask:0xf bound_ctrl:1
	v_fma_mix_f32 v84, -v53, v48, v84 op_sel:[0,0,0] op_sel_hi:[0,1,0]
	v_fma_mix_f32 v85, -v53, v48, v85 op_sel:[0,1,0] op_sel_hi:[0,1,0]
	v_fma_mix_f32 v86, -v53, v49, v86 op_sel:[0,0,0] op_sel_hi:[0,1,0]
	v_fma_mix_f32 v87, -v53, v49, v87 op_sel:[0,1,0] op_sel_hi:[0,1,0]
	v_fma_mix_f32 v41, v84, v42, 0 op_sel:[0,0,0] op_sel_hi:[0,1,0]
	v_add_u32_e32 v173, 12, v193
	v_fma_mix_f32 v41, v85, v42, v41 op_sel:[0,1,0] op_sel_hi:[0,1,0]
	ds_write_b32 v172, v173 offset:49216
	v_fma_mix_f32 v41, v86, v43, v41 op_sel:[0,0,0] op_sel_hi:[0,1,0]
	v_cndmask_b32_e64 v187, v57, v56, s[38:39]
	v_fma_mix_f32 v41, v87, v43, v41 op_sel:[0,1,0] op_sel_hi:[0,1,0]
	v_cndmask_b32_e64 v188, v56, v57, s[38:39]
	v_cndmask_b32_e64 v189, v41, v40, s[38:39]
	v_cndmask_b32_e64 v190, v40, v41, s[38:39]
	s_waitcnt lgkmcnt(1)
	v_fma_mix_f32 v98, v84, v6, 0 op_sel:[0,0,0] op_sel_hi:[0,1,0]
	v_fma_mix_f32 v98, v85, v6, v98 op_sel:[0,1,0] op_sel_hi:[0,1,0]
	v_add_f32_dpp v188, v188, v187 quad_perm:[1,0,3,2] row_mask:0xf bank_mask:0xf bound_ctrl:1
	v_add_f32_dpp v189, v190, v189 quad_perm:[1,0,3,2] row_mask:0xf bank_mask:0xf bound_ctrl:1
	v_fma_mix_f32 v98, v86, v7, v98 op_sel:[0,0,0] op_sel_hi:[0,1,0]
	v_fma_mix_f32 v98, v87, v7, v98 op_sel:[0,1,0] op_sel_hi:[0,1,0]
	v_cndmask_b32_e64 v191, v189, v188, s[40:41]
	v_cndmask_b32_e64 v192, v188, v189, s[40:41]
	v_fma_mix_f32 v100, v88, v14, 0 op_sel:[0,0,0] op_sel_hi:[1,1,0]
	v_fma_mix_f32 v101, v88, v14, 0 op_sel:[0,1,0] op_sel_hi:[1,1,0]
	v_add_f32_dpp v192, v192, v191 quad_perm:[2,3,0,1] row_mask:0xf bank_mask:0xf bound_ctrl:1
	v_add_f32_dpp v98, v98, v98 quad_perm:[1,0,3,2] row_mask:0xf bank_mask:0xf bound_ctrl:1
	v_fma_mix_f32 v102, v88, v15, 0 op_sel:[0,0,0] op_sel_hi:[1,1,0]
	v_add_f32_dpp v192, v192, v192 row_ror:4 row_mask:0xf bank_mask:0xf bound_ctrl:1
	v_fma_mix_f32 v103, v88, v15, 0 op_sel:[0,1,0] op_sel_hi:[1,1,0]
	v_add_f32_dpp v98, v98, v98 quad_perm:[2,3,0,1] row_mask:0xf bank_mask:0xf bound_ctrl:1
	v_add_f32_dpp v192, v192, v192 row_ror:8 row_mask:0xf bank_mask:0xf bound_ctrl:1
	v_cvt_f16_f32_e32 v192, v192
	global_store_short v83, v192, s[36:37]
	s_add_u32 s36, s36, s44
	s_addc_u32 s37, s37, s45
	global_load_ushort v200, v83, s[22:23]
	s_add_u32 s22, s22, s44
	s_addc_u32 s23, s23, s45
	ds_read_b128 v[56:59], v194 offset:41984
	ds_read_b128 v[72:75], v194 offset:39936
	ds_read_b128 v[64:67], v194 offset:40192
	ds_read_b128 v[76:79], v194 offset:40960
	ds_read_b128 v[68:71], v194 offset:41216
	ds_read_b128 v[40:43], v194 offset:42240
	ds_read_b128 v[52:55], v194 offset:40448
	ds_read_b128 v[44:47], v194 offset:40704
	ds_read_b128 v[60:63], v194 offset:41472
	ds_read_b128 v[48:51], v194 offset:41728
	s_waitcnt vmcnt(12)
	v_mov_b32_dpp v92, v210 quad_perm:[0,0,0,0] row_mask:0xf bank_mask:0xf
	v_mov_b32_dpp v93, v210 quad_perm:[1,1,1,1] row_mask:0xf bank_mask:0xf
	v_mov_b32_dpp v94, v210 quad_perm:[2,2,2,2] row_mask:0xf bank_mask:0xf
	v_mov_b32_dpp v95, v210 quad_perm:[3,3,3,3] row_mask:0xf bank_mask:0xf
	v_fma_mix_f32 v84, v84, v4, v100 op_sel:[0,0,0] op_sel_hi:[0,1,0]
	v_fma_mix_f32 v85, v85, v4, v101 op_sel:[0,1,0] op_sel_hi:[0,1,0]
	v_add_f32_dpp v98, v98, v98 row_half_mirror row_mask:0xf bank_mask:0xf bound_ctrl:1
	v_fma_mix_f32 v86, v86, v5, v102 op_sel:[0,0,0] op_sel_hi:[0,1,0]
	v_fma_mix_f32 v87, v87, v5, v103 op_sel:[0,1,0] op_sel_hi:[0,1,0]
	v_add_f32_dpp v98, v98, v98 row_mirror row_mask:0xf bank_mask:0xf bound_ctrl:1
	v_fma_mix_f32 v84, -v98, v12, v84 op_sel:[0,0,0] op_sel_hi:[0,1,0]
	v_fma_mix_f32 v85, -v98, v12, v85 op_sel:[0,1,0] op_sel_hi:[0,1,0]
	v_fma_mix_f32 v86, -v98, v13, v86 op_sel:[0,0,0] op_sel_hi:[0,1,0]
	v_fma_mix_f32 v87, -v98, v13, v87 op_sel:[0,1,0] op_sel_hi:[0,1,0]
	v_fma_mix_f32 v99, v84, v10, 0 op_sel:[0,0,0] op_sel_hi:[0,1,0]
	v_fma_mix_f32 v96, v84, v0, 0 op_sel:[0,0,0] op_sel_hi:[0,1,0]
	v_fma_mix_f32 v99, v85, v10, v99 op_sel:[0,1,0] op_sel_hi:[0,1,0]
	v_fma_mix_f32 v96, v85, v0, v96 op_sel:[0,1,0] op_sel_hi:[0,1,0]
	v_fma_mix_f32 v99, v86, v11, v99 op_sel:[0,0,0] op_sel_hi:[0,1,0]
	v_fma_mix_f32 v96, v86, v1, v96 op_sel:[0,0,0] op_sel_hi:[0,1,0]
	v_fma_mix_f32 v99, v87, v11, v99 op_sel:[0,1,0] op_sel_hi:[0,1,0]
	v_fma_mix_f32 v96, v87, v1, v96 op_sel:[0,1,0] op_sel_hi:[0,1,0]
	v_fma_mix_f32 v101, v89, v18, 0 op_sel:[0,0,0] op_sel_hi:[1,1,0]
	v_fma_mix_f32 v102, v89, v18, 0 op_sel:[0,1,0] op_sel_hi:[1,1,0]
	v_add_f32_dpp v99, v99, v99 quad_perm:[1,0,3,2] row_mask:0xf bank_mask:0xf bound_ctrl:1
	v_fma_mix_f32 v103, v89, v19, 0 op_sel:[0,0,0] op_sel_hi:[1,1,0]
	v_fma_mix_f32 v104, v89, v19, 0 op_sel:[0,1,0] op_sel_hi:[1,1,0]
	v_add_f32_dpp v99, v99, v99 quad_perm:[2,3,0,1] row_mask:0xf bank_mask:0xf bound_ctrl:1
	v_fma_mix_f32 v84, v84, v8, v101 op_sel:[0,0,0] op_sel_hi:[0,1,0]
	v_fma_mix_f32 v85, v85, v8, v102 op_sel:[0,1,0] op_sel_hi:[0,1,0]
	v_add_f32_dpp v99, v99, v99 row_half_mirror row_mask:0xf bank_mask:0xf bound_ctrl:1
	v_fma_mix_f32 v86, v86, v9, v103 op_sel:[0,0,0] op_sel_hi:[0,1,0]
	v_fma_mix_f32 v87, v87, v9, v104 op_sel:[0,1,0] op_sel_hi:[0,1,0]
	v_add_f32_dpp v99, v99, v99 row_mirror row_mask:0xf bank_mask:0xf bound_ctrl:1
	v_fma_mix_f32 v84, -v99, v16, v84 op_sel:[0,0,0] op_sel_hi:[0,1,0]
	v_fma_mix_f32 v85, -v99, v16, v85 op_sel:[0,1,0] op_sel_hi:[0,1,0]
	v_fma_mix_f32 v86, -v99, v17, v86 op_sel:[0,0,0] op_sel_hi:[0,1,0]
	v_fma_mix_f32 v87, -v99, v17, v87 op_sel:[0,1,0] op_sel_hi:[0,1,0]
	v_fma_mix_f32 v100, v84, v26, 0 op_sel:[0,0,0] op_sel_hi:[0,1,0]
	v_fma_mix_f32 v97, v84, v2, 0 op_sel:[0,0,0] op_sel_hi:[0,1,0]
	v_fma_mix_f32 v100, v85, v26, v100 op_sel:[0,1,0] op_sel_hi:[0,1,0]
	v_fma_mix_f32 v97, v85, v2, v97 op_sel:[0,1,0] op_sel_hi:[0,1,0]
	v_fma_mix_f32 v100, v86, v27, v100 op_sel:[0,0,0] op_sel_hi:[0,1,0]
	v_fma_mix_f32 v97, v86, v3, v97 op_sel:[0,0,0] op_sel_hi:[0,1,0]
	v_fma_mix_f32 v100, v87, v27, v100 op_sel:[0,1,0] op_sel_hi:[0,1,0]
	v_fma_mix_f32 v97, v87, v3, v97 op_sel:[0,1,0] op_sel_hi:[0,1,0]
	v_fma_mix_f32 v102, v90, v34, 0 op_sel:[0,0,0] op_sel_hi:[1,1,0]
	v_fma_mix_f32 v103, v90, v34, 0 op_sel:[0,1,0] op_sel_hi:[1,1,0]
	v_add_f32_dpp v100, v100, v100 quad_perm:[1,0,3,2] row_mask:0xf bank_mask:0xf bound_ctrl:1
	v_fma_mix_f32 v104, v90, v35, 0 op_sel:[0,0,0] op_sel_hi:[1,1,0]
	v_fma_mix_f32 v105, v90, v35, 0 op_sel:[0,1,0] op_sel_hi:[1,1,0]
	v_add_f32_dpp v100, v100, v100 quad_perm:[2,3,0,1] row_mask:0xf bank_mask:0xf bound_ctrl:1
	v_fma_mix_f32 v84, v84, v24, v102 op_sel:[0,0,0] op_sel_hi:[0,1,0]
	v_fma_mix_f32 v85, v85, v24, v103 op_sel:[0,1,0] op_sel_hi:[0,1,0]
	v_add_f32_dpp v100, v100, v100 row_half_mirror row_mask:0xf bank_mask:0xf bound_ctrl:1
	v_fma_mix_f32 v86, v86, v25, v104 op_sel:[0,0,0] op_sel_hi:[0,1,0]
	v_fma_mix_f32 v87, v87, v25, v105 op_sel:[0,1,0] op_sel_hi:[0,1,0]
	v_add_f32_dpp v100, v100, v100 row_mirror row_mask:0xf bank_mask:0xf bound_ctrl:1
	v_fma_mix_f32 v84, -v100, v32, v84 op_sel:[0,0,0] op_sel_hi:[0,1,0]
	v_fma_mix_f32 v85, -v100, v32, v85 op_sel:[0,1,0] op_sel_hi:[0,1,0]
	v_fma_mix_f32 v86, -v100, v33, v86 op_sel:[0,0,0] op_sel_hi:[0,1,0]
	v_fma_mix_f32 v87, -v100, v33, v87 op_sel:[0,1,0] op_sel_hi:[0,1,0]
	v_fma_mix_f32 v101, v84, v30, 0 op_sel:[0,0,0] op_sel_hi:[0,1,0]
	v_fma_mix_f32 v98, v84, v20, 0 op_sel:[0,0,0] op_sel_hi:[0,1,0]
	v_fma_mix_f32 v101, v85, v30, v101 op_sel:[0,1,0] op_sel_hi:[0,1,0]
	v_fma_mix_f32 v98, v85, v20, v98 op_sel:[0,1,0] op_sel_hi:[0,1,0]
	v_fma_mix_f32 v101, v86, v31, v101 op_sel:[0,0,0] op_sel_hi:[0,1,0]
	v_fma_mix_f32 v98, v86, v21, v98 op_sel:[0,0,0] op_sel_hi:[0,1,0]
	v_fma_mix_f32 v101, v87, v31, v101 op_sel:[0,1,0] op_sel_hi:[0,1,0]
	v_fma_mix_f32 v98, v87, v21, v98 op_sel:[0,1,0] op_sel_hi:[0,1,0]
	v_fma_mix_f32 v103, v91, v38, 0 op_sel:[0,0,0] op_sel_hi:[1,1,0]
	v_fma_mix_f32 v104, v91, v38, 0 op_sel:[0,1,0] op_sel_hi:[1,1,0]
	v_add_f32_dpp v101, v101, v101 quad_perm:[1,0,3,2] row_mask:0xf bank_mask:0xf bound_ctrl:1
	v_fma_mix_f32 v105, v91, v39, 0 op_sel:[0,0,0] op_sel_hi:[1,1,0]
	v_fma_mix_f32 v119, v91, v39, 0 op_sel:[0,1,0] op_sel_hi:[1,1,0]
	v_add_f32_dpp v101, v101, v101 quad_perm:[2,3,0,1] row_mask:0xf bank_mask:0xf bound_ctrl:1
	v_fma_mix_f32 v84, v84, v28, v103 op_sel:[0,0,0] op_sel_hi:[0,1,0]
	v_fma_mix_f32 v85, v85, v28, v104 op_sel:[0,1,0] op_sel_hi:[0,1,0]
	v_add_f32_dpp v101, v101, v101 row_half_mirror row_mask:0xf bank_mask:0xf bound_ctrl:1
	v_fma_mix_f32 v86, v86, v29, v105 op_sel:[0,0,0] op_sel_hi:[0,1,0]
	v_fma_mix_f32 v87, v87, v29, v119 op_sel:[0,1,0] op_sel_hi:[0,1,0]
	v_add_f32_dpp v101, v101, v101 row_mirror row_mask:0xf bank_mask:0xf bound_ctrl:1
	v_fma_mix_f32 v84, -v101, v36, v84 op_sel:[0,0,0] op_sel_hi:[0,1,0]
	v_fma_mix_f32 v85, -v101, v36, v85 op_sel:[0,1,0] op_sel_hi:[0,1,0]
	v_fma_mix_f32 v86, -v101, v37, v86 op_sel:[0,0,0] op_sel_hi:[0,1,0]
	v_fma_mix_f32 v87, -v101, v37, v87 op_sel:[0,1,0] op_sel_hi:[0,1,0]
	v_fma_mix_f32 v99, v84, v22, 0 op_sel:[0,0,0] op_sel_hi:[0,1,0]
	v_cndmask_b32_e64 v187, v97, v96, s[38:39]
	v_fma_mix_f32 v99, v85, v22, v99 op_sel:[0,1,0] op_sel_hi:[0,1,0]
	v_cndmask_b32_e64 v188, v96, v97, s[38:39]
	v_fma_mix_f32 v99, v86, v23, v99 op_sel:[0,0,0] op_sel_hi:[0,1,0]
	v_fma_mix_f32 v99, v87, v23, v99 op_sel:[0,1,0] op_sel_hi:[0,1,0]
	v_cndmask_b32_e64 v189, v99, v98, s[38:39]
	v_cndmask_b32_e64 v190, v98, v99, s[38:39]
	s_waitcnt lgkmcnt(0)
	v_fma_mix_f32 v98, v84, v74, 0 op_sel:[0,0,0] op_sel_hi:[0,1,0]
	v_fma_mix_f32 v98, v85, v74, v98 op_sel:[0,1,0] op_sel_hi:[0,1,0]
	v_add_f32_dpp v188, v188, v187 quad_perm:[1,0,3,2] row_mask:0xf bank_mask:0xf bound_ctrl:1
	v_add_f32_dpp v189, v190, v189 quad_perm:[1,0,3,2] row_mask:0xf bank_mask:0xf bound_ctrl:1
	v_fma_mix_f32 v98, v86, v75, v98 op_sel:[0,0,0] op_sel_hi:[0,1,0]
	v_fma_mix_f32 v98, v87, v75, v98 op_sel:[0,1,0] op_sel_hi:[0,1,0]
	v_cndmask_b32_e64 v191, v189, v188, s[40:41]
	v_cndmask_b32_e64 v192, v188, v189, s[40:41]
	v_fma_mix_f32 v100, v92, v78, 0 op_sel:[0,0,0] op_sel_hi:[1,1,0]
	v_fma_mix_f32 v101, v92, v78, 0 op_sel:[0,1,0] op_sel_hi:[1,1,0]
	v_add_f32_dpp v192, v192, v191 quad_perm:[2,3,0,1] row_mask:0xf bank_mask:0xf bound_ctrl:1
	v_add_f32_dpp v98, v98, v98 quad_perm:[1,0,3,2] row_mask:0xf bank_mask:0xf bound_ctrl:1
	v_fma_mix_f32 v102, v92, v79, 0 op_sel:[0,0,0] op_sel_hi:[1,1,0]
	v_add_f32_dpp v192, v192, v192 row_ror:4 row_mask:0xf bank_mask:0xf bound_ctrl:1
	v_fma_mix_f32 v103, v92, v79, 0 op_sel:[0,1,0] op_sel_hi:[1,1,0]
	v_add_f32_dpp v98, v98, v98 quad_perm:[2,3,0,1] row_mask:0xf bank_mask:0xf bound_ctrl:1
	v_add_f32_dpp v192, v192, v192 row_ror:8 row_mask:0xf bank_mask:0xf bound_ctrl:1
	v_cvt_f16_f32_e32 v192, v192
	global_store_short v83, v192, s[36:37]
	s_add_u32 s36, s36, s44
	s_addc_u32 s37, s37, s45
	global_load_ushort v201, v83, s[22:23]
	s_add_u32 s22, s22, s44
	s_addc_u32 s23, s23, s45
	s_cmp_gt_i32 s35, 15
	s_cbranch_scc0 .Lc_poll_A6
.Lc_ret_A6:
	ds_read_b128 v[0:3], v194 offset:45056
	ds_read_b128 v[4:7], v194 offset:43008
	ds_read_b128 v[8:11], v194 offset:43264
	ds_read_b128 v[12:15], v194 offset:44032
	ds_read_b128 v[16:19], v194 offset:44288
	ds_read_b128 v[20:23], v194 offset:45312
	ds_read_b128 v[24:27], v194 offset:43520
	ds_read_b128 v[28:31], v194 offset:43776
	ds_read_b128 v[32:35], v194 offset:44544
	ds_read_b128 v[36:39], v194 offset:44800
	s_waitcnt vmcnt(12)
	v_mov_b32_dpp v88, v211 quad_perm:[0,0,0,0] row_mask:0xf bank_mask:0xf
	v_mov_b32_dpp v89, v211 quad_perm:[1,1,1,1] row_mask:0xf bank_mask:0xf
	v_mov_b32_dpp v90, v211 quad_perm:[2,2,2,2] row_mask:0xf bank_mask:0xf
	v_mov_b32_dpp v91, v211 quad_perm:[3,3,3,3] row_mask:0xf bank_mask:0xf
	v_fma_mix_f32 v84, v84, v72, v100 op_sel:[0,0,0] op_sel_hi:[0,1,0]
	v_fma_mix_f32 v85, v85, v72, v101 op_sel:[0,1,0] op_sel_hi:[0,1,0]
	v_add_f32_dpp v98, v98, v98 row_half_mirror row_mask:0xf bank_mask:0xf bound_ctrl:1
	v_fma_mix_f32 v86, v86, v73, v102 op_sel:[0,0,0] op_sel_hi:[0,1,0]
	v_fma_mix_f32 v87, v87, v73, v103 op_sel:[0,1,0] op_sel_hi:[0,1,0]
	v_add_f32_dpp v98, v98, v98 row_mirror row_mask:0xf bank_mask:0xf bound_ctrl:1
	v_fma_mix_f32 v84, -v98, v76, v84 op_sel:[0,0,0] op_sel_hi:[0,1,0]
	v_fma_mix_f32 v85, -v98, v76, v85 op_sel:[0,1,0] op_sel_hi:[0,1,0]
	v_fma_mix_f32 v86, -v98, v77, v86 op_sel:[0,0,0] op_sel_hi:[0,1,0]
	v_fma_mix_f32 v87, -v98, v77, v87 op_sel:[0,1,0] op_sel_hi:[0,1,0]
	v_fma_mix_f32 v73, v84, v66, 0 op_sel:[0,0,0] op_sel_hi:[0,1,0]
	v_fma_mix_f32 v97, v84, v56, 0 op_sel:[0,0,0] op_sel_hi:[0,1,0]
	v_fma_mix_f32 v73, v85, v66, v73 op_sel:[0,1,0] op_sel_hi:[0,1,0]
	v_fma_mix_f32 v56, v85, v56, v97 op_sel:[0,1,0] op_sel_hi:[0,1,0]
	v_fma_mix_f32 v73, v86, v67, v73 op_sel:[0,0,0] op_sel_hi:[0,1,0]
	v_fma_mix_f32 v56, v86, v57, v56 op_sel:[0,0,0] op_sel_hi:[0,1,0]
	v_fma_mix_f32 v73, v87, v67, v73 op_sel:[0,1,0] op_sel_hi:[0,1,0]
	v_fma_mix_f32 v56, v87, v57, v56 op_sel:[0,1,0] op_sel_hi:[0,1,0]
	v_fma_mix_f32 v75, v93, v70, 0 op_sel:[0,0,0] op_sel_hi:[1,1,0]
	v_fma_mix_f32 v76, v93, v70, 0 op_sel:[0,1,0] op_sel_hi:[1,1,0]
	v_add_f32_dpp v73, v73, v73 quad_perm:[1,0,3,2] row_mask:0xf bank_mask:0xf bound_ctrl:1
	v_fma_mix_f32 v77, v93, v71, 0 op_sel:[0,0,0] op_sel_hi:[1,1,0]
	v_fma_mix_f32 v78, v93, v71, 0 op_sel:[0,1,0] op_sel_hi:[1,1,0]
	v_add_f32_dpp v73, v73, v73 quad_perm:[2,3,0,1] row_mask:0xf bank_mask:0xf bound_ctrl:1
	v_fma_mix_f32 v84, v84, v64, v75 op_sel:[0,0,0] op_sel_hi:[0,1,0]
	v_fma_mix_f32 v85, v85, v64, v76 op_sel:[0,1,0] op_sel_hi:[0,1,0]
	v_add_f32_dpp v73, v73, v73 row_half_mirror row_mask:0xf bank_mask:0xf bound_ctrl:1
	v_fma_mix_f32 v86, v86, v65, v77 op_sel:[0,0,0] op_sel_hi:[0,1,0]
	v_fma_mix_f32 v87, v87, v65, v78 op_sel:[0,1,0] op_sel_hi:[0,1,0]
	v_add_f32_dpp v73, v73, v73 row_mirror row_mask:0xf bank_mask:0xf bound_ctrl:1
	v_fma_mix_f32 v84, -v73, v68, v84 op_sel:[0,0,0] op_sel_hi:[0,1,0]
	v_fma_mix_f32 v85, -v73, v68, v85 op_sel:[0,1,0] op_sel_hi:[0,1,0]
	v_fma_mix_f32 v86, -v73, v69, v86 op_sel:[0,0,0] op_sel_hi:[0,1,0]
	v_fma_mix_f32 v87, -v73, v69, v87 op_sel:[0,1,0] op_sel_hi:[0,1,0]
	v_fma_mix_f32 v64, v84, v54, 0 op_sel:[0,0,0] op_sel_hi:[0,1,0]
	v_fma_mix_f32 v57, v84, v58, 0 op_sel:[0,0,0] op_sel_hi:[0,1,0]
	v_fma_mix_f32 v64, v85, v54, v64 op_sel:[0,1,0] op_sel_hi:[0,1,0]
	v_fma_mix_f32 v57, v85, v58, v57 op_sel:[0,1,0] op_sel_hi:[0,1,0]
	v_fma_mix_f32 v64, v86, v55, v64 op_sel:[0,0,0] op_sel_hi:[0,1,0]
	v_fma_mix_f32 v57, v86, v59, v57 op_sel:[0,0,0] op_sel_hi:[0,1,0]
	v_fma_mix_f32 v64, v87, v55, v64 op_sel:[0,1,0] op_sel_hi:[0,1,0]
	v_fma_mix_f32 v57, v87, v59, v57 op_sel:[0,1,0] op_sel_hi:[0,1,0]
	v_fma_mix_f32 v66, v94, v62, 0 op_sel:[0,0,0] op_sel_hi:[1,1,0]
	v_fma_mix_f32 v67, v94, v62, 0 op_sel:[0,1,0] op_sel_hi:[1,1,0]
	v_add_f32_dpp v64, v64, v64 quad_perm:[1,0,3,2] row_mask:0xf bank_mask:0xf bound_ctrl:1
	v_fma_mix_f32 v68, v94, v63, 0 op_sel:[0,0,0] op_sel_hi:[1,1,0]
	v_fma_mix_f32 v69, v94, v63, 0 op_sel:[0,1,0] op_sel_hi:[1,1,0]
	v_add_f32_dpp v64, v64, v64 quad_perm:[2,3,0,1] row_mask:0xf bank_mask:0xf bound_ctrl:1
	v_fma_mix_f32 v84, v84, v52, v66 op_sel:[0,0,0] op_sel_hi:[0,1,0]
	v_fma_mix_f32 v85, v85, v52, v67 op_sel:[0,1,0] op_sel_hi:[0,1,0]
	v_add_f32_dpp v64, v64, v64 row_half_mirror row_mask:0xf bank_mask:0xf bound_ctrl:1
	v_fma_mix_f32 v86, v86, v53, v68 op_sel:[0,0,0] op_sel_hi:[0,1,0]
	v_fma_mix_f32 v87, v87, v53, v69 op_sel:[0,1,0] op_sel_hi:[0,1,0]
	v_add_f32_dpp v64, v64, v64 row_mirror row_mask:0xf bank_mask:0xf bound_ctrl:1
	v_fma_mix_f32 v84, -v64, v60, v84 op_sel:[0,0,0] op_sel_hi:[0,1,0]
	v_fma_mix_f32 v85, -v64, v60, v85 op_sel:[0,1,0] op_sel_hi:[0,1,0]
	v_fma_mix_f32 v86, -v64, v61, v86 op_sel:[0,0,0] op_sel_hi:[0,1,0]
	v_fma_mix_f32 v87, -v64, v61, v87 op_sel:[0,1,0] op_sel_hi:[0,1,0]
	v_fma_mix_f32 v53, v84, v46, 0 op_sel:[0,0,0] op_sel_hi:[0,1,0]
	v_fma_mix_f32 v59, v84, v40, 0 op_sel:[0,0,0] op_sel_hi:[0,1,0]
	v_fma_mix_f32 v53, v85, v46, v53 op_sel:[0,1,0] op_sel_hi:[0,1,0]
	v_fma_mix_f32 v40, v85, v40, v59 op_sel:[0,1,0] op_sel_hi:[0,1,0]
	v_fma_mix_f32 v53, v86, v47, v53 op_sel:[0,0,0] op_sel_hi:[0,1,0]
	v_fma_mix_f32 v40, v86, v41, v40 op_sel:[0,0,0] op_sel_hi:[0,1,0]
	v_fma_mix_f32 v53, v87, v47, v53 op_sel:[0,1,0] op_sel_hi:[0,1,0]
	v_fma_mix_f32 v40, v87, v41, v40 op_sel:[0,1,0] op_sel_hi:[0,1,0]
	v_fma_mix_f32 v55, v95, v50, 0 op_sel:[0,0,0] op_sel_hi:[1,1,0]
	v_fma_mix_f32 v58, v95, v50, 0 op_sel:[0,1,0] op_sel_hi:[1,1,0]
	v_add_f32_dpp v53, v53, v53 quad_perm:[1,0,3,2] row_mask:0xf bank_mask:0xf bound_ctrl:1
	v_fma_mix_f32 v59, v95, v51, 0 op_sel:[0,0,0] op_sel_hi:[1,1,0]
	v_fma_mix_f32 v60, v95, v51, 0 op_sel:[0,1,0] op_sel_hi:[1,1,0]
	v_add_f32_dpp v53, v53, v53 quad_perm:[2,3,0,1] row_mask:0xf bank_mask:0xf bound_ctrl:1
	v_fma_mix_f32 v84, v84, v44, v55 op_sel:[0,0,0] op_sel_hi:[0,1,0]
	v_fma_mix_f32 v85, v85, v44, v58 op_sel:[0,1,0] op_sel_hi:[0,1,0]
	v_add_f32_dpp v53, v53, v53 row_half_mirror row_mask:0xf bank_mask:0xf bound_ctrl:1
	v_fma_mix_f32 v86, v86, v45, v59 op_sel:[0,0,0] op_sel_hi:[0,1,0]
	v_fma_mix_f32 v87, v87, v45, v60 op_sel:[0,1,0] op_sel_hi:[0,1,0]
	v_add_f32_dpp v53, v53, v53 row_mirror row_mask:0xf bank_mask:0xf bound_ctrl:1
	v_fma_mix_f32 v84, -v53, v48, v84 op_sel:[0,0,0] op_sel_hi:[0,1,0]
	v_fma_mix_f32 v85, -v53, v48, v85 op_sel:[0,1,0] op_sel_hi:[0,1,0]
	v_fma_mix_f32 v86, -v53, v49, v86 op_sel:[0,0,0] op_sel_hi:[0,1,0]
	v_fma_mix_f32 v87, -v53, v49, v87 op_sel:[0,1,0] op_sel_hi:[0,1,0]
	v_fma_mix_f32 v41, v84, v42, 0 op_sel:[0,0,0] op_sel_hi:[0,1,0]
	v_cndmask_b32_e64 v187, v57, v56, s[38:39]
	v_fma_mix_f32 v41, v85, v42, v41 op_sel:[0,1,0] op_sel_hi:[0,1,0]
	v_cndmask_b32_e64 v188, v56, v57, s[38:39]
	v_fma_mix_f32 v41, v86, v43, v41 op_sel:[0,0,0] op_sel_hi:[0,1,0]
	v_fma_mix_f32 v41, v87, v43, v41 op_sel:[0,1,0] op_sel_hi:[0,1,0]
	v_cndmask_b32_e64 v189, v41, v40, s[38:39]
	v_cndmask_b32_e64 v190, v40, v41, s[38:39]
	s_waitcnt lgkmcnt(0)
	v_fma_mix_f32 v98, v84, v6, 0 op_sel:[0,0,0] op_sel_hi:[0,1,0]
	v_fma_mix_f32 v98, v85, v6, v98 op_sel:[0,1,0] op_sel_hi:[0,1,0]
	v_add_f32_dpp v188, v188, v187 quad_perm:[1,0,3,2] row_mask:0xf bank_mask:0xf bound_ctrl:1
	v_add_f32_dpp v189, v190, v189 quad_perm:[1,0,3,2] row_mask:0xf bank_mask:0xf bound_ctrl:1
	v_fma_mix_f32 v98, v86, v7, v98 op_sel:[0,0,0] op_sel_hi:[0,1,0]
	v_fma_mix_f32 v98, v87, v7, v98 op_sel:[0,1,0] op_sel_hi:[0,1,0]
	v_cndmask_b32_e64 v191, v189, v188, s[40:41]
	v_cndmask_b32_e64 v192, v188, v189, s[40:41]
	v_fma_mix_f32 v100, v88, v14, 0 op_sel:[0,0,0] op_sel_hi:[1,1,0]
	v_fma_mix_f32 v101, v88, v14, 0 op_sel:[0,1,0] op_sel_hi:[1,1,0]
	v_add_f32_dpp v192, v192, v191 quad_perm:[2,3,0,1] row_mask:0xf bank_mask:0xf bound_ctrl:1
	v_add_f32_dpp v98, v98, v98 quad_perm:[1,0,3,2] row_mask:0xf bank_mask:0xf bound_ctrl:1
	v_fma_mix_f32 v102, v88, v15, 0 op_sel:[0,0,0] op_sel_hi:[1,1,0]
	v_add_f32_dpp v192, v192, v192 row_ror:4 row_mask:0xf bank_mask:0xf bound_ctrl:1
	v_fma_mix_f32 v103, v88, v15, 0 op_sel:[0,1,0] op_sel_hi:[1,1,0]
	v_add_f32_dpp v98, v98, v98 quad_perm:[2,3,0,1] row_mask:0xf bank_mask:0xf bound_ctrl:1
	v_add_f32_dpp v192, v192, v192 row_ror:8 row_mask:0xf bank_mask:0xf bound_ctrl:1
	v_cvt_f16_f32_e32 v192, v192
	global_store_short v83, v192, s[36:37]
	s_add_u32 s36, s36, s44
	s_addc_u32 s37, s37, s45
	global_load_ushort v202, v83, s[22:23]
	s_add_u32 s22, s22, s44
	s_addc_u32 s23, s23, s45
	ds_read_b128 v[56:59], v194 offset:48128
	ds_read_b128 v[72:75], v194 offset:46080
	ds_read_b128 v[64:67], v194 offset:46336
	ds_read_b128 v[76:79], v194 offset:47104
	ds_read_b128 v[68:71], v194 offset:47360
	ds_read_b128 v[40:43], v194 offset:48384
	ds_read_b128 v[52:55], v194 offset:46592
	ds_read_b128 v[44:47], v194 offset:46848
	ds_read_b128 v[60:63], v194 offset:47616
	ds_read_b128 v[48:51], v194 offset:47872
	s_waitcnt vmcnt(12)
	v_mov_b32_dpp v92, v212 quad_perm:[0,0,0,0] row_mask:0xf bank_mask:0xf
	v_mov_b32_dpp v93, v212 quad_perm:[1,1,1,1] row_mask:0xf bank_mask:0xf
	v_mov_b32_dpp v94, v212 quad_perm:[2,2,2,2] row_mask:0xf bank_mask:0xf
	v_mov_b32_dpp v95, v212 quad_perm:[3,3,3,3] row_mask:0xf bank_mask:0xf
	v_fma_mix_f32 v84, v84, v4, v100 op_sel:[0,0,0] op_sel_hi:[0,1,0]
	v_fma_mix_f32 v85, v85, v4, v101 op_sel:[0,1,0] op_sel_hi:[0,1,0]
	v_add_f32_dpp v98, v98, v98 row_half_mirror row_mask:0xf bank_mask:0xf bound_ctrl:1
	v_fma_mix_f32 v86, v86, v5, v102 op_sel:[0,0,0] op_sel_hi:[0,1,0]
	v_fma_mix_f32 v87, v87, v5, v103 op_sel:[0,1,0] op_sel_hi:[0,1,0]
	v_add_f32_dpp v98, v98, v98 row_mirror row_mask:0xf bank_mask:0xf bound_ctrl:1
	v_fma_mix_f32 v84, -v98, v12, v84 op_sel:[0,0,0] op_sel_hi:[0,1,0]
	v_fma_mix_f32 v85, -v98, v12, v85 op_sel:[0,1,0] op_sel_hi:[0,1,0]
	v_fma_mix_f32 v86, -v98, v13, v86 op_sel:[0,0,0] op_sel_hi:[0,1,0]
	v_fma_mix_f32 v87, -v98, v13, v87 op_sel:[0,1,0] op_sel_hi:[0,1,0]
	v_fma_mix_f32 v99, v84, v10, 0 op_sel:[0,0,0] op_sel_hi:[0,1,0]
	v_fma_mix_f32 v96, v84, v0, 0 op_sel:[0,0,0] op_sel_hi:[0,1,0]
	v_fma_mix_f32 v99, v85, v10, v99 op_sel:[0,1,0] op_sel_hi:[0,1,0]
	v_fma_mix_f32 v96, v85, v0, v96 op_sel:[0,1,0] op_sel_hi:[0,1,0]
	v_fma_mix_f32 v99, v86, v11, v99 op_sel:[0,0,0] op_sel_hi:[0,1,0]
	v_fma_mix_f32 v96, v86, v1, v96 op_sel:[0,0,0] op_sel_hi:[0,1,0]
	v_fma_mix_f32 v99, v87, v11, v99 op_sel:[0,1,0] op_sel_hi:[0,1,0]
	v_fma_mix_f32 v96, v87, v1, v96 op_sel:[0,1,0] op_sel_hi:[0,1,0]
	v_fma_mix_f32 v101, v89, v18, 0 op_sel:[0,0,0] op_sel_hi:[1,1,0]
	v_fma_mix_f32 v102, v89, v18, 0 op_sel:[0,1,0] op_sel_hi:[1,1,0]
	v_add_f32_dpp v99, v99, v99 quad_perm:[1,0,3,2] row_mask:0xf bank_mask:0xf bound_ctrl:1
	v_fma_mix_f32 v103, v89, v19, 0 op_sel:[0,0,0] op_sel_hi:[1,1,0]
	v_fma_mix_f32 v104, v89, v19, 0 op_sel:[0,1,0] op_sel_hi:[1,1,0]
	v_add_f32_dpp v99, v99, v99 quad_perm:[2,3,0,1] row_mask:0xf bank_mask:0xf bound_ctrl:1
	v_fma_mix_f32 v84, v84, v8, v101 op_sel:[0,0,0] op_sel_hi:[0,1,0]
	v_fma_mix_f32 v85, v85, v8, v102 op_sel:[0,1,0] op_sel_hi:[0,1,0]
	v_add_f32_dpp v99, v99, v99 row_half_mirror row_mask:0xf bank_mask:0xf bound_ctrl:1
	v_fma_mix_f32 v86, v86, v9, v103 op_sel:[0,0,0] op_sel_hi:[0,1,0]
	v_fma_mix_f32 v87, v87, v9, v104 op_sel:[0,1,0] op_sel_hi:[0,1,0]
	v_add_f32_dpp v99, v99, v99 row_mirror row_mask:0xf bank_mask:0xf bound_ctrl:1
	v_fma_mix_f32 v84, -v99, v16, v84 op_sel:[0,0,0] op_sel_hi:[0,1,0]
	v_fma_mix_f32 v85, -v99, v16, v85 op_sel:[0,1,0] op_sel_hi:[0,1,0]
	v_fma_mix_f32 v86, -v99, v17, v86 op_sel:[0,0,0] op_sel_hi:[0,1,0]
	v_fma_mix_f32 v87, -v99, v17, v87 op_sel:[0,1,0] op_sel_hi:[0,1,0]
	v_fma_mix_f32 v100, v84, v26, 0 op_sel:[0,0,0] op_sel_hi:[0,1,0]
	v_fma_mix_f32 v97, v84, v2, 0 op_sel:[0,0,0] op_sel_hi:[0,1,0]
	v_fma_mix_f32 v100, v85, v26, v100 op_sel:[0,1,0] op_sel_hi:[0,1,0]
	v_fma_mix_f32 v97, v85, v2, v97 op_sel:[0,1,0] op_sel_hi:[0,1,0]
	v_fma_mix_f32 v100, v86, v27, v100 op_sel:[0,0,0] op_sel_hi:[0,1,0]
	v_fma_mix_f32 v97, v86, v3, v97 op_sel:[0,0,0] op_sel_hi:[0,1,0]
	v_fma_mix_f32 v100, v87, v27, v100 op_sel:[0,1,0] op_sel_hi:[0,1,0]
	v_fma_mix_f32 v97, v87, v3, v97 op_sel:[0,1,0] op_sel_hi:[0,1,0]
	v_fma_mix_f32 v102, v90, v34, 0 op_sel:[0,0,0] op_sel_hi:[1,1,0]
	v_fma_mix_f32 v103, v90, v34, 0 op_sel:[0,1,0] op_sel_hi:[1,1,0]
	v_add_f32_dpp v100, v100, v100 quad_perm:[1,0,3,2] row_mask:0xf bank_mask:0xf bound_ctrl:1
	v_fma_mix_f32 v104, v90, v35, 0 op_sel:[0,0,0] op_sel_hi:[1,1,0]
	v_fma_mix_f32 v105, v90, v35, 0 op_sel:[0,1,0] op_sel_hi:[1,1,0]
	v_add_f32_dpp v100, v100, v100 quad_perm:[2,3,0,1] row_mask:0xf bank_mask:0xf bound_ctrl:1
	v_fma_mix_f32 v84, v84, v24, v102 op_sel:[0,0,0] op_sel_hi:[0,1,0]
	v_fma_mix_f32 v85, v85, v24, v103 op_sel:[0,1,0] op_sel_hi:[0,1,0]
	v_add_f32_dpp v100, v100, v100 row_half_mirror row_mask:0xf bank_mask:0xf bound_ctrl:1
	v_fma_mix_f32 v86, v86, v25, v104 op_sel:[0,0,0] op_sel_hi:[0,1,0]
	v_fma_mix_f32 v87, v87, v25, v105 op_sel:[0,1,0] op_sel_hi:[0,1,0]
	v_add_f32_dpp v100, v100, v100 row_mirror row_mask:0xf bank_mask:0xf bound_ctrl:1
	v_fma_mix_f32 v84, -v100, v32, v84 op_sel:[0,0,0] op_sel_hi:[0,1,0]
	v_fma_mix_f32 v85, -v100, v32, v85 op_sel:[0,1,0] op_sel_hi:[0,1,0]
	v_fma_mix_f32 v86, -v100, v33, v86 op_sel:[0,0,0] op_sel_hi:[0,1,0]
	v_fma_mix_f32 v87, -v100, v33, v87 op_sel:[0,1,0] op_sel_hi:[0,1,0]
	v_fma_mix_f32 v101, v84, v30, 0 op_sel:[0,0,0] op_sel_hi:[0,1,0]
	v_fma_mix_f32 v98, v84, v20, 0 op_sel:[0,0,0] op_sel_hi:[0,1,0]
	v_fma_mix_f32 v101, v85, v30, v101 op_sel:[0,1,0] op_sel_hi:[0,1,0]
	v_fma_mix_f32 v98, v85, v20, v98 op_sel:[0,1,0] op_sel_hi:[0,1,0]
	v_fma_mix_f32 v101, v86, v31, v101 op_sel:[0,0,0] op_sel_hi:[0,1,0]
	v_fma_mix_f32 v98, v86, v21, v98 op_sel:[0,0,0] op_sel_hi:[0,1,0]
	v_fma_mix_f32 v101, v87, v31, v101 op_sel:[0,1,0] op_sel_hi:[0,1,0]
	v_fma_mix_f32 v98, v87, v21, v98 op_sel:[0,1,0] op_sel_hi:[0,1,0]
	v_fma_mix_f32 v103, v91, v38, 0 op_sel:[0,0,0] op_sel_hi:[1,1,0]
	v_fma_mix_f32 v104, v91, v38, 0 op_sel:[0,1,0] op_sel_hi:[1,1,0]
	v_add_f32_dpp v101, v101, v101 quad_perm:[1,0,3,2] row_mask:0xf bank_mask:0xf bound_ctrl:1
	v_fma_mix_f32 v105, v91, v39, 0 op_sel:[0,0,0] op_sel_hi:[1,1,0]
	v_fma_mix_f32 v119, v91, v39, 0 op_sel:[0,1,0] op_sel_hi:[1,1,0]
	v_add_f32_dpp v101, v101, v101 quad_perm:[2,3,0,1] row_mask:0xf bank_mask:0xf bound_ctrl:1
	v_fma_mix_f32 v84, v84, v28, v103 op_sel:[0,0,0] op_sel_hi:[0,1,0]
	v_fma_mix_f32 v85, v85, v28, v104 op_sel:[0,1,0] op_sel_hi:[0,1,0]
	v_add_f32_dpp v101, v101, v101 row_half_mirror row_mask:0xf bank_mask:0xf bound_ctrl:1
	v_fma_mix_f32 v86, v86, v29, v105 op_sel:[0,0,0] op_sel_hi:[0,1,0]
	v_fma_mix_f32 v87, v87, v29, v119 op_sel:[0,1,0] op_sel_hi:[0,1,0]
	v_add_f32_dpp v101, v101, v101 row_mirror row_mask:0xf bank_mask:0xf bound_ctrl:1
	v_fma_mix_f32 v84, -v101, v36, v84 op_sel:[0,0,0] op_sel_hi:[0,1,0]
	v_fma_mix_f32 v85, -v101, v36, v85 op_sel:[0,1,0] op_sel_hi:[0,1,0]
	v_fma_mix_f32 v86, -v101, v37, v86 op_sel:[0,0,0] op_sel_hi:[0,1,0]
	v_fma_mix_f32 v87, -v101, v37, v87 op_sel:[0,1,0] op_sel_hi:[0,1,0]
	v_fma_mix_f32 v99, v84, v22, 0 op_sel:[0,0,0] op_sel_hi:[0,1,0]
	v_cndmask_b32_e64 v187, v97, v96, s[38:39]
	v_fma_mix_f32 v99, v85, v22, v99 op_sel:[0,1,0] op_sel_hi:[0,1,0]
	v_cndmask_b32_e64 v188, v96, v97, s[38:39]
	v_fma_mix_f32 v99, v86, v23, v99 op_sel:[0,0,0] op_sel_hi:[0,1,0]
	v_fma_mix_f32 v99, v87, v23, v99 op_sel:[0,1,0] op_sel_hi:[0,1,0]
	v_cndmask_b32_e64 v189, v99, v98, s[38:39]
	v_cndmask_b32_e64 v190, v98, v99, s[38:39]
	s_waitcnt lgkmcnt(0)
	v_fma_mix_f32 v98, v84, v74, 0 op_sel:[0,0,0] op_sel_hi:[0,1,0]
	v_fma_mix_f32 v98, v85, v74, v98 op_sel:[0,1,0] op_sel_hi:[0,1,0]
	v_add_f32_dpp v188, v188, v187 quad_perm:[1,0,3,2] row_mask:0xf bank_mask:0xf bound_ctrl:1
	v_add_f32_dpp v189, v190, v189 quad_perm:[1,0,3,2] row_mask:0xf bank_mask:0xf bound_ctrl:1
	v_fma_mix_f32 v98, v86, v75, v98 op_sel:[0,0,0] op_sel_hi:[0,1,0]
	v_fma_mix_f32 v98, v87, v75, v98 op_sel:[0,1,0] op_sel_hi:[0,1,0]
	v_cndmask_b32_e64 v191, v189, v188, s[40:41]
	v_cndmask_b32_e64 v192, v188, v189, s[40:41]
	v_fma_mix_f32 v100, v92, v78, 0 op_sel:[0,0,0] op_sel_hi:[1,1,0]
	v_fma_mix_f32 v101, v92, v78, 0 op_sel:[0,1,0] op_sel_hi:[1,1,0]
	v_add_f32_dpp v192, v192, v191 quad_perm:[2,3,0,1] row_mask:0xf bank_mask:0xf bound_ctrl:1
	v_add_f32_dpp v98, v98, v98 quad_perm:[1,0,3,2] row_mask:0xf bank_mask:0xf bound_ctrl:1
	v_fma_mix_f32 v102, v92, v79, 0 op_sel:[0,0,0] op_sel_hi:[1,1,0]
	v_add_f32_dpp v192, v192, v192 row_ror:4 row_mask:0xf bank_mask:0xf bound_ctrl:1
	v_fma_mix_f32 v103, v92, v79, 0 op_sel:[0,1,0] op_sel_hi:[1,1,0]
	v_add_f32_dpp v98, v98, v98 quad_perm:[2,3,0,1] row_mask:0xf bank_mask:0xf bound_ctrl:1
	v_add_f32_dpp v192, v192, v192 row_ror:8 row_mask:0xf bank_mask:0xf bound_ctrl:1
	v_cvt_f16_f32_e32 v192, v192
	global_store_short v83, v192, s[36:37]
	s_add_u32 s36, s36, s44
	s_addc_u32 s37, s37, s45
	global_load_ushort v203, v83, s[22:23]
	s_add_u32 s22, s22, s44
	s_addc_u32 s23, s23, s45
	s_cmp_gt_i32 s35, 17
	s_cbranch_scc0 .Lc_poll_A7
.Lc_ret_A7:
	ds_read_b128 v[0:3], v194 offset:2048
	ds_read_b128 v[4:7], v194 offset:0
	ds_read_b128 v[8:11], v194 offset:256
	ds_read_b128 v[12:15], v194 offset:1024
	ds_read_b128 v[16:19], v194 offset:1280
	ds_read_b128 v[20:23], v194 offset:2304
	ds_read_b128 v[24:27], v194 offset:512
	ds_read_b128 v[28:31], v194 offset:768
	ds_read_b128 v[32:35], v194 offset:1536
	ds_read_b128 v[36:39], v194 offset:1792
	s_waitcnt vmcnt(12)
	v_mov_b32_dpp v88, v197 quad_perm:[0,0,0,0] row_mask:0xf bank_mask:0xf
	v_mov_b32_dpp v89, v197 quad_perm:[1,1,1,1] row_mask:0xf bank_mask:0xf
	v_mov_b32_dpp v90, v197 quad_perm:[2,2,2,2] row_mask:0xf bank_mask:0xf
	v_mov_b32_dpp v91, v197 quad_perm:[3,3,3,3] row_mask:0xf bank_mask:0xf
	v_fma_mix_f32 v84, v84, v72, v100 op_sel:[0,0,0] op_sel_hi:[0,1,0]
	v_fma_mix_f32 v85, v85, v72, v101 op_sel:[0,1,0] op_sel_hi:[0,1,0]
	v_add_f32_dpp v98, v98, v98 row_half_mirror row_mask:0xf bank_mask:0xf bound_ctrl:1
	v_fma_mix_f32 v86, v86, v73, v102 op_sel:[0,0,0] op_sel_hi:[0,1,0]
	v_fma_mix_f32 v87, v87, v73, v103 op_sel:[0,1,0] op_sel_hi:[0,1,0]
	v_add_f32_dpp v98, v98, v98 row_mirror row_mask:0xf bank_mask:0xf bound_ctrl:1
	v_fma_mix_f32 v84, -v98, v76, v84 op_sel:[0,0,0] op_sel_hi:[0,1,0]
	v_fma_mix_f32 v85, -v98, v76, v85 op_sel:[0,1,0] op_sel_hi:[0,1,0]
	v_fma_mix_f32 v86, -v98, v77, v86 op_sel:[0,0,0] op_sel_hi:[0,1,0]
	v_fma_mix_f32 v87, -v98, v77, v87 op_sel:[0,1,0] op_sel_hi:[0,1,0]
	v_fma_mix_f32 v73, v84, v66, 0 op_sel:[0,0,0] op_sel_hi:[0,1,0]
	v_fma_mix_f32 v97, v84, v56, 0 op_sel:[0,0,0] op_sel_hi:[0,1,0]
	v_fma_mix_f32 v73, v85, v66, v73 op_sel:[0,1,0] op_sel_hi:[0,1,0]
	v_fma_mix_f32 v56, v85, v56, v97 op_sel:[0,1,0] op_sel_hi:[0,1,0]
	v_fma_mix_f32 v73, v86, v67, v73 op_sel:[0,0,0] op_sel_hi:[0,1,0]
	v_fma_mix_f32 v56, v86, v57, v56 op_sel:[0,0,0] op_sel_hi:[0,1,0]
	v_fma_mix_f32 v73, v87, v67, v73 op_sel:[0,1,0] op_sel_hi:[0,1,0]
	v_fma_mix_f32 v56, v87, v57, v56 op_sel:[0,1,0] op_sel_hi:[0,1,0]
	v_fma_mix_f32 v75, v93, v70, 0 op_sel:[0,0,0] op_sel_hi:[1,1,0]
	v_fma_mix_f32 v76, v93, v70, 0 op_sel:[0,1,0] op_sel_hi:[1,1,0]
	v_add_f32_dpp v73, v73, v73 quad_perm:[1,0,3,2] row_mask:0xf bank_mask:0xf bound_ctrl:1
	v_fma_mix_f32 v77, v93, v71, 0 op_sel:[0,0,0] op_sel_hi:[1,1,0]
	v_fma_mix_f32 v78, v93, v71, 0 op_sel:[0,1,0] op_sel_hi:[1,1,0]
	v_add_f32_dpp v73, v73, v73 quad_perm:[2,3,0,1] row_mask:0xf bank_mask:0xf bound_ctrl:1
	v_fma_mix_f32 v84, v84, v64, v75 op_sel:[0,0,0] op_sel_hi:[0,1,0]
	v_fma_mix_f32 v85, v85, v64, v76 op_sel:[0,1,0] op_sel_hi:[0,1,0]
	v_add_f32_dpp v73, v73, v73 row_half_mirror row_mask:0xf bank_mask:0xf bound_ctrl:1
	v_fma_mix_f32 v86, v86, v65, v77 op_sel:[0,0,0] op_sel_hi:[0,1,0]
	v_fma_mix_f32 v87, v87, v65, v78 op_sel:[0,1,0] op_sel_hi:[0,1,0]
	v_add_f32_dpp v73, v73, v73 row_mirror row_mask:0xf bank_mask:0xf bound_ctrl:1
	v_fma_mix_f32 v84, -v73, v68, v84 op_sel:[0,0,0] op_sel_hi:[0,1,0]
	v_fma_mix_f32 v85, -v73, v68, v85 op_sel:[0,1,0] op_sel_hi:[0,1,0]
	v_fma_mix_f32 v86, -v73, v69, v86 op_sel:[0,0,0] op_sel_hi:[0,1,0]
	v_fma_mix_f32 v87, -v73, v69, v87 op_sel:[0,1,0] op_sel_hi:[0,1,0]
	v_fma_mix_f32 v64, v84, v54, 0 op_sel:[0,0,0] op_sel_hi:[0,1,0]
	v_fma_mix_f32 v57, v84, v58, 0 op_sel:[0,0,0] op_sel_hi:[0,1,0]
	v_fma_mix_f32 v64, v85, v54, v64 op_sel:[0,1,0] op_sel_hi:[0,1,0]
	v_fma_mix_f32 v57, v85, v58, v57 op_sel:[0,1,0] op_sel_hi:[0,1,0]
	v_fma_mix_f32 v64, v86, v55, v64 op_sel:[0,0,0] op_sel_hi:[0,1,0]
	v_fma_mix_f32 v57, v86, v59, v57 op_sel:[0,0,0] op_sel_hi:[0,1,0]
	v_fma_mix_f32 v64, v87, v55, v64 op_sel:[0,1,0] op_sel_hi:[0,1,0]
	v_fma_mix_f32 v57, v87, v59, v57 op_sel:[0,1,0] op_sel_hi:[0,1,0]
	v_fma_mix_f32 v66, v94, v62, 0 op_sel:[0,0,0] op_sel_hi:[1,1,0]
	v_fma_mix_f32 v67, v94, v62, 0 op_sel:[0,1,0] op_sel_hi:[1,1,0]
	v_add_f32_dpp v64, v64, v64 quad_perm:[1,0,3,2] row_mask:0xf bank_mask:0xf bound_ctrl:1
	v_fma_mix_f32 v68, v94, v63, 0 op_sel:[0,0,0] op_sel_hi:[1,1,0]
	v_fma_mix_f32 v69, v94, v63, 0 op_sel:[0,1,0] op_sel_hi:[1,1,0]
	v_add_f32_dpp v64, v64, v64 quad_perm:[2,3,0,1] row_mask:0xf bank_mask:0xf bound_ctrl:1
	v_fma_mix_f32 v84, v84, v52, v66 op_sel:[0,0,0] op_sel_hi:[0,1,0]
	v_fma_mix_f32 v85, v85, v52, v67 op_sel:[0,1,0] op_sel_hi:[0,1,0]
	v_add_f32_dpp v64, v64, v64 row_half_mirror row_mask:0xf bank_mask:0xf bound_ctrl:1
	v_fma_mix_f32 v86, v86, v53, v68 op_sel:[0,0,0] op_sel_hi:[0,1,0]
	v_fma_mix_f32 v87, v87, v53, v69 op_sel:[0,1,0] op_sel_hi:[0,1,0]
	v_add_f32_dpp v64, v64, v64 row_mirror row_mask:0xf bank_mask:0xf bound_ctrl:1
	v_fma_mix_f32 v84, -v64, v60, v84 op_sel:[0,0,0] op_sel_hi:[0,1,0]
	v_fma_mix_f32 v85, -v64, v60, v85 op_sel:[0,1,0] op_sel_hi:[0,1,0]
	v_fma_mix_f32 v86, -v64, v61, v86 op_sel:[0,0,0] op_sel_hi:[0,1,0]
	v_fma_mix_f32 v87, -v64, v61, v87 op_sel:[0,1,0] op_sel_hi:[0,1,0]
	v_fma_mix_f32 v53, v84, v46, 0 op_sel:[0,0,0] op_sel_hi:[0,1,0]
	v_fma_mix_f32 v59, v84, v40, 0 op_sel:[0,0,0] op_sel_hi:[0,1,0]
	v_fma_mix_f32 v53, v85, v46, v53 op_sel:[0,1,0] op_sel_hi:[0,1,0]
	v_fma_mix_f32 v40, v85, v40, v59 op_sel:[0,1,0] op_sel_hi:[0,1,0]
	v_fma_mix_f32 v53, v86, v47, v53 op_sel:[0,0,0] op_sel_hi:[0,1,0]
	v_fma_mix_f32 v40, v86, v41, v40 op_sel:[0,0,0] op_sel_hi:[0,1,0]
	v_fma_mix_f32 v53, v87, v47, v53 op_sel:[0,1,0] op_sel_hi:[0,1,0]
	v_fma_mix_f32 v40, v87, v41, v40 op_sel:[0,1,0] op_sel_hi:[0,1,0]
	v_fma_mix_f32 v55, v95, v50, 0 op_sel:[0,0,0] op_sel_hi:[1,1,0]
	v_fma_mix_f32 v58, v95, v50, 0 op_sel:[0,1,0] op_sel_hi:[1,1,0]
	v_add_f32_dpp v53, v53, v53 quad_perm:[1,0,3,2] row_mask:0xf bank_mask:0xf bound_ctrl:1
	v_fma_mix_f32 v59, v95, v51, 0 op_sel:[0,0,0] op_sel_hi:[1,1,0]
	v_fma_mix_f32 v60, v95, v51, 0 op_sel:[0,1,0] op_sel_hi:[1,1,0]
	v_add_f32_dpp v53, v53, v53 quad_perm:[2,3,0,1] row_mask:0xf bank_mask:0xf bound_ctrl:1
	v_fma_mix_f32 v84, v84, v44, v55 op_sel:[0,0,0] op_sel_hi:[0,1,0]
	v_fma_mix_f32 v85, v85, v44, v58 op_sel:[0,1,0] op_sel_hi:[0,1,0]
	v_add_f32_dpp v53, v53, v53 row_half_mirror row_mask:0xf bank_mask:0xf bound_ctrl:1
	v_fma_mix_f32 v86, v86, v45, v59 op_sel:[0,0,0] op_sel_hi:[0,1,0]
	v_fma_mix_f32 v87, v87, v45, v60 op_sel:[0,1,0] op_sel_hi:[0,1,0]
	v_add_f32_dpp v53, v53, v53 row_mirror row_mask:0xf bank_mask:0xf bound_ctrl:1
	v_fma_mix_f32 v84, -v53, v48, v84 op_sel:[0,0,0] op_sel_hi:[0,1,0]
	v_fma_mix_f32 v85, -v53, v48, v85 op_sel:[0,1,0] op_sel_hi:[0,1,0]
	v_fma_mix_f32 v86, -v53, v49, v86 op_sel:[0,0,0] op_sel_hi:[0,1,0]
	v_fma_mix_f32 v87, -v53, v49, v87 op_sel:[0,1,0] op_sel_hi:[0,1,0]
	v_fma_mix_f32 v41, v84, v42, 0 op_sel:[0,0,0] op_sel_hi:[0,1,0]
	v_add_u32_e32 v173, 16, v193
	v_fma_mix_f32 v41, v85, v42, v41 op_sel:[0,1,0] op_sel_hi:[0,1,0]
	ds_write_b32 v172, v173 offset:49216
	v_fma_mix_f32 v41, v86, v43, v41 op_sel:[0,0,0] op_sel_hi:[0,1,0]
	v_cndmask_b32_e64 v187, v57, v56, s[38:39]
	v_fma_mix_f32 v41, v87, v43, v41 op_sel:[0,1,0] op_sel_hi:[0,1,0]
	v_cndmask_b32_e64 v188, v56, v57, s[38:39]
	v_cndmask_b32_e64 v189, v41, v40, s[38:39]
	v_cndmask_b32_e64 v190, v40, v41, s[38:39]
	s_waitcnt lgkmcnt(1)
; #define RC_WAIT(gq) { if (pseen <= (gq)) { do { pseen = __builtin_amdgcn_readfirstlane(*pflag); if (pseen <= (gq)) __builtin_amdgcn_s_sleep(1); } while (pseen <= (gq)); } asm volatile("" ::: "memory"); }
; DEV void rwkv_consumer(const Params& p, const Ctx& cx, int l, int task, int lane, const char* ring, int widx) {
;     ...
;   RC_WAIT(0); RC_LOAD(A, 0);
; #pragma unroll 1
;   for (int g = 0; g < RW_NG; g += 2) {
;     RC_WAIT(g + 1); RC_LOAD(B, g + 1);
;     RC_COMP(A, g);
;     if (g + 2 < RW_NG) { RC_WAIT(g + 2); RC_LOAD(A, g + 2); }
;     RC_COMP(B, g + 1);
	v_fma_mix_f32 v98, v84, v6, 0 op_sel:[0,0,0] op_sel_hi:[0,1,0]
	v_fma_mix_f32 v98, v85, v6, v98 op_sel:[0,1,0] op_sel_hi:[0,1,0]
	v_add_f32_dpp v188, v188, v187 quad_perm:[1,0,3,2] row_mask:0xf bank_mask:0xf bound_ctrl:1
	v_add_f32_dpp v189, v190, v189 quad_perm:[1,0,3,2] row_mask:0xf bank_mask:0xf bound_ctrl:1
	v_fma_mix_f32 v98, v86, v7, v98 op_sel:[0,0,0] op_sel_hi:[0,1,0]
	v_fma_mix_f32 v98, v87, v7, v98 op_sel:[0,1,0] op_sel_hi:[0,1,0]
	v_cndmask_b32_e64 v191, v189, v188, s[40:41]
	v_cndmask_b32_e64 v192, v188, v189, s[40:41]
	v_fma_mix_f32 v100, v88, v14, 0 op_sel:[0,0,0] op_sel_hi:[1,1,0]
	v_fma_mix_f32 v101, v88, v14, 0 op_sel:[0,1,0] op_sel_hi:[1,1,0]
	v_add_f32_dpp v192, v192, v191 quad_perm:[2,3,0,1] row_mask:0xf bank_mask:0xf bound_ctrl:1
	v_add_f32_dpp v98, v98, v98 quad_perm:[1,0,3,2] row_mask:0xf bank_mask:0xf bound_ctrl:1
	v_fma_mix_f32 v102, v88, v15, 0 op_sel:[0,0,0] op_sel_hi:[1,1,0]
	v_add_f32_dpp v192, v192, v192 row_ror:4 row_mask:0xf bank_mask:0xf bound_ctrl:1
	v_fma_mix_f32 v103, v88, v15, 0 op_sel:[0,1,0] op_sel_hi:[1,1,0]
	v_add_f32_dpp v98, v98, v98 quad_perm:[2,3,0,1] row_mask:0xf bank_mask:0xf bound_ctrl:1
	v_add_f32_dpp v192, v192, v192 row_ror:8 row_mask:0xf bank_mask:0xf bound_ctrl:1
	v_cvt_f16_f32_e32 v192, v192
	global_store_short v83, v192, s[36:37]
	s_add_u32 s36, s36, s44
	s_addc_u32 s37, s37, s45
	global_load_ushort v204, v83, s[22:23]
	s_add_u32 s22, s22, s44
	s_addc_u32 s23, s23, s45
	ds_read_b128 v[56:59], v194 offset:5120
	ds_read_b128 v[72:75], v194 offset:3072
	ds_read_b128 v[64:67], v194 offset:3328
	ds_read_b128 v[76:79], v194 offset:4096
	ds_read_b128 v[68:71], v194 offset:4352
	ds_read_b128 v[40:43], v194 offset:5376
	ds_read_b128 v[52:55], v194 offset:3584
	ds_read_b128 v[44:47], v194 offset:3840
	ds_read_b128 v[60:63], v194 offset:4608
	ds_read_b128 v[48:51], v194 offset:4864
	s_waitcnt vmcnt(12)
	v_mov_b32_dpp v92, v198 quad_perm:[0,0,0,0] row_mask:0xf bank_mask:0xf
	v_mov_b32_dpp v93, v198 quad_perm:[1,1,1,1] row_mask:0xf bank_mask:0xf
	v_mov_b32_dpp v94, v198 quad_perm:[2,2,2,2] row_mask:0xf bank_mask:0xf
	v_mov_b32_dpp v95, v198 quad_perm:[3,3,3,3] row_mask:0xf bank_mask:0xf
	s_add_i32 s33, s33, 16
	s_sub_i32 s35, s35, 16
	v_mov_b32_e32 v193, s33
	s_cmp_eq_u32 s33, 64
	s_cbranch_scc1 .Lc_fix
